# adds hand-scheduled gate epilogue: P/TMP chunk loads software-pipelined 6 chunks ahead with counted vmcnt (same arithmetic)
# speedup vs baseline: 1.0090x; 1.0090x over previous
; __device__ __forceinline__ unsigned pk2(float lo, float hi) { f32x2_t v = {lo, hi}; bf16x2_t b = __builtin_convertvector(v, bf16x2_t); return __builtin_bit_cast(unsigned, b); }
; __device__ __forceinline__ float sigmoidf_(float x) { return __builtin_amdgcn_rcpf(1.0f + fexp2(-x * LOG2E)); }
;     __device__ __forceinline__ void operator()(AccRef acc, const pg8::Unit& u, int wr, int wc, int fr, int fq) const {
;         const int row0 = u.pm * 256 + wr * 64 + fr, col0 = u.pn * 128 + wc * 32 + 8 * fq;
; #pragma unroll
;         for (int ai = 0; ai < 2; ++ai)
; #pragma unroll
;             for (int m = 0; m < 4; ++m) {
;                 const int row = row0 + ai * 128 + m * 16;
;                 const float rs = rst[row & 255];
;                 float v[8];
; #pragma unroll
;                 for (int n = 0; n < 2; ++n)
; #pragma unroll
;                     for (int j = 0; j < 4; ++j) { const float g = acc[ai][0][m][n][j] * rs, up = acc[ai][1][m][n][j] * rs; v[4 * n + j] = g * sigmoidf_(g) * up; }
;                 v4u w; w.x = pk2(v[0], v[1]); w.y = pk2(v[2], v[3]); w.z = pk2(v[4], v[5]); w.w = pk2(v[6], v[7]);
;                 *(v4u*)(U + (size_t)row * FF + col0) = w;
;             }
.LBB0_260:
	s_and_b64 vcc, exec, s[6:7]
	s_cbranch_vccz .LBB0_377
	v_add_u32_e32 v4, s71, v245
	v_lshl_add_u32 v5, s45, 8, v4
	v_add_u32_e32 v36, 0x90, v5
	s_add_i32 s6, 0, 0x20100
	v_and_b32_e32 v14, 0xff, v36
	v_add_u32_e32 v37, 0xa0, v5
	v_add_u32_e32 v7, 16, v5
	v_add_u32_e32 v9, 32, v5
	v_add_u32_e32 v11, 48, v5
	v_lshl_add_u32 v15, v14, 2, s6
	v_and_b32_e32 v14, 0xff, v37
	v_add_u32_e32 v38, 0xb0, v5
	v_and_b32_e32 v4, 0xff, v4
	v_and_b32_e32 v6, 0xff, v7
	v_and_b32_e32 v8, 0xff, v9
	v_and_b32_e32 v10, 0xff, v11
	v_add_u32_e32 v12, 0x80, v5
	v_lshl_add_u32 v16, v14, 2, s6
	v_and_b32_e32 v14, 0xff, v38
	v_lshl_add_u32 v4, v4, 2, s6
	v_lshl_add_u32 v6, v6, 2, s6
	v_lshl_add_u32 v8, v8, 2, s6
	v_lshl_add_u32 v10, v10, 2, s6
	v_and_b32_e32 v13, 0xff, v12
	v_lshl_add_u32 v17, v14, 2, s6
	v_lshl_add_u32 v13, v13, 2, s6
	ds_read_b32 v14, v4
	ds_read_b32 v18, v6
	ds_read_b32 v20, v8
	ds_read_b32 v22, v10
	ds_read_b32 v10, v13
	ds_read_b32 v8, v15
	ds_read_b32 v6, v16
	ds_read_b32 v4, v17
	s_waitcnt lgkmcnt(0)
	v_pk_mul_f32 v[16:17], v[190:191], v[14:15] op_sel_hi:[1,0]
	s_lshl_b32 s3, s40, 7
	v_mul_f32_e32 v13, 0xbfb8aa3b, v16
	v_mul_f32_e32 v15, 0xbfb8aa3b, v17
	v_exp_f32_e32 v13, v13
	v_exp_f32_e32 v15, v15
	s_or_b32 s3, s3, s67
	v_lshl_add_u32 v2, v244, 3, s3
	v_add_f32_e32 v13, 1.0, v13
	v_pk_mul_f32 v[28:29], v[192:193], v[14:15] op_sel_hi:[1,0]
	v_rcp_f32_e32 v24, v13
	v_pk_mul_f32 v[26:27], v[182:183], v[14:15] op_sel_hi:[1,0]
	v_add_f32_e32 v13, 1.0, v15
	v_mul_f32_e32 v15, 0xbfb8aa3b, v28
	v_exp_f32_e32 v15, v15
	v_mul_f32_e32 v19, 0xbfb8aa3b, v29
	v_exp_f32_e32 v19, v19
	v_rcp_f32_e32 v25, v13
	v_add_f32_e32 v13, 1.0, v15
	v_rcp_f32_e32 v30, v13
	v_add_f32_e32 v13, 1.0, v19
	v_rcp_f32_e32 v31, v13
	v_pk_mul_f32 v[16:17], v[16:17], v[24:25]
	v_pk_mul_f32 v[24:25], v[184:185], v[14:15] op_sel_hi:[1,0]
	v_pk_mul_f32 v[16:17], v[26:27], v[16:17]
	v_pk_mul_f32 v[26:27], v[28:29], v[30:31]
	v_pk_mul_f32 v[28:29], v[186:187], v[14:15] op_sel_hi:[1,0]
	v_pk_mul_f32 v[24:25], v[24:25], v[26:27]
	v_mul_f32_e32 v13, 0xbfb8aa3b, v28
	v_mul_f32_e32 v15, 0xbfb8aa3b, v29
	v_exp_f32_e32 v13, v13
	v_exp_f32_e32 v15, v15
	v_readlane_b32 s6, v255, 23
	v_ashrrev_i32_e32 v3, 31, v2
	v_add_f32_e32 v13, 1.0, v13
	v_pk_mul_f32 v[32:33], v[188:189], v[14:15] op_sel_hi:[1,0]
	v_rcp_f32_e32 v26, v13
	v_pk_mul_f32 v[30:31], v[178:179], v[14:15] op_sel_hi:[1,0]
	v_add_f32_e32 v13, 1.0, v15
	v_mul_f32_e32 v15, 0xbfb8aa3b, v32
	v_exp_f32_e32 v15, v15
	v_mul_f32_e32 v19, 0xbfb8aa3b, v33
	v_exp_f32_e32 v19, v19
	v_rcp_f32_e32 v27, v13
	v_add_f32_e32 v13, 1.0, v15
	v_rcp_f32_e32 v34, v13
	v_add_f32_e32 v13, 1.0, v19
	v_rcp_f32_e32 v35, v13
	v_pk_mul_f32 v[26:27], v[28:29], v[26:27]
	v_readlane_b32 s7, v255, 24
	v_pk_mul_f32 v[26:27], v[30:31], v[26:27]
	v_pk_mul_f32 v[14:15], v[180:181], v[14:15] op_sel_hi:[1,0]
	v_pk_mul_f32 v[28:29], v[32:33], v[34:35]
	v_lshl_add_u64 v[2:3], v[2:3], 1, s[6:7]
	v_pk_mul_f32 v[28:29], v[14:15], v[28:29]
	v_cvt_pk_bf16_f32 v14, v16, v17
	v_cvt_pk_bf16_f32 v16, v26, v27
	s_movk_i32 s3, 0x1600
	v_pk_mul_f32 v[26:27], v[174:175], v[18:19] op_sel_hi:[1,0]
	v_cvt_pk_bf16_f32 v15, v24, v25
	v_mad_i64_i32 v[24:25], s[6:7], v5, s3, v[2:3]
	v_mul_f32_e32 v5, 0xbfb8aa3b, v26
	v_exp_f32_e32 v5, v5
	v_mul_f32_e32 v13, 0xbfb8aa3b, v27
	v_exp_f32_e32 v13, v13
	v_cvt_pk_bf16_f32 v17, v28, v29
	global_store_dwordx4 v[24:25], v[14:17], off
	v_add_f32_e32 v5, 1.0, v5
	v_pk_mul_f32 v[24:25], v[176:177], v[18:19] op_sel_hi:[1,0]
	v_rcp_f32_e32 v14, v5
	v_add_f32_e32 v5, 1.0, v13
	v_mul_f32_e32 v13, 0xbfb8aa3b, v24
	v_exp_f32_e32 v13, v13
	v_mul_f32_e32 v15, 0xbfb8aa3b, v25
	v_pk_mul_f32 v[16:17], v[166:167], v[18:19] op_sel_hi:[1,0]
	v_exp_f32_e32 v19, v15
	v_rcp_f32_e32 v15, v5
	v_add_f32_e32 v5, 1.0, v13
	v_rcp_f32_e32 v28, v5
	v_add_f32_e32 v5, 1.0, v19
	v_pk_mul_f32 v[14:15], v[26:27], v[14:15]
	v_pk_mul_f32 v[26:27], v[170:171], v[18:19] op_sel_hi:[1,0]
	v_rcp_f32_e32 v29, v5
	v_mul_f32_e32 v5, 0xbfb8aa3b, v26
	v_exp_f32_e32 v5, v5
	v_mul_f32_e32 v13, 0xbfb8aa3b, v27
	v_exp_f32_e32 v13, v13
	v_pk_mul_f32 v[14:15], v[16:17], v[14:15]
	v_pk_mul_f32 v[16:17], v[168:169], v[18:19] op_sel_hi:[1,0]
	v_pk_mul_f32 v[24:25], v[24:25], v[28:29]
	v_add_f32_e32 v5, 1.0, v5
	v_pk_mul_f32 v[30:31], v[172:173], v[18:19] op_sel_hi:[1,0]
	v_pk_mul_f32 v[16:17], v[16:17], v[24:25]
	v_rcp_f32_e32 v24, v5
	v_add_f32_e32 v5, 1.0, v13
	v_mul_f32_e32 v13, 0xbfb8aa3b, v30
	v_pk_mul_f32 v[28:29], v[162:163], v[18:19] op_sel_hi:[1,0]
	v_exp_f32_e32 v13, v13
	v_mul_f32_e32 v19, 0xbfb8aa3b, v31
	v_exp_f32_e32 v19, v19
	v_rcp_f32_e32 v25, v5
	v_add_f32_e32 v5, 1.0, v13
	v_rcp_f32_e32 v32, v5
	v_add_f32_e32 v5, 1.0, v19
	v_rcp_f32_e32 v33, v5
	v_pk_mul_f32 v[24:25], v[26:27], v[24:25]
	v_pk_mul_f32 v[18:19], v[164:165], v[18:19] op_sel_hi:[1,0]
	v_pk_mul_f32 v[24:25], v[28:29], v[24:25]
	v_pk_mul_f32 v[26:27], v[30:31], v[32:33]
	v_cvt_pk_bf16_f32 v14, v14, v15
	v_cvt_pk_bf16_f32 v15, v16, v17
	v_cvt_pk_bf16_f32 v16, v24, v25
	v_pk_mul_f32 v[24:25], v[158:159], v[20:21] op_sel_hi:[1,0]
	v_pk_mul_f32 v[18:19], v[18:19], v[26:27]
	v_mul_f32_e32 v5, 0xbfb8aa3b, v24
	v_cvt_pk_bf16_f32 v17, v18, v19
	v_mad_i64_i32 v[18:19], s[6:7], v7, s3, v[2:3]
	v_exp_f32_e32 v5, v5
	v_mul_f32_e32 v7, 0xbfb8aa3b, v25
	v_exp_f32_e32 v7, v7
	global_store_dwordx4 v[18:19], v[14:17], off
	v_add_f32_e32 v5, 1.0, v5
	v_pk_mul_f32 v[18:19], v[160:161], v[20:21] op_sel_hi:[1,0]
	v_rcp_f32_e32 v14, v5
	v_add_f32_e32 v5, 1.0, v7
	v_mul_f32_e32 v7, 0xbfb8aa3b, v18
	v_exp_f32_e32 v7, v7
	v_mul_f32_e32 v13, 0xbfb8aa3b, v19
	v_exp_f32_e32 v13, v13
	v_rcp_f32_e32 v15, v5
	v_add_f32_e32 v5, 1.0, v7
; __device__ __forceinline__ unsigned pk2(float lo, float hi) { f32x2_t v = {lo, hi}; bf16x2_t b = __builtin_convertvector(v, bf16x2_t); return __builtin_bit_cast(unsigned, b); }
; __device__ __forceinline__ float sigmoidf_(float x) { return __builtin_amdgcn_rcpf(1.0f + fexp2(-x * LOG2E)); }
;     __device__ __forceinline__ void operator()(AccRef acc, const pg8::Unit& u, int wr, int wc, int fr, int fq) const {
;     ...
;                 const int row = row0 + ai * 128 + m * 16;
;                 const float rs = rst[row & 255];
;                 float v[8];
; #pragma unroll
;                 for (int n = 0; n < 2; ++n)
; #pragma unroll
;                     for (int j = 0; j < 4; ++j) { const float g = acc[ai][0][m][n][j] * rs, up = acc[ai][1][m][n][j] * rs; v[4 * n + j] = g * sigmoidf_(g) * up; }
;                 v4u w; w.x = pk2(v[0], v[1]); w.y = pk2(v[2], v[3]); w.z = pk2(v[4], v[5]); w.w = pk2(v[6], v[7]);
;                 *(v4u*)(U + (size_t)row * FF + col0) = w;
	v_rcp_f32_e32 v26, v5
	v_add_f32_e32 v5, 1.0, v13
	v_pk_mul_f32 v[14:15], v[24:25], v[14:15]
	v_pk_mul_f32 v[24:25], v[154:155], v[20:21] op_sel_hi:[1,0]
	v_rcp_f32_e32 v27, v5
	v_mul_f32_e32 v5, 0xbfb8aa3b, v24
	v_exp_f32_e32 v5, v5
	v_mul_f32_e32 v7, 0xbfb8aa3b, v25
	v_exp_f32_e32 v7, v7
	v_pk_mul_f32 v[16:17], v[150:151], v[20:21] op_sel_hi:[1,0]
	v_pk_mul_f32 v[18:19], v[18:19], v[26:27]
	v_pk_mul_f32 v[14:15], v[16:17], v[14:15]
	v_pk_mul_f32 v[16:17], v[152:153], v[20:21] op_sel_hi:[1,0]
	v_add_f32_e32 v5, 1.0, v5
	v_pk_mul_f32 v[28:29], v[156:157], v[20:21] op_sel_hi:[1,0]
	v_pk_mul_f32 v[16:17], v[16:17], v[18:19]
	v_rcp_f32_e32 v18, v5
	v_add_f32_e32 v5, 1.0, v7
	v_mul_f32_e32 v7, 0xbfb8aa3b, v28
	v_exp_f32_e32 v7, v7
	v_mul_f32_e32 v13, 0xbfb8aa3b, v29
	v_exp_f32_e32 v13, v13
	v_rcp_f32_e32 v19, v5
	v_add_f32_e32 v5, 1.0, v7
	v_rcp_f32_e32 v30, v5
	v_add_f32_e32 v5, 1.0, v13
	v_rcp_f32_e32 v31, v5
	v_pk_mul_f32 v[26:27], v[146:147], v[20:21] op_sel_hi:[1,0]
	v_pk_mul_f32 v[18:19], v[24:25], v[18:19]
	v_pk_mul_f32 v[20:21], v[148:149], v[20:21] op_sel_hi:[1,0]
	v_pk_mul_f32 v[24:25], v[28:29], v[30:31]
	v_cvt_pk_bf16_f32 v14, v14, v15
	v_pk_mul_f32 v[20:21], v[20:21], v[24:25]
	v_cvt_pk_bf16_f32 v15, v16, v17
	v_cvt_pk_bf16_f32 v17, v20, v21
	v_pk_mul_f32 v[20:21], v[142:143], v[22:23] op_sel_hi:[1,0]
	v_pk_mul_f32 v[18:19], v[26:27], v[18:19]
	v_mul_f32_e32 v5, 0xbfb8aa3b, v20
	v_exp_f32_e32 v5, v5
	v_mul_f32_e32 v7, 0xbfb8aa3b, v21
	v_exp_f32_e32 v7, v7
	v_cvt_pk_bf16_f32 v16, v18, v19
	v_mad_i64_i32 v[18:19], s[6:7], v9, s3, v[2:3]
	global_store_dwordx4 v[18:19], v[14:17], off
	v_add_f32_e32 v5, 1.0, v5
	v_pk_mul_f32 v[18:19], v[144:145], v[22:23] op_sel_hi:[1,0]
	v_rcp_f32_e32 v14, v5
	v_add_f32_e32 v5, 1.0, v7
	v_mul_f32_e32 v7, 0xbfb8aa3b, v18
	v_exp_f32_e32 v7, v7
	v_mul_f32_e32 v9, 0xbfb8aa3b, v19
	v_exp_f32_e32 v9, v9
	v_rcp_f32_e32 v15, v5
	v_add_f32_e32 v5, 1.0, v7
	v_rcp_f32_e32 v24, v5
	v_add_f32_e32 v5, 1.0, v9
	v_pk_mul_f32 v[14:15], v[20:21], v[14:15]
	v_pk_mul_f32 v[20:21], v[138:139], v[22:23] op_sel_hi:[1,0]
	v_rcp_f32_e32 v25, v5
	v_mul_f32_e32 v5, 0xbfb8aa3b, v20
	v_exp_f32_e32 v5, v5
	v_mul_f32_e32 v7, 0xbfb8aa3b, v21
	v_exp_f32_e32 v7, v7
	v_pk_mul_f32 v[16:17], v[134:135], v[22:23] op_sel_hi:[1,0]
	v_pk_mul_f32 v[18:19], v[18:19], v[24:25]
	v_pk_mul_f32 v[14:15], v[16:17], v[14:15]
	v_pk_mul_f32 v[16:17], v[136:137], v[22:23] op_sel_hi:[1,0]
	v_add_f32_e32 v5, 1.0, v5
	v_pk_mul_f32 v[26:27], v[140:141], v[22:23] op_sel_hi:[1,0]
	v_pk_mul_f32 v[16:17], v[16:17], v[18:19]
	v_rcp_f32_e32 v18, v5
	v_add_f32_e32 v5, 1.0, v7
	v_mul_f32_e32 v7, 0xbfb8aa3b, v26
	v_exp_f32_e32 v7, v7
	v_mul_f32_e32 v9, 0xbfb8aa3b, v27
	v_exp_f32_e32 v9, v9
	v_rcp_f32_e32 v19, v5
	v_add_f32_e32 v5, 1.0, v7
	v_rcp_f32_e32 v28, v5
	v_add_f32_e32 v5, 1.0, v9
	v_rcp_f32_e32 v29, v5
	v_pk_mul_f32 v[24:25], v[130:131], v[22:23] op_sel_hi:[1,0]
	v_pk_mul_f32 v[18:19], v[20:21], v[18:19]
	v_pk_mul_f32 v[20:21], v[132:133], v[22:23] op_sel_hi:[1,0]
	v_pk_mul_f32 v[22:23], v[26:27], v[28:29]
	v_cvt_pk_bf16_f32 v14, v14, v15
	v_pk_mul_f32 v[20:21], v[20:21], v[22:23]
	v_cvt_pk_bf16_f32 v15, v16, v17
	v_cvt_pk_bf16_f32 v17, v20, v21
	v_pk_mul_f32 v[20:21], v[126:127], v[10:11] op_sel_hi:[1,0]
	v_pk_mul_f32 v[18:19], v[24:25], v[18:19]
	v_mul_f32_e32 v5, 0xbfb8aa3b, v20
	v_exp_f32_e32 v5, v5
	v_mul_f32_e32 v7, 0xbfb8aa3b, v21
	v_exp_f32_e32 v7, v7
	v_cvt_pk_bf16_f32 v16, v18, v19
	v_mad_i64_i32 v[18:19], s[6:7], v11, s3, v[2:3]
	global_store_dwordx4 v[18:19], v[14:17], off
	v_add_f32_e32 v5, 1.0, v5
	v_pk_mul_f32 v[18:19], v[128:129], v[10:11] op_sel_hi:[1,0]
	v_rcp_f32_e32 v14, v5
	v_add_f32_e32 v5, 1.0, v7
	v_mul_f32_e32 v7, 0xbfb8aa3b, v18
	v_exp_f32_e32 v7, v7
	v_mul_f32_e32 v9, 0xbfb8aa3b, v19
	v_exp_f32_e32 v9, v9
	v_rcp_f32_e32 v15, v5
	v_add_f32_e32 v5, 1.0, v7
	v_rcp_f32_e32 v22, v5
	v_add_f32_e32 v5, 1.0, v9
	v_pk_mul_f32 v[14:15], v[20:21], v[14:15]
	v_pk_mul_f32 v[20:21], v[122:123], v[10:11] op_sel_hi:[1,0]
	v_rcp_f32_e32 v23, v5
	v_mul_f32_e32 v5, 0xbfb8aa3b, v20
	v_exp_f32_e32 v5, v5
	v_mul_f32_e32 v7, 0xbfb8aa3b, v21
	v_exp_f32_e32 v7, v7
	v_pk_mul_f32 v[16:17], v[118:119], v[10:11] op_sel_hi:[1,0]
	v_pk_mul_f32 v[18:19], v[18:19], v[22:23]
	v_pk_mul_f32 v[14:15], v[16:17], v[14:15]
	v_pk_mul_f32 v[16:17], v[120:121], v[10:11] op_sel_hi:[1,0]
	v_add_f32_e32 v5, 1.0, v5
	v_pk_mul_f32 v[24:25], v[124:125], v[10:11] op_sel_hi:[1,0]
	v_pk_mul_f32 v[16:17], v[16:17], v[18:19]
	v_rcp_f32_e32 v18, v5
	v_add_f32_e32 v5, 1.0, v7
	v_mul_f32_e32 v7, 0xbfb8aa3b, v24
	v_exp_f32_e32 v7, v7
	v_mul_f32_e32 v9, 0xbfb8aa3b, v25
	v_exp_f32_e32 v9, v9
	v_rcp_f32_e32 v19, v5
	v_add_f32_e32 v5, 1.0, v7
	v_rcp_f32_e32 v26, v5
	v_add_f32_e32 v5, 1.0, v9
	v_rcp_f32_e32 v27, v5
	v_pk_mul_f32 v[22:23], v[114:115], v[10:11] op_sel_hi:[1,0]
	v_pk_mul_f32 v[18:19], v[20:21], v[18:19]
	v_pk_mul_f32 v[10:11], v[116:117], v[10:11] op_sel_hi:[1,0]
	v_pk_mul_f32 v[20:21], v[24:25], v[26:27]
	v_cvt_pk_bf16_f32 v14, v14, v15
	v_pk_mul_f32 v[10:11], v[10:11], v[20:21]
	v_cvt_pk_bf16_f32 v15, v16, v17
	v_cvt_pk_bf16_f32 v17, v10, v11
	v_mad_i64_i32 v[10:11], s[6:7], v12, s3, v[2:3]
	v_pk_mul_f32 v[12:13], v[110:111], v[8:9] op_sel_hi:[1,0]
	v_pk_mul_f32 v[18:19], v[22:23], v[18:19]
	v_mul_f32_e32 v5, 0xbfb8aa3b, v12
	v_exp_f32_e32 v5, v5
	v_mul_f32_e32 v7, 0xbfb8aa3b, v13
	v_exp_f32_e32 v7, v7
	v_cvt_pk_bf16_f32 v16, v18, v19
	global_store_dwordx4 v[10:11], v[14:17], off
	v_add_f32_e32 v5, 1.0, v5
	v_rcp_f32_e32 v10, v5
	v_pk_mul_f32 v[16:17], v[112:113], v[8:9] op_sel_hi:[1,0]
	v_add_f32_e32 v5, 1.0, v7
	v_mul_f32_e32 v7, 0xbfb8aa3b, v16
; __device__ __forceinline__ unsigned pk2(float lo, float hi) { f32x2_t v = {lo, hi}; bf16x2_t b = __builtin_convertvector(v, bf16x2_t); return __builtin_bit_cast(unsigned, b); }
; __device__ __forceinline__ float sigmoidf_(float x) { return __builtin_amdgcn_rcpf(1.0f + fexp2(-x * LOG2E)); }
;     __device__ __forceinline__ void operator()(AccRef acc, const pg8::Unit& u, int wr, int wc, int fr, int fq) const {
;     ...
;                 const int row = row0 + ai * 128 + m * 16;
;                 const float rs = rst[row & 255];
;                 float v[8];
; #pragma unroll
;                 for (int n = 0; n < 2; ++n)
; #pragma unroll
;                     for (int j = 0; j < 4; ++j) { const float g = acc[ai][0][m][n][j] * rs, up = acc[ai][1][m][n][j] * rs; v[4 * n + j] = g * sigmoidf_(g) * up; }
;                 v4u w; w.x = pk2(v[0], v[1]); w.y = pk2(v[2], v[3]); w.z = pk2(v[4], v[5]); w.w = pk2(v[6], v[7]);
;                 *(v4u*)(U + (size_t)row * FF + col0) = w;
;     __device__ __forceinline__ void operator()(AccRef acc, const pg8::Unit& u, int wr, int wc, int fr, int fq) const {
;     ...
;         if (kind == 0) { EpiSwiglu E{(bf16*)big, rst}; E(acc, u, wr, wc, fr, fq); }
;         else if (kind == 1) { EpiResid E{(bf16*)(ws + WS_HN), outf, scale, rss_out}; E(acc, u, wr, wc, fr, fq); }
;         else if (kind == 2) {
;             const int l = layer;
;             EpiQKV E{big, pp->in[9] + l * 64, pp->in[10] + l * 64, pp->in[13] + l * 64, pp->in[14] + l * 64, pp->in[15] + l * 64, pp->in[16] + l * 64, pp->in[8] + l * 6, (float*)(ws + WS_LOGF), rst};
;             E(acc, u, wr, wc, fr, fq);
;         }
;         else if (kind == 3) { EpiPStore E{(v4u*)(big + B_P)}; E(acc, u, wr, wc, fr, fq); }
;         else { EpiGate E{pp->in[7] + (size_t)layer * 4 * D + (size_t)bi * D, (const v4u*)(big + B_P), (v4u*)(big + B_TMP), (bf16*)(big + B_MRG), bi == 0, bi == 3, rst}; E(acc, u, wr, wc, fr, fq); }
	v_pk_mul_f32 v[14:15], v[102:103], v[8:9] op_sel_hi:[1,0]
	v_exp_f32_e32 v7, v7
	v_mul_f32_e32 v9, 0xbfb8aa3b, v17
	v_exp_f32_e32 v9, v9
	v_rcp_f32_e32 v11, v5
	v_add_f32_e32 v5, 1.0, v7
	v_rcp_f32_e32 v18, v5
	v_add_f32_e32 v5, 1.0, v9
	v_rcp_f32_e32 v19, v5
	v_pk_mul_f32 v[10:11], v[12:13], v[10:11]
	v_pk_mul_f32 v[12:13], v[104:105], v[8:9] op_sel_hi:[1,0]
	v_pk_mul_f32 v[10:11], v[14:15], v[10:11]
	v_pk_mul_f32 v[14:15], v[16:17], v[18:19]
	v_pk_mul_f32 v[16:17], v[106:107], v[8:9] op_sel_hi:[1,0]
	v_pk_mul_f32 v[20:21], v[108:109], v[8:9] op_sel_hi:[1,0]
	v_mul_f32_e32 v5, 0xbfb8aa3b, v16
	v_exp_f32_e32 v5, v5
	v_mul_f32_e32 v7, 0xbfb8aa3b, v17
	v_exp_f32_e32 v7, v7
	v_pk_mul_f32 v[12:13], v[12:13], v[14:15]
	v_add_f32_e32 v5, 1.0, v5
	v_rcp_f32_e32 v14, v5
	v_add_f32_e32 v5, 1.0, v7
	v_mul_f32_e32 v7, 0xbfb8aa3b, v20
	v_pk_mul_f32 v[18:19], v[98:99], v[8:9] op_sel_hi:[1,0]
	v_exp_f32_e32 v7, v7
	v_mul_f32_e32 v9, 0xbfb8aa3b, v21
	v_exp_f32_e32 v9, v9
	v_rcp_f32_e32 v15, v5
	v_add_f32_e32 v5, 1.0, v7
	v_rcp_f32_e32 v22, v5
	v_add_f32_e32 v5, 1.0, v9
	v_rcp_f32_e32 v23, v5
	v_pk_mul_f32 v[14:15], v[16:17], v[14:15]
	v_pk_mul_f32 v[8:9], v[100:101], v[8:9] op_sel_hi:[1,0]
	v_pk_mul_f32 v[14:15], v[18:19], v[14:15]
	v_pk_mul_f32 v[16:17], v[20:21], v[22:23]
	s_nop 0
	v_pk_mul_f32 v[16:17], v[8:9], v[16:17]
	v_cvt_pk_bf16_f32 v8, v10, v11
	v_cvt_pk_bf16_f32 v10, v14, v15
	v_pk_mul_f32 v[14:15], v[94:95], v[6:7] op_sel_hi:[1,0]
	v_cvt_pk_bf16_f32 v9, v12, v13
	v_mul_f32_e32 v5, 0xbfb8aa3b, v14
	v_mul_f32_e32 v7, 0xbfb8aa3b, v15
	v_exp_f32_e32 v5, v5
	v_exp_f32_e32 v7, v7
	v_cvt_pk_bf16_f32 v11, v16, v17
	v_mad_i64_i32 v[12:13], s[6:7], v36, s3, v[2:3]
	global_store_dwordx4 v[12:13], v[8:11], off
	v_add_f32_e32 v5, 1.0, v5
	v_pk_mul_f32 v[12:13], v[96:97], v[6:7] op_sel_hi:[1,0]
	v_rcp_f32_e32 v8, v5
	v_pk_mul_f32 v[10:11], v[86:87], v[6:7] op_sel_hi:[1,0]
	v_add_f32_e32 v5, 1.0, v7
	v_mul_f32_e32 v7, 0xbfb8aa3b, v12
	v_exp_f32_e32 v7, v7
	v_mul_f32_e32 v9, 0xbfb8aa3b, v13
	v_exp_f32_e32 v17, v9
	v_rcp_f32_e32 v9, v5
	v_add_f32_e32 v5, 1.0, v7
	v_rcp_f32_e32 v16, v5
	v_add_f32_e32 v5, 1.0, v17
	v_pk_mul_f32 v[8:9], v[14:15], v[8:9]
	v_pk_mul_f32 v[14:15], v[90:91], v[6:7] op_sel_hi:[1,0]
	v_rcp_f32_e32 v17, v5
	v_pk_mul_f32 v[8:9], v[10:11], v[8:9]
	v_pk_mul_f32 v[10:11], v[88:89], v[6:7] op_sel_hi:[1,0]
	v_mul_f32_e32 v5, 0xbfb8aa3b, v14
	v_mul_f32_e32 v7, 0xbfb8aa3b, v15
	v_exp_f32_e32 v5, v5
	v_exp_f32_e32 v7, v7
	v_pk_mul_f32 v[12:13], v[12:13], v[16:17]
	v_add_f32_e32 v5, 1.0, v5
	v_pk_mul_f32 v[18:19], v[92:93], v[6:7] op_sel_hi:[1,0]
	v_pk_mul_f32 v[10:11], v[10:11], v[12:13]
	v_rcp_f32_e32 v12, v5
	v_pk_mul_f32 v[16:17], v[82:83], v[6:7] op_sel_hi:[1,0]
	v_add_f32_e32 v5, 1.0, v7
	v_mul_f32_e32 v7, 0xbfb8aa3b, v18
	v_exp_f32_e32 v7, v7
	v_mul_f32_e32 v13, 0xbfb8aa3b, v19
	v_exp_f32_e32 v21, v13
	v_rcp_f32_e32 v13, v5
	v_add_f32_e32 v5, 1.0, v7
	v_rcp_f32_e32 v20, v5
	v_add_f32_e32 v5, 1.0, v21
	v_rcp_f32_e32 v21, v5
	v_pk_mul_f32 v[12:13], v[14:15], v[12:13]
	v_pk_mul_f32 v[6:7], v[84:85], v[6:7] op_sel_hi:[1,0]
	v_pk_mul_f32 v[12:13], v[16:17], v[12:13]
	v_pk_mul_f32 v[14:15], v[18:19], v[20:21]
	s_nop 0
	v_pk_mul_f32 v[14:15], v[6:7], v[14:15]
	v_cvt_pk_bf16_f32 v6, v8, v9
	v_cvt_pk_bf16_f32 v8, v12, v13
	v_pk_mul_f32 v[12:13], v[78:79], v[4:5] op_sel_hi:[1,0]
	v_cvt_pk_bf16_f32 v7, v10, v11
	v_cvt_pk_bf16_f32 v9, v14, v15
	v_mad_i64_i32 v[10:11], s[6:7], v37, s3, v[2:3]
	v_mul_f32_e32 v5, 0xbfb8aa3b, v12
	v_exp_f32_e32 v5, v5
	global_store_dwordx4 v[10:11], v[6:9], off
	v_mad_i64_i32 v[2:3], s[6:7], v38, s3, v[2:3]
	s_nop 0
	v_mul_f32_e32 v6, 0xbfb8aa3b, v13
	v_exp_f32_e32 v7, v6
	v_add_f32_e32 v5, 1.0, v5
	v_rcp_f32_e32 v6, v5
	v_pk_mul_f32 v[8:9], v[70:71], v[4:5] op_sel_hi:[1,0]
	v_add_f32_e32 v5, 1.0, v7
	v_pk_mul_f32 v[10:11], v[80:81], v[4:5] op_sel_hi:[1,0]
	s_nop 0
	v_mul_f32_e32 v7, 0xbfb8aa3b, v10
	v_exp_f32_e32 v14, v7
	v_mul_f32_e32 v7, 0xbfb8aa3b, v11
	v_exp_f32_e32 v15, v7
	v_rcp_f32_e32 v7, v5
	v_add_f32_e32 v5, 1.0, v14
	v_rcp_f32_e32 v14, v5
	v_add_f32_e32 v5, 1.0, v15
	v_rcp_f32_e32 v15, v5
	v_pk_mul_f32 v[6:7], v[12:13], v[6:7]
	v_pk_mul_f32 v[12:13], v[74:75], v[4:5] op_sel_hi:[1,0]
	v_pk_mul_f32 v[6:7], v[8:9], v[6:7]
	v_pk_mul_f32 v[8:9], v[72:73], v[4:5] op_sel_hi:[1,0]
	v_pk_mul_f32 v[10:11], v[10:11], v[14:15]
	v_mul_f32_e32 v5, 0xbfb8aa3b, v12
	v_exp_f32_e32 v5, v5
	v_pk_mul_f32 v[8:9], v[8:9], v[10:11]
	v_mul_f32_e32 v10, 0xbfb8aa3b, v13
	v_exp_f32_e32 v11, v10
	v_add_f32_e32 v5, 1.0, v5
	v_rcp_f32_e32 v10, v5
	v_pk_mul_f32 v[14:15], v[66:67], v[4:5] op_sel_hi:[1,0]
	v_add_f32_e32 v5, 1.0, v11
	v_pk_mul_f32 v[16:17], v[76:77], v[4:5] op_sel_hi:[1,0]
	s_nop 0
	v_mul_f32_e32 v11, 0xbfb8aa3b, v16
	v_exp_f32_e32 v18, v11
	v_mul_f32_e32 v11, 0xbfb8aa3b, v17
	v_exp_f32_e32 v19, v11
	v_rcp_f32_e32 v11, v5
	v_add_f32_e32 v5, 1.0, v18
	v_rcp_f32_e32 v18, v5
	v_add_f32_e32 v5, 1.0, v19
	v_rcp_f32_e32 v19, v5
	v_pk_mul_f32 v[10:11], v[12:13], v[10:11]
	v_pk_mul_f32 v[4:5], v[68:69], v[4:5] op_sel_hi:[1,0]
	v_pk_mul_f32 v[10:11], v[14:15], v[10:11]
	v_pk_mul_f32 v[12:13], v[16:17], v[18:19]
	s_nop 0
	v_pk_mul_f32 v[12:13], v[4:5], v[12:13]
	v_cvt_pk_bf16_f32 v4, v6, v7
	v_cvt_pk_bf16_f32 v5, v8, v9
	v_cvt_pk_bf16_f32 v6, v10, v11
	v_cvt_pk_bf16_f32 v7, v12, v13
	global_store_dwordx4 v[2:3], v[4:7], off
	s_andn2_b64 vcc, exec, s[96:97]
	s_cbranch_vccnz .LBB0_469
	s_branch .LBB0_378
.LBB0_265:
	s_cmp_lg_u32 s15, 0
	s_mov_b64 s[6:7], -1
	s_mov_b64 s[96:97], 0
	s_cselect_b64 s[8:9], -1, 0
	s_and_b64 vcc, exec, s[8:9]
	s_cbranch_vccz .LBB0_260
	s_branch .LBB0_263
.LBB0_262:
	s_and_b64 vcc, exec, s[8:9]
	s_cbranch_vccz .LBB0_260
;     __device__ __forceinline__ void operator()(AccRef acc, const pg8::Unit& u, int wr, int wc, int fr, int fq) const {
;         const size_t ub = (size_t)(u.pm * 4 + u.pn) * 16 * NTHREADS + opaque_tid();
;         const int row0 = u.pm * 256 + wr * 64 + fr, col0 = u.pn * 256 + wc * 32 + 8 * fq;
; #pragma unroll
;         for (int bj = 0; bj < 2; ++bj) {
;             const f32x4 bv0 = *(const f32x4*)(gb + col0 + bj * 128), bv1 = *(const f32x4*)(gb + col0 + bj * 128 + 4);
; #pragma unroll
;             for (int ai = 0; ai < 2; ++ai) {
;                 v4u pw4[4], tw4[4];
; #pragma unroll
;                 for (int m = 0; m < 4; ++m) {
;                     const size_t ci = ub + (size_t)((ai * 2 + bj) * 4 + m) * NTHREADS;
;                     pw4[m] = P[ci];
;                     if (!first) tw4[m] = TMP[ci]; else tw4[m] = (v4u){0u, 0u, 0u, 0u};
;                 }
; #pragma unroll
;                 for (int m = 0; m < 4; ++m) {
;                     const size_t ci = ub + (size_t)((ai * 2 + bj) * 4 + m) * NTHREADS;
;                     const v4u pw = pw4[m], tw = tw4[m];
;                     const float rs = rst[(row0 + ai * 128 + m * 16) & 255];
;                     float v[8];
;                     v[0] = sigmoidf_(acc[ai][bj][m][0][0] * rs + bv0[0]) * bflo(pw.x); v[1] = sigmoidf_(acc[ai][bj][m][0][1] * rs + bv0[1]) * bfhi(pw.x);
;                     v[2] = sigmoidf_(acc[ai][bj][m][0][2] * rs + bv0[2]) * bflo(pw.y); v[3] = sigmoidf_(acc[ai][bj][m][0][3] * rs + bv0[3]) * bfhi(pw.y);
;                     v[4] = sigmoidf_(acc[ai][bj][m][1][0] * rs + bv1[0]) * bflo(pw.z); v[5] = sigmoidf_(acc[ai][bj][m][1][1] * rs + bv1[1]) * bfhi(pw.z);
;                     v[6] = sigmoidf_(acc[ai][bj][m][1][2] * rs + bv1[2]) * bflo(pw.w); v[7] = sigmoidf_(acc[ai][bj][m][1][3] * rs + bv1[3]) * bfhi(pw.w);
;                     v[0] += bflo(tw.x); v[1] += bfhi(tw.x); v[2] += bflo(tw.y); v[3] += bfhi(tw.y);
;                     v[4] += bflo(tw.z); v[5] += bfhi(tw.z); v[6] += bflo(tw.w); v[7] += bfhi(tw.w);
;                     v4u w; w.x = pk2(v[0], v[1]); w.y = pk2(v[2], v[3]); w.z = pk2(v[4], v[5]); w.w = pk2(v[6], v[7]);
;                     if (!last) TMP[ci] = w;
;                     else *(v4u*)(MRG + (size_t)(row0 + ai * 128 + m * 16) * D + col0 + bj * 128) = w;
.LBB0_263:
	s_load_dwordx2 s[6:7], s[42:43], 0x38
	v_readlane_b32 s3, v255, 41
	v_lshlrev_b32_e32 v224, 4, v214
	v_lshlrev_b32_e32 v227, 5, v244
	s_waitcnt lgkmcnt(0)
	s_add_u32 s6, s6, s3
	s_addc_u32 s7, s7, 0
	s_add_u32 s6, s6, s16
	s_addc_u32 s7, s7, s17
	s_lshl_b32 s3, s40, 8
	s_or_b32 s3, s3, s67
	s_lshl_b32 s8, s3, 2
	s_add_u32 s6, s6, s8
	s_addc_u32 s7, s7, 0
	global_load_dwordx4 v[194:197], v227, s[6:7]
	global_load_dwordx4 v[198:201], v227, s[6:7] offset:16
	global_load_dwordx4 v[202:205], v227, s[6:7] offset:512
	global_load_dwordx4 v[206:209], v227, s[6:7] offset:528
	v_lshl_add_u32 v226, v244, 3, s3
	s_lshl_b32 s3, s45, 8
	s_add_i32 s3, s3, s71
	v_add_u32_e32 v225, s3, v245
	v_lshlrev_b32_e32 v226, 1, v226
	v_lshl_add_u32 v226, v225, 11, v226
	v_add_u32_e32 v225, 0x4000000, v224
	v_add_u32_e32 v227, s71, v245
	v_lshlrev_b32_e32 v227, 2, v227
	v_add_u32_e32 v227, 0x20100, v227
	s_lshl_b32 s3, s45, 2
	s_add_i32 s3, s3, s40
	s_ashr_i32 s8, s3, 31
	s_mov_b32 s6, s3
	s_mov_b32 s7, s8
	s_lshl_b64 s[6:7], s[6:7], 17
	s_add_u32 s6, s6, s68
	s_addc_u32 s7, s7, s69
	s_and_b64 vcc, exec, s[86:87]
	s_mov_b64 s[8:9], s[6:7]
	s_cbranch_vccnz .Lgate_ptr_done
	s_mov_b64 s[8:9], s[82:83]
.Lgate_ptr_done:
	s_cmp_lg_u64 s[84:85], 0
	s_cbranch_scc1 .Lgate_n
.Lgate_f:
	v_mov_b32_e32 v62, 0
	v_mov_b32_e32 v63, 0
	global_load_dwordx4 v[2:5], v224, s[6:7]
	s_add_u32 s6, s6, 0x2000
	s_addc_u32 s7, s7, 0
	global_load_dwordx4 v[10:13], v224, s[6:7]
	s_add_u32 s6, s6, 0x2000
	s_addc_u32 s7, s7, 0
	global_load_dwordx4 v[18:21], v224, s[6:7]
	s_add_u32 s6, s6, 0x2000
	s_addc_u32 s7, s7, 0
	global_load_dwordx4 v[26:29], v224, s[6:7]
	s_add_u32 s6, s6, 0x2000
	s_addc_u32 s7, s7, 0
	global_load_dwordx4 v[34:37], v224, s[6:7]
	s_add_u32 s6, s6, 0x2000
	s_addc_u32 s7, s7, 0
	global_load_dwordx4 v[42:45], v224, s[6:7]
	s_add_u32 s6, s6, 0x2000
	s_addc_u32 s7, s7, 0
	ds_read_b32 v210, v227 offset:0
	ds_read_b32 v211, v227 offset:64
	ds_read_b32 v212, v227 offset:128
	ds_read_b32 v213, v227 offset:192
	ds_read_b32 v228, v227 offset:512
	ds_read_b32 v229, v227 offset:576
	ds_read_b32 v230, v227 offset:640
	ds_read_b32 v231, v227 offset:704
	s_waitcnt lgkmcnt(0)
	s_waitcnt vmcnt(5)
	v_fma_f32 v50, v190, v210, v194
	v_fma_f32 v51, v191, v210, v195
	v_fma_f32 v52, v192, v210, v196
	v_fma_f32 v53, v193, v210, v197
	v_fma_f32 v54, v186, v210, v198
	v_fma_f32 v55, v187, v210, v199
	v_fma_f32 v56, v188, v210, v200
	v_fma_f32 v57, v189, v210, v201
	v_mul_f32_e32 v50, 0xbfb8aa3b, v50
	v_mul_f32_e32 v51, 0xbfb8aa3b, v51
	v_mul_f32_e32 v52, 0xbfb8aa3b, v52
	v_mul_f32_e32 v53, 0xbfb8aa3b, v53
	v_mul_f32_e32 v54, 0xbfb8aa3b, v54
	v_mul_f32_e32 v55, 0xbfb8aa3b, v55
	v_mul_f32_e32 v56, 0xbfb8aa3b, v56
	v_mul_f32_e32 v57, 0xbfb8aa3b, v57
	v_exp_f32_e32 v50, v50
	v_exp_f32_e32 v51, v51
	v_exp_f32_e32 v52, v52
	v_exp_f32_e32 v53, v53
	v_exp_f32_e32 v54, v54
	v_exp_f32_e32 v55, v55
	v_exp_f32_e32 v56, v56
	v_exp_f32_e32 v57, v57
	v_add_f32_e32 v50, 1.0, v50
	v_add_f32_e32 v51, 1.0, v51
	v_add_f32_e32 v52, 1.0, v52
	v_add_f32_e32 v53, 1.0, v53
	v_add_f32_e32 v54, 1.0, v54
	v_add_f32_e32 v55, 1.0, v55
	v_add_f32_e32 v56, 1.0, v56
	v_add_f32_e32 v57, 1.0, v57
	v_rcp_f32_e32 v50, v50
	v_rcp_f32_e32 v51, v51
	v_rcp_f32_e32 v52, v52
	v_rcp_f32_e32 v53, v53
	v_rcp_f32_e32 v54, v54
	v_rcp_f32_e32 v55, v55
	v_rcp_f32_e32 v56, v56
	v_rcp_f32_e32 v57, v57
	v_lshlrev_b32_e32 v58, 16, v2
	v_and_b32_e32 v59, 0xffff0000, v2
	v_pk_fma_f32 v[50:51], v[50:51], v[58:59], v[62:63]
	v_lshlrev_b32_e32 v58, 16, v3
	v_and_b32_e32 v59, 0xffff0000, v3
	v_pk_fma_f32 v[52:53], v[52:53], v[58:59], v[62:63]
	v_lshlrev_b32_e32 v58, 16, v4
	v_and_b32_e32 v59, 0xffff0000, v4
	v_pk_fma_f32 v[54:55], v[54:55], v[58:59], v[62:63]
	v_lshlrev_b32_e32 v58, 16, v5
	v_and_b32_e32 v59, 0xffff0000, v5
	v_pk_fma_f32 v[56:57], v[56:57], v[58:59], v[62:63]
	v_cvt_pk_bf16_f32 v2, v50, v51
	v_cvt_pk_bf16_f32 v3, v52, v53
	v_cvt_pk_bf16_f32 v4, v54, v55
	v_cvt_pk_bf16_f32 v5, v56, v57
	s_cbranch_vccz .Lgate_f_m0
	global_store_dwordx4 v225, v[2:5], s[8:9]
	s_add_u32 s8, s8, 0x2000
	s_addc_u32 s9, s9, 0
	s_branch .Lgate_f_j0
.Lgate_f_m0:
	global_store_dwordx4 v226, v[2:5], s[8:9]
	s_add_u32 s8, s8, 0x8000
	s_addc_u32 s9, s9, 0
.Lgate_f_j0:
	global_load_dwordx4 v[2:5], v224, s[6:7]
	s_add_u32 s6, s6, 0x2000
	s_addc_u32 s7, s7, 0
	s_waitcnt vmcnt(6)
	v_fma_f32 v50, v174, v211, v194
	v_fma_f32 v51, v175, v211, v195
	v_fma_f32 v52, v176, v211, v196
	v_fma_f32 v53, v177, v211, v197
	v_fma_f32 v54, v170, v211, v198
	v_fma_f32 v55, v171, v211, v199
	v_fma_f32 v56, v172, v211, v200
	v_fma_f32 v57, v173, v211, v201
	v_mul_f32_e32 v50, 0xbfb8aa3b, v50
	v_mul_f32_e32 v51, 0xbfb8aa3b, v51
	v_mul_f32_e32 v52, 0xbfb8aa3b, v52
	v_mul_f32_e32 v53, 0xbfb8aa3b, v53
	v_mul_f32_e32 v54, 0xbfb8aa3b, v54
	v_mul_f32_e32 v55, 0xbfb8aa3b, v55
	v_mul_f32_e32 v56, 0xbfb8aa3b, v56
	v_mul_f32_e32 v57, 0xbfb8aa3b, v57
	v_exp_f32_e32 v50, v50
	v_exp_f32_e32 v51, v51
	v_exp_f32_e32 v52, v52
	v_exp_f32_e32 v53, v53
	v_exp_f32_e32 v54, v54
	v_exp_f32_e32 v55, v55
	v_exp_f32_e32 v56, v56
	v_exp_f32_e32 v57, v57
	v_add_f32_e32 v50, 1.0, v50
	v_add_f32_e32 v51, 1.0, v51
	v_add_f32_e32 v52, 1.0, v52
	v_add_f32_e32 v53, 1.0, v53
	v_add_f32_e32 v54, 1.0, v54
	v_add_f32_e32 v55, 1.0, v55
	v_add_f32_e32 v56, 1.0, v56
	v_add_f32_e32 v57, 1.0, v57
	v_rcp_f32_e32 v50, v50
	v_rcp_f32_e32 v51, v51
	v_rcp_f32_e32 v52, v52
	v_rcp_f32_e32 v53, v53
	v_rcp_f32_e32 v54, v54
	v_rcp_f32_e32 v55, v55
	v_rcp_f32_e32 v56, v56
	v_rcp_f32_e32 v57, v57
	v_lshlrev_b32_e32 v58, 16, v10
	v_and_b32_e32 v59, 0xffff0000, v10
	v_pk_fma_f32 v[50:51], v[50:51], v[58:59], v[62:63]
	v_lshlrev_b32_e32 v58, 16, v11
	v_and_b32_e32 v59, 0xffff0000, v11
	v_pk_fma_f32 v[52:53], v[52:53], v[58:59], v[62:63]
	v_lshlrev_b32_e32 v58, 16, v12
	v_and_b32_e32 v59, 0xffff0000, v12
	v_pk_fma_f32 v[54:55], v[54:55], v[58:59], v[62:63]
	v_lshlrev_b32_e32 v58, 16, v13
	v_and_b32_e32 v59, 0xffff0000, v13
	v_pk_fma_f32 v[56:57], v[56:57], v[58:59], v[62:63]
	v_cvt_pk_bf16_f32 v10, v50, v51
	v_cvt_pk_bf16_f32 v11, v52, v53
	v_cvt_pk_bf16_f32 v12, v54, v55
	v_cvt_pk_bf16_f32 v13, v56, v57
	s_cbranch_vccz .Lgate_f_m1
	global_store_dwordx4 v225, v[10:13], s[8:9]
	s_add_u32 s8, s8, 0x2000
	s_addc_u32 s9, s9, 0
	s_branch .Lgate_f_j1
; __device__ __forceinline__ unsigned pk2(float lo, float hi) { f32x2_t v = {lo, hi}; bf16x2_t b = __builtin_convertvector(v, bf16x2_t); return __builtin_bit_cast(unsigned, b); }
; __device__ __forceinline__ float sigmoidf_(float x) { return __builtin_amdgcn_rcpf(1.0f + fexp2(-x * LOG2E)); }
;     __device__ __forceinline__ void operator()(AccRef acc, const pg8::Unit& u, int wr, int wc, int fr, int fq) const {
;     ...
;                 for (int m = 0; m < 4; ++m) {
;                     const size_t ci = ub + (size_t)((ai * 2 + bj) * 4 + m) * NTHREADS;
;                     const v4u pw = pw4[m], tw = tw4[m];
;                     const float rs = rst[(row0 + ai * 128 + m * 16) & 255];
;                     float v[8];
;                     v[0] = sigmoidf_(acc[ai][bj][m][0][0] * rs + bv0[0]) * bflo(pw.x); v[1] = sigmoidf_(acc[ai][bj][m][0][1] * rs + bv0[1]) * bfhi(pw.x);
;                     v[2] = sigmoidf_(acc[ai][bj][m][0][2] * rs + bv0[2]) * bflo(pw.y); v[3] = sigmoidf_(acc[ai][bj][m][0][3] * rs + bv0[3]) * bfhi(pw.y);
;                     v[4] = sigmoidf_(acc[ai][bj][m][1][0] * rs + bv1[0]) * bflo(pw.z); v[5] = sigmoidf_(acc[ai][bj][m][1][1] * rs + bv1[1]) * bfhi(pw.z);
;                     v[6] = sigmoidf_(acc[ai][bj][m][1][2] * rs + bv1[2]) * bflo(pw.w); v[7] = sigmoidf_(acc[ai][bj][m][1][3] * rs + bv1[3]) * bfhi(pw.w);
;                     v[0] += bflo(tw.x); v[1] += bfhi(tw.x); v[2] += bflo(tw.y); v[3] += bfhi(tw.y);
;                     v[4] += bflo(tw.z); v[5] += bfhi(tw.z); v[6] += bflo(tw.w); v[7] += bfhi(tw.w);
;                     v4u w; w.x = pk2(v[0], v[1]); w.y = pk2(v[2], v[3]); w.z = pk2(v[4], v[5]); w.w = pk2(v[6], v[7]);
;                     if (!last) TMP[ci] = w;
;                     else *(v4u*)(MRG + (size_t)(row0 + ai * 128 + m * 16) * D + col0 + bj * 128) = w;
.Lgate_f_m1:
	global_store_dwordx4 v226, v[10:13], s[8:9]
	s_add_u32 s8, s8, 0x8000
	s_addc_u32 s9, s9, 0
.Lgate_f_j1:
	global_load_dwordx4 v[10:13], v224, s[6:7]
	s_add_u32 s6, s6, 0x2000
	s_addc_u32 s7, s7, 0
	s_waitcnt vmcnt(7)
	v_fma_f32 v50, v158, v212, v194
	v_fma_f32 v51, v159, v212, v195
	v_fma_f32 v52, v160, v212, v196
	v_fma_f32 v53, v161, v212, v197
	v_fma_f32 v54, v154, v212, v198
	v_fma_f32 v55, v155, v212, v199
	v_fma_f32 v56, v156, v212, v200
	v_fma_f32 v57, v157, v212, v201
	v_mul_f32_e32 v50, 0xbfb8aa3b, v50
	v_mul_f32_e32 v51, 0xbfb8aa3b, v51
	v_mul_f32_e32 v52, 0xbfb8aa3b, v52
	v_mul_f32_e32 v53, 0xbfb8aa3b, v53
	v_mul_f32_e32 v54, 0xbfb8aa3b, v54
	v_mul_f32_e32 v55, 0xbfb8aa3b, v55
	v_mul_f32_e32 v56, 0xbfb8aa3b, v56
	v_mul_f32_e32 v57, 0xbfb8aa3b, v57
	v_exp_f32_e32 v50, v50
	v_exp_f32_e32 v51, v51
	v_exp_f32_e32 v52, v52
	v_exp_f32_e32 v53, v53
	v_exp_f32_e32 v54, v54
	v_exp_f32_e32 v55, v55
	v_exp_f32_e32 v56, v56
	v_exp_f32_e32 v57, v57
	v_add_f32_e32 v50, 1.0, v50
	v_add_f32_e32 v51, 1.0, v51
	v_add_f32_e32 v52, 1.0, v52
	v_add_f32_e32 v53, 1.0, v53
	v_add_f32_e32 v54, 1.0, v54
	v_add_f32_e32 v55, 1.0, v55
	v_add_f32_e32 v56, 1.0, v56
	v_add_f32_e32 v57, 1.0, v57
	v_rcp_f32_e32 v50, v50
	v_rcp_f32_e32 v51, v51
	v_rcp_f32_e32 v52, v52
	v_rcp_f32_e32 v53, v53
	v_rcp_f32_e32 v54, v54
	v_rcp_f32_e32 v55, v55
	v_rcp_f32_e32 v56, v56
	v_rcp_f32_e32 v57, v57
	v_lshlrev_b32_e32 v58, 16, v18
	v_and_b32_e32 v59, 0xffff0000, v18
	v_pk_fma_f32 v[50:51], v[50:51], v[58:59], v[62:63]
	v_lshlrev_b32_e32 v58, 16, v19
	v_and_b32_e32 v59, 0xffff0000, v19
	v_pk_fma_f32 v[52:53], v[52:53], v[58:59], v[62:63]
	v_lshlrev_b32_e32 v58, 16, v20
	v_and_b32_e32 v59, 0xffff0000, v20
	v_pk_fma_f32 v[54:55], v[54:55], v[58:59], v[62:63]
	v_lshlrev_b32_e32 v58, 16, v21
	v_and_b32_e32 v59, 0xffff0000, v21
	v_pk_fma_f32 v[56:57], v[56:57], v[58:59], v[62:63]
	v_cvt_pk_bf16_f32 v18, v50, v51
	v_cvt_pk_bf16_f32 v19, v52, v53
	v_cvt_pk_bf16_f32 v20, v54, v55
	v_cvt_pk_bf16_f32 v21, v56, v57
	s_cbranch_vccz .Lgate_f_m2
	global_store_dwordx4 v225, v[18:21], s[8:9]
	s_add_u32 s8, s8, 0x2000
	s_addc_u32 s9, s9, 0
	s_branch .Lgate_f_j2
.Lgate_f_m2:
	global_store_dwordx4 v226, v[18:21], s[8:9]
	s_add_u32 s8, s8, 0x8000
	s_addc_u32 s9, s9, 0
.Lgate_f_j2:
	global_load_dwordx4 v[18:21], v224, s[6:7]
	s_add_u32 s6, s6, 0x2000
	s_addc_u32 s7, s7, 0
	s_waitcnt vmcnt(8)
	v_fma_f32 v50, v142, v213, v194
	v_fma_f32 v51, v143, v213, v195
	v_fma_f32 v52, v144, v213, v196
	v_fma_f32 v53, v145, v213, v197
	v_fma_f32 v54, v138, v213, v198
	v_fma_f32 v55, v139, v213, v199
	v_fma_f32 v56, v140, v213, v200
	v_fma_f32 v57, v141, v213, v201
	v_mul_f32_e32 v50, 0xbfb8aa3b, v50
	v_mul_f32_e32 v51, 0xbfb8aa3b, v51
	v_mul_f32_e32 v52, 0xbfb8aa3b, v52
	v_mul_f32_e32 v53, 0xbfb8aa3b, v53
	v_mul_f32_e32 v54, 0xbfb8aa3b, v54
	v_mul_f32_e32 v55, 0xbfb8aa3b, v55
	v_mul_f32_e32 v56, 0xbfb8aa3b, v56
	v_mul_f32_e32 v57, 0xbfb8aa3b, v57
	v_exp_f32_e32 v50, v50
	v_exp_f32_e32 v51, v51
	v_exp_f32_e32 v52, v52
	v_exp_f32_e32 v53, v53
	v_exp_f32_e32 v54, v54
	v_exp_f32_e32 v55, v55
	v_exp_f32_e32 v56, v56
	v_exp_f32_e32 v57, v57
	v_add_f32_e32 v50, 1.0, v50
	v_add_f32_e32 v51, 1.0, v51
	v_add_f32_e32 v52, 1.0, v52
	v_add_f32_e32 v53, 1.0, v53
	v_add_f32_e32 v54, 1.0, v54
	v_add_f32_e32 v55, 1.0, v55
	v_add_f32_e32 v56, 1.0, v56
	v_add_f32_e32 v57, 1.0, v57
	v_rcp_f32_e32 v50, v50
	v_rcp_f32_e32 v51, v51
	v_rcp_f32_e32 v52, v52
	v_rcp_f32_e32 v53, v53
	v_rcp_f32_e32 v54, v54
	v_rcp_f32_e32 v55, v55
	v_rcp_f32_e32 v56, v56
	v_rcp_f32_e32 v57, v57
	v_lshlrev_b32_e32 v58, 16, v26
	v_and_b32_e32 v59, 0xffff0000, v26
	v_pk_fma_f32 v[50:51], v[50:51], v[58:59], v[62:63]
	v_lshlrev_b32_e32 v58, 16, v27
	v_and_b32_e32 v59, 0xffff0000, v27
	v_pk_fma_f32 v[52:53], v[52:53], v[58:59], v[62:63]
	v_lshlrev_b32_e32 v58, 16, v28
	v_and_b32_e32 v59, 0xffff0000, v28
	v_pk_fma_f32 v[54:55], v[54:55], v[58:59], v[62:63]
	v_lshlrev_b32_e32 v58, 16, v29
	v_and_b32_e32 v59, 0xffff0000, v29
	v_pk_fma_f32 v[56:57], v[56:57], v[58:59], v[62:63]
	v_cvt_pk_bf16_f32 v26, v50, v51
	v_cvt_pk_bf16_f32 v27, v52, v53
	v_cvt_pk_bf16_f32 v28, v54, v55
	v_cvt_pk_bf16_f32 v29, v56, v57
	s_cbranch_vccz .Lgate_f_m3
	global_store_dwordx4 v225, v[26:29], s[8:9]
	s_add_u32 s8, s8, 0x2000
	s_addc_u32 s9, s9, 0
	s_branch .Lgate_f_j3
.Lgate_f_m3:
	global_store_dwordx4 v226, v[26:29], s[8:9]
	s_sub_u32 s8, s8, 0x17f00
	s_subb_u32 s9, s9, 0
; __device__ __forceinline__ unsigned pk2(float lo, float hi) { f32x2_t v = {lo, hi}; bf16x2_t b = __builtin_convertvector(v, bf16x2_t); return __builtin_bit_cast(unsigned, b); }
; __device__ __forceinline__ float sigmoidf_(float x) { return __builtin_amdgcn_rcpf(1.0f + fexp2(-x * LOG2E)); }
;     __device__ __forceinline__ void operator()(AccRef acc, const pg8::Unit& u, int wr, int wc, int fr, int fq) const {
;     ...
;                 for (int m = 0; m < 4; ++m) {
;                     const size_t ci = ub + (size_t)((ai * 2 + bj) * 4 + m) * NTHREADS;
;                     const v4u pw = pw4[m], tw = tw4[m];
;                     const float rs = rst[(row0 + ai * 128 + m * 16) & 255];
;                     float v[8];
;                     v[0] = sigmoidf_(acc[ai][bj][m][0][0] * rs + bv0[0]) * bflo(pw.x); v[1] = sigmoidf_(acc[ai][bj][m][0][1] * rs + bv0[1]) * bfhi(pw.x);
;                     v[2] = sigmoidf_(acc[ai][bj][m][0][2] * rs + bv0[2]) * bflo(pw.y); v[3] = sigmoidf_(acc[ai][bj][m][0][3] * rs + bv0[3]) * bfhi(pw.y);
;                     v[4] = sigmoidf_(acc[ai][bj][m][1][0] * rs + bv1[0]) * bflo(pw.z); v[5] = sigmoidf_(acc[ai][bj][m][1][1] * rs + bv1[1]) * bfhi(pw.z);
;                     v[6] = sigmoidf_(acc[ai][bj][m][1][2] * rs + bv1[2]) * bflo(pw.w); v[7] = sigmoidf_(acc[ai][bj][m][1][3] * rs + bv1[3]) * bfhi(pw.w);
;                     v[0] += bflo(tw.x); v[1] += bfhi(tw.x); v[2] += bflo(tw.y); v[3] += bfhi(tw.y);
;                     v[4] += bflo(tw.z); v[5] += bfhi(tw.z); v[6] += bflo(tw.w); v[7] += bfhi(tw.w);
;                     v4u w; w.x = pk2(v[0], v[1]); w.y = pk2(v[2], v[3]); w.z = pk2(v[4], v[5]); w.w = pk2(v[6], v[7]);
;                     if (!last) TMP[ci] = w;
;                     else *(v4u*)(MRG + (size_t)(row0 + ai * 128 + m * 16) * D + col0 + bj * 128) = w;
.Lgate_f_j3:
	global_load_dwordx4 v[26:29], v224, s[6:7]
	s_add_u32 s6, s6, 0x2000
	s_addc_u32 s7, s7, 0
	s_waitcnt vmcnt(9)
	v_fma_f32 v50, v182, v210, v202
	v_fma_f32 v51, v183, v210, v203
	v_fma_f32 v52, v184, v210, v204
	v_fma_f32 v53, v185, v210, v205
	v_fma_f32 v54, v178, v210, v206
	v_fma_f32 v55, v179, v210, v207
	v_fma_f32 v56, v180, v210, v208
	v_fma_f32 v57, v181, v210, v209
	v_mul_f32_e32 v50, 0xbfb8aa3b, v50
	v_mul_f32_e32 v51, 0xbfb8aa3b, v51
	v_mul_f32_e32 v52, 0xbfb8aa3b, v52
	v_mul_f32_e32 v53, 0xbfb8aa3b, v53
	v_mul_f32_e32 v54, 0xbfb8aa3b, v54
	v_mul_f32_e32 v55, 0xbfb8aa3b, v55
	v_mul_f32_e32 v56, 0xbfb8aa3b, v56
	v_mul_f32_e32 v57, 0xbfb8aa3b, v57
	v_exp_f32_e32 v50, v50
	v_exp_f32_e32 v51, v51
	v_exp_f32_e32 v52, v52
	v_exp_f32_e32 v53, v53
	v_exp_f32_e32 v54, v54
	v_exp_f32_e32 v55, v55
	v_exp_f32_e32 v56, v56
	v_exp_f32_e32 v57, v57
	v_add_f32_e32 v50, 1.0, v50
	v_add_f32_e32 v51, 1.0, v51
	v_add_f32_e32 v52, 1.0, v52
	v_add_f32_e32 v53, 1.0, v53
	v_add_f32_e32 v54, 1.0, v54
	v_add_f32_e32 v55, 1.0, v55
	v_add_f32_e32 v56, 1.0, v56
	v_add_f32_e32 v57, 1.0, v57
	v_rcp_f32_e32 v50, v50
	v_rcp_f32_e32 v51, v51
	v_rcp_f32_e32 v52, v52
	v_rcp_f32_e32 v53, v53
	v_rcp_f32_e32 v54, v54
	v_rcp_f32_e32 v55, v55
	v_rcp_f32_e32 v56, v56
	v_rcp_f32_e32 v57, v57
	v_lshlrev_b32_e32 v58, 16, v34
	v_and_b32_e32 v59, 0xffff0000, v34
	v_pk_fma_f32 v[50:51], v[50:51], v[58:59], v[62:63]
	v_lshlrev_b32_e32 v58, 16, v35
	v_and_b32_e32 v59, 0xffff0000, v35
	v_pk_fma_f32 v[52:53], v[52:53], v[58:59], v[62:63]
	v_lshlrev_b32_e32 v58, 16, v36
	v_and_b32_e32 v59, 0xffff0000, v36
	v_pk_fma_f32 v[54:55], v[54:55], v[58:59], v[62:63]
	v_lshlrev_b32_e32 v58, 16, v37
	v_and_b32_e32 v59, 0xffff0000, v37
	v_pk_fma_f32 v[56:57], v[56:57], v[58:59], v[62:63]
	v_cvt_pk_bf16_f32 v34, v50, v51
	v_cvt_pk_bf16_f32 v35, v52, v53
	v_cvt_pk_bf16_f32 v36, v54, v55
	v_cvt_pk_bf16_f32 v37, v56, v57
	s_cbranch_vccz .Lgate_f_m4
	global_store_dwordx4 v225, v[34:37], s[8:9]
	s_add_u32 s8, s8, 0x2000
	s_addc_u32 s9, s9, 0
	s_branch .Lgate_f_j4
.Lgate_f_m4:
	global_store_dwordx4 v226, v[34:37], s[8:9]
	s_add_u32 s8, s8, 0x8000
	s_addc_u32 s9, s9, 0
.Lgate_f_j4:
	global_load_dwordx4 v[34:37], v224, s[6:7]
	s_add_u32 s6, s6, 0x2000
	s_addc_u32 s7, s7, 0
	s_waitcnt vmcnt(10)
	v_fma_f32 v50, v166, v211, v202
	v_fma_f32 v51, v167, v211, v203
	v_fma_f32 v52, v168, v211, v204
	v_fma_f32 v53, v169, v211, v205
	v_fma_f32 v54, v162, v211, v206
	v_fma_f32 v55, v163, v211, v207
	v_fma_f32 v56, v164, v211, v208
	v_fma_f32 v57, v165, v211, v209
	v_mul_f32_e32 v50, 0xbfb8aa3b, v50
	v_mul_f32_e32 v51, 0xbfb8aa3b, v51
	v_mul_f32_e32 v52, 0xbfb8aa3b, v52
	v_mul_f32_e32 v53, 0xbfb8aa3b, v53
	v_mul_f32_e32 v54, 0xbfb8aa3b, v54
	v_mul_f32_e32 v55, 0xbfb8aa3b, v55
	v_mul_f32_e32 v56, 0xbfb8aa3b, v56
	v_mul_f32_e32 v57, 0xbfb8aa3b, v57
	v_exp_f32_e32 v50, v50
	v_exp_f32_e32 v51, v51
	v_exp_f32_e32 v52, v52
	v_exp_f32_e32 v53, v53
	v_exp_f32_e32 v54, v54
	v_exp_f32_e32 v55, v55
	v_exp_f32_e32 v56, v56
	v_exp_f32_e32 v57, v57
	v_add_f32_e32 v50, 1.0, v50
	v_add_f32_e32 v51, 1.0, v51
	v_add_f32_e32 v52, 1.0, v52
	v_add_f32_e32 v53, 1.0, v53
	v_add_f32_e32 v54, 1.0, v54
	v_add_f32_e32 v55, 1.0, v55
	v_add_f32_e32 v56, 1.0, v56
	v_add_f32_e32 v57, 1.0, v57
	v_rcp_f32_e32 v50, v50
	v_rcp_f32_e32 v51, v51
	v_rcp_f32_e32 v52, v52
	v_rcp_f32_e32 v53, v53
	v_rcp_f32_e32 v54, v54
	v_rcp_f32_e32 v55, v55
	v_rcp_f32_e32 v56, v56
	v_rcp_f32_e32 v57, v57
	v_lshlrev_b32_e32 v58, 16, v42
	v_and_b32_e32 v59, 0xffff0000, v42
	v_pk_fma_f32 v[50:51], v[50:51], v[58:59], v[62:63]
	v_lshlrev_b32_e32 v58, 16, v43
	v_and_b32_e32 v59, 0xffff0000, v43
	v_pk_fma_f32 v[52:53], v[52:53], v[58:59], v[62:63]
	v_lshlrev_b32_e32 v58, 16, v44
	v_and_b32_e32 v59, 0xffff0000, v44
	v_pk_fma_f32 v[54:55], v[54:55], v[58:59], v[62:63]
	v_lshlrev_b32_e32 v58, 16, v45
	v_and_b32_e32 v59, 0xffff0000, v45
	v_pk_fma_f32 v[56:57], v[56:57], v[58:59], v[62:63]
	v_cvt_pk_bf16_f32 v42, v50, v51
	v_cvt_pk_bf16_f32 v43, v52, v53
	v_cvt_pk_bf16_f32 v44, v54, v55
	v_cvt_pk_bf16_f32 v45, v56, v57
	s_cbranch_vccz .Lgate_f_m5
	global_store_dwordx4 v225, v[42:45], s[8:9]
	s_add_u32 s8, s8, 0x2000
	s_addc_u32 s9, s9, 0
	s_branch .Lgate_f_j5
.Lgate_f_m5:
	global_store_dwordx4 v226, v[42:45], s[8:9]
	s_add_u32 s8, s8, 0x8000
	s_addc_u32 s9, s9, 0
.Lgate_f_j5:
	global_load_dwordx4 v[42:45], v224, s[6:7]
	s_add_u32 s6, s6, 0x2000
	s_addc_u32 s7, s7, 0
	s_waitcnt vmcnt(10)
	v_fma_f32 v50, v150, v212, v202
	v_fma_f32 v51, v151, v212, v203
	v_fma_f32 v52, v152, v212, v204
	v_fma_f32 v53, v153, v212, v205
	v_fma_f32 v54, v146, v212, v206
	v_fma_f32 v55, v147, v212, v207
	v_fma_f32 v56, v148, v212, v208
	v_fma_f32 v57, v149, v212, v209
	v_mul_f32_e32 v50, 0xbfb8aa3b, v50
	v_mul_f32_e32 v51, 0xbfb8aa3b, v51
	v_mul_f32_e32 v52, 0xbfb8aa3b, v52
	v_mul_f32_e32 v53, 0xbfb8aa3b, v53
	v_mul_f32_e32 v54, 0xbfb8aa3b, v54
	v_mul_f32_e32 v55, 0xbfb8aa3b, v55
	v_mul_f32_e32 v56, 0xbfb8aa3b, v56
	v_mul_f32_e32 v57, 0xbfb8aa3b, v57
	v_exp_f32_e32 v50, v50
	v_exp_f32_e32 v51, v51
	v_exp_f32_e32 v52, v52
	v_exp_f32_e32 v53, v53
	v_exp_f32_e32 v54, v54
	v_exp_f32_e32 v55, v55
	v_exp_f32_e32 v56, v56
	v_exp_f32_e32 v57, v57
	v_add_f32_e32 v50, 1.0, v50
	v_add_f32_e32 v51, 1.0, v51
	v_add_f32_e32 v52, 1.0, v52
	v_add_f32_e32 v53, 1.0, v53
	v_add_f32_e32 v54, 1.0, v54
	v_add_f32_e32 v55, 1.0, v55
	v_add_f32_e32 v56, 1.0, v56
	v_add_f32_e32 v57, 1.0, v57
	v_rcp_f32_e32 v50, v50
	v_rcp_f32_e32 v51, v51
	v_rcp_f32_e32 v52, v52
	v_rcp_f32_e32 v53, v53
	v_rcp_f32_e32 v54, v54
	v_rcp_f32_e32 v55, v55
	v_rcp_f32_e32 v56, v56
	v_rcp_f32_e32 v57, v57
	v_lshlrev_b32_e32 v58, 16, v2
	v_and_b32_e32 v59, 0xffff0000, v2
	v_pk_fma_f32 v[50:51], v[50:51], v[58:59], v[62:63]
	v_lshlrev_b32_e32 v58, 16, v3
	v_and_b32_e32 v59, 0xffff0000, v3
	v_pk_fma_f32 v[52:53], v[52:53], v[58:59], v[62:63]
	v_lshlrev_b32_e32 v58, 16, v4
	v_and_b32_e32 v59, 0xffff0000, v4
	v_pk_fma_f32 v[54:55], v[54:55], v[58:59], v[62:63]
	v_lshlrev_b32_e32 v58, 16, v5
	v_and_b32_e32 v59, 0xffff0000, v5
	v_pk_fma_f32 v[56:57], v[56:57], v[58:59], v[62:63]
	v_cvt_pk_bf16_f32 v2, v50, v51
	v_cvt_pk_bf16_f32 v3, v52, v53
	v_cvt_pk_bf16_f32 v4, v54, v55
	v_cvt_pk_bf16_f32 v5, v56, v57
	s_cbranch_vccz .Lgate_f_m6
	global_store_dwordx4 v225, v[2:5], s[8:9]
	s_add_u32 s8, s8, 0x2000
	s_addc_u32 s9, s9, 0
	s_branch .Lgate_f_j6

; __device__ __forceinline__ unsigned pk2(float lo, float hi) { f32x2_t v = {lo, hi}; bf16x2_t b = __builtin_convertvector(v, bf16x2_t); return __builtin_bit_cast(unsigned, b); }
; __device__ __forceinline__ float sigmoidf_(float x) { return __builtin_amdgcn_rcpf(1.0f + fexp2(-x * LOG2E)); }
;     __device__ __forceinline__ void operator()(AccRef acc, const pg8::Unit& u, int wr, int wc, int fr, int fq) const {
;     ...
;                 for (int m = 0; m < 4; ++m) {
;                     const size_t ci = ub + (size_t)((ai * 2 + bj) * 4 + m) * NTHREADS;
;                     const v4u pw = pw4[m], tw = tw4[m];
;                     const float rs = rst[(row0 + ai * 128 + m * 16) & 255];
;                     float v[8];
;                     v[0] = sigmoidf_(acc[ai][bj][m][0][0] * rs + bv0[0]) * bflo(pw.x); v[1] = sigmoidf_(acc[ai][bj][m][0][1] * rs + bv0[1]) * bfhi(pw.x);
;                     v[2] = sigmoidf_(acc[ai][bj][m][0][2] * rs + bv0[2]) * bflo(pw.y); v[3] = sigmoidf_(acc[ai][bj][m][0][3] * rs + bv0[3]) * bfhi(pw.y);
;                     v[4] = sigmoidf_(acc[ai][bj][m][1][0] * rs + bv1[0]) * bflo(pw.z); v[5] = sigmoidf_(acc[ai][bj][m][1][1] * rs + bv1[1]) * bfhi(pw.z);
;                     v[6] = sigmoidf_(acc[ai][bj][m][1][2] * rs + bv1[2]) * bflo(pw.w); v[7] = sigmoidf_(acc[ai][bj][m][1][3] * rs + bv1[3]) * bfhi(pw.w);
;                     v[0] += bflo(tw.x); v[1] += bfhi(tw.x); v[2] += bflo(tw.y); v[3] += bfhi(tw.y);
;                     v[4] += bflo(tw.z); v[5] += bfhi(tw.z); v[6] += bflo(tw.w); v[7] += bfhi(tw.w);
;                     v4u w; w.x = pk2(v[0], v[1]); w.y = pk2(v[2], v[3]); w.z = pk2(v[4], v[5]); w.w = pk2(v[6], v[7]);
;                     if (!last) TMP[ci] = w;
;                     else *(v4u*)(MRG + (size_t)(row0 + ai * 128 + m * 16) * D + col0 + bj * 128) = w;
.Lgate_f_j6:
	global_load_dwordx4 v[2:5], v224, s[6:7]
	s_add_u32 s6, s6, 0x2000
	s_addc_u32 s7, s7, 0
	s_waitcnt vmcnt(10)
	v_fma_f32 v50, v134, v213, v202
	v_fma_f32 v51, v135, v213, v203
	v_fma_f32 v52, v136, v213, v204
	v_fma_f32 v53, v137, v213, v205
	v_fma_f32 v54, v130, v213, v206
	v_fma_f32 v55, v131, v213, v207
	v_fma_f32 v56, v132, v213, v208
	v_fma_f32 v57, v133, v213, v209
	v_mul_f32_e32 v50, 0xbfb8aa3b, v50
	v_mul_f32_e32 v51, 0xbfb8aa3b, v51
	v_mul_f32_e32 v52, 0xbfb8aa3b, v52
	v_mul_f32_e32 v53, 0xbfb8aa3b, v53
	v_mul_f32_e32 v54, 0xbfb8aa3b, v54
	v_mul_f32_e32 v55, 0xbfb8aa3b, v55
	v_mul_f32_e32 v56, 0xbfb8aa3b, v56
	v_mul_f32_e32 v57, 0xbfb8aa3b, v57
	v_exp_f32_e32 v50, v50
	v_exp_f32_e32 v51, v51
	v_exp_f32_e32 v52, v52
	v_exp_f32_e32 v53, v53
	v_exp_f32_e32 v54, v54
	v_exp_f32_e32 v55, v55
	v_exp_f32_e32 v56, v56
	v_exp_f32_e32 v57, v57
	v_add_f32_e32 v50, 1.0, v50
	v_add_f32_e32 v51, 1.0, v51
	v_add_f32_e32 v52, 1.0, v52
	v_add_f32_e32 v53, 1.0, v53
	v_add_f32_e32 v54, 1.0, v54
	v_add_f32_e32 v55, 1.0, v55
	v_add_f32_e32 v56, 1.0, v56
	v_add_f32_e32 v57, 1.0, v57
	v_rcp_f32_e32 v50, v50
	v_rcp_f32_e32 v51, v51
	v_rcp_f32_e32 v52, v52
	v_rcp_f32_e32 v53, v53
	v_rcp_f32_e32 v54, v54
	v_rcp_f32_e32 v55, v55
	v_rcp_f32_e32 v56, v56
	v_rcp_f32_e32 v57, v57
	v_lshlrev_b32_e32 v58, 16, v10
	v_and_b32_e32 v59, 0xffff0000, v10
	v_pk_fma_f32 v[50:51], v[50:51], v[58:59], v[62:63]
	v_lshlrev_b32_e32 v58, 16, v11
	v_and_b32_e32 v59, 0xffff0000, v11
	v_pk_fma_f32 v[52:53], v[52:53], v[58:59], v[62:63]
	v_lshlrev_b32_e32 v58, 16, v12
	v_and_b32_e32 v59, 0xffff0000, v12
	v_pk_fma_f32 v[54:55], v[54:55], v[58:59], v[62:63]
	v_lshlrev_b32_e32 v58, 16, v13
	v_and_b32_e32 v59, 0xffff0000, v13
	v_pk_fma_f32 v[56:57], v[56:57], v[58:59], v[62:63]
	v_cvt_pk_bf16_f32 v10, v50, v51
	v_cvt_pk_bf16_f32 v11, v52, v53
	v_cvt_pk_bf16_f32 v12, v54, v55
	v_cvt_pk_bf16_f32 v13, v56, v57
	s_cbranch_vccz .Lgate_f_m7
	global_store_dwordx4 v225, v[10:13], s[8:9]
	s_add_u32 s8, s8, 0x2000
	s_addc_u32 s9, s9, 0
	s_branch .Lgate_f_j7
.Lgate_f_m7:
	global_store_dwordx4 v226, v[10:13], s[8:9]
	s_add_u32 s8, s8, 0x27f00
	s_addc_u32 s9, s9, 0
.Lgate_f_j7:
	global_load_dwordx4 v[10:13], v224, s[6:7]
	s_add_u32 s6, s6, 0x2000
	s_addc_u32 s7, s7, 0
	s_waitcnt vmcnt(10)
	v_fma_f32 v50, v126, v228, v194
	v_fma_f32 v51, v127, v228, v195
	v_fma_f32 v52, v128, v228, v196
	v_fma_f32 v53, v129, v228, v197
	v_fma_f32 v54, v122, v228, v198
	v_fma_f32 v55, v123, v228, v199
	v_fma_f32 v56, v124, v228, v200
	v_fma_f32 v57, v125, v228, v201
	v_mul_f32_e32 v50, 0xbfb8aa3b, v50
	v_mul_f32_e32 v51, 0xbfb8aa3b, v51
	v_mul_f32_e32 v52, 0xbfb8aa3b, v52
	v_mul_f32_e32 v53, 0xbfb8aa3b, v53
	v_mul_f32_e32 v54, 0xbfb8aa3b, v54
	v_mul_f32_e32 v55, 0xbfb8aa3b, v55
	v_mul_f32_e32 v56, 0xbfb8aa3b, v56
	v_mul_f32_e32 v57, 0xbfb8aa3b, v57
	v_exp_f32_e32 v50, v50
	v_exp_f32_e32 v51, v51
	v_exp_f32_e32 v52, v52
	v_exp_f32_e32 v53, v53
	v_exp_f32_e32 v54, v54
	v_exp_f32_e32 v55, v55
	v_exp_f32_e32 v56, v56
	v_exp_f32_e32 v57, v57
	v_add_f32_e32 v50, 1.0, v50
	v_add_f32_e32 v51, 1.0, v51
	v_add_f32_e32 v52, 1.0, v52
	v_add_f32_e32 v53, 1.0, v53
	v_add_f32_e32 v54, 1.0, v54
	v_add_f32_e32 v55, 1.0, v55
	v_add_f32_e32 v56, 1.0, v56
	v_add_f32_e32 v57, 1.0, v57
	v_rcp_f32_e32 v50, v50
	v_rcp_f32_e32 v51, v51
	v_rcp_f32_e32 v52, v52
	v_rcp_f32_e32 v53, v53
	v_rcp_f32_e32 v54, v54
	v_rcp_f32_e32 v55, v55
	v_rcp_f32_e32 v56, v56
	v_rcp_f32_e32 v57, v57
	v_lshlrev_b32_e32 v58, 16, v18
	v_and_b32_e32 v59, 0xffff0000, v18
	v_pk_fma_f32 v[50:51], v[50:51], v[58:59], v[62:63]
	v_lshlrev_b32_e32 v58, 16, v19
	v_and_b32_e32 v59, 0xffff0000, v19
	v_pk_fma_f32 v[52:53], v[52:53], v[58:59], v[62:63]
	v_lshlrev_b32_e32 v58, 16, v20
	v_and_b32_e32 v59, 0xffff0000, v20
	v_pk_fma_f32 v[54:55], v[54:55], v[58:59], v[62:63]
	v_lshlrev_b32_e32 v58, 16, v21
	v_and_b32_e32 v59, 0xffff0000, v21
	v_pk_fma_f32 v[56:57], v[56:57], v[58:59], v[62:63]
	v_cvt_pk_bf16_f32 v18, v50, v51
	v_cvt_pk_bf16_f32 v19, v52, v53
	v_cvt_pk_bf16_f32 v20, v54, v55
	v_cvt_pk_bf16_f32 v21, v56, v57
	s_cbranch_vccz .Lgate_f_m8
	global_store_dwordx4 v225, v[18:21], s[8:9]
	s_add_u32 s8, s8, 0x2000
	s_addc_u32 s9, s9, 0
	s_branch .Lgate_f_j8

; __device__ __forceinline__ unsigned pk2(float lo, float hi) { f32x2_t v = {lo, hi}; bf16x2_t b = __builtin_convertvector(v, bf16x2_t); return __builtin_bit_cast(unsigned, b); }
; __device__ __forceinline__ float sigmoidf_(float x) { return __builtin_amdgcn_rcpf(1.0f + fexp2(-x * LOG2E)); }
;     __device__ __forceinline__ void operator()(AccRef acc, const pg8::Unit& u, int wr, int wc, int fr, int fq) const {
;     ...
;                 for (int m = 0; m < 4; ++m) {
;                     const size_t ci = ub + (size_t)((ai * 2 + bj) * 4 + m) * NTHREADS;
;                     const v4u pw = pw4[m], tw = tw4[m];
;                     const float rs = rst[(row0 + ai * 128 + m * 16) & 255];
;                     float v[8];
;                     v[0] = sigmoidf_(acc[ai][bj][m][0][0] * rs + bv0[0]) * bflo(pw.x); v[1] = sigmoidf_(acc[ai][bj][m][0][1] * rs + bv0[1]) * bfhi(pw.x);
;                     v[2] = sigmoidf_(acc[ai][bj][m][0][2] * rs + bv0[2]) * bflo(pw.y); v[3] = sigmoidf_(acc[ai][bj][m][0][3] * rs + bv0[3]) * bfhi(pw.y);
;                     v[4] = sigmoidf_(acc[ai][bj][m][1][0] * rs + bv1[0]) * bflo(pw.z); v[5] = sigmoidf_(acc[ai][bj][m][1][1] * rs + bv1[1]) * bfhi(pw.z);
;                     v[6] = sigmoidf_(acc[ai][bj][m][1][2] * rs + bv1[2]) * bflo(pw.w); v[7] = sigmoidf_(acc[ai][bj][m][1][3] * rs + bv1[3]) * bfhi(pw.w);
;                     v[0] += bflo(tw.x); v[1] += bfhi(tw.x); v[2] += bflo(tw.y); v[3] += bfhi(tw.y);
;                     v[4] += bflo(tw.z); v[5] += bfhi(tw.z); v[6] += bflo(tw.w); v[7] += bfhi(tw.w);
;                     v4u w; w.x = pk2(v[0], v[1]); w.y = pk2(v[2], v[3]); w.z = pk2(v[4], v[5]); w.w = pk2(v[6], v[7]);
;                     if (!last) TMP[ci] = w;
;                     else *(v4u*)(MRG + (size_t)(row0 + ai * 128 + m * 16) * D + col0 + bj * 128) = w;
.Lgate_f_j8:
	global_load_dwordx4 v[18:21], v224, s[6:7]
	s_add_u32 s6, s6, 0x2000
	s_addc_u32 s7, s7, 0
	s_waitcnt vmcnt(10)
	v_fma_f32 v50, v110, v229, v194
	v_fma_f32 v51, v111, v229, v195
	v_fma_f32 v52, v112, v229, v196
	v_fma_f32 v53, v113, v229, v197
	v_fma_f32 v54, v106, v229, v198
	v_fma_f32 v55, v107, v229, v199
	v_fma_f32 v56, v108, v229, v200
	v_fma_f32 v57, v109, v229, v201
	v_mul_f32_e32 v50, 0xbfb8aa3b, v50
	v_mul_f32_e32 v51, 0xbfb8aa3b, v51
	v_mul_f32_e32 v52, 0xbfb8aa3b, v52
	v_mul_f32_e32 v53, 0xbfb8aa3b, v53
	v_mul_f32_e32 v54, 0xbfb8aa3b, v54
	v_mul_f32_e32 v55, 0xbfb8aa3b, v55
	v_mul_f32_e32 v56, 0xbfb8aa3b, v56
	v_mul_f32_e32 v57, 0xbfb8aa3b, v57
	v_exp_f32_e32 v50, v50
	v_exp_f32_e32 v51, v51
	v_exp_f32_e32 v52, v52
	v_exp_f32_e32 v53, v53
	v_exp_f32_e32 v54, v54
	v_exp_f32_e32 v55, v55
	v_exp_f32_e32 v56, v56
	v_exp_f32_e32 v57, v57
	v_add_f32_e32 v50, 1.0, v50
	v_add_f32_e32 v51, 1.0, v51
	v_add_f32_e32 v52, 1.0, v52
	v_add_f32_e32 v53, 1.0, v53
	v_add_f32_e32 v54, 1.0, v54
	v_add_f32_e32 v55, 1.0, v55
	v_add_f32_e32 v56, 1.0, v56
	v_add_f32_e32 v57, 1.0, v57
	v_rcp_f32_e32 v50, v50
	v_rcp_f32_e32 v51, v51
	v_rcp_f32_e32 v52, v52
	v_rcp_f32_e32 v53, v53
	v_rcp_f32_e32 v54, v54
	v_rcp_f32_e32 v55, v55
	v_rcp_f32_e32 v56, v56
	v_rcp_f32_e32 v57, v57
	v_lshlrev_b32_e32 v58, 16, v26
	v_and_b32_e32 v59, 0xffff0000, v26
	v_pk_fma_f32 v[50:51], v[50:51], v[58:59], v[62:63]
	v_lshlrev_b32_e32 v58, 16, v27
	v_and_b32_e32 v59, 0xffff0000, v27
	v_pk_fma_f32 v[52:53], v[52:53], v[58:59], v[62:63]
	v_lshlrev_b32_e32 v58, 16, v28
	v_and_b32_e32 v59, 0xffff0000, v28
	v_pk_fma_f32 v[54:55], v[54:55], v[58:59], v[62:63]
	v_lshlrev_b32_e32 v58, 16, v29
	v_and_b32_e32 v59, 0xffff0000, v29
	v_pk_fma_f32 v[56:57], v[56:57], v[58:59], v[62:63]
	v_cvt_pk_bf16_f32 v26, v50, v51
	v_cvt_pk_bf16_f32 v27, v52, v53
	v_cvt_pk_bf16_f32 v28, v54, v55
	v_cvt_pk_bf16_f32 v29, v56, v57
	s_cbranch_vccz .Lgate_f_m9
	global_store_dwordx4 v225, v[26:29], s[8:9]
	s_add_u32 s8, s8, 0x2000
	s_addc_u32 s9, s9, 0
	s_branch .Lgate_f_j9
.Lgate_f_m9:
	global_store_dwordx4 v226, v[26:29], s[8:9]
	s_add_u32 s8, s8, 0x8000
	s_addc_u32 s9, s9, 0
.Lgate_f_j9:
	global_load_dwordx4 v[26:29], v224, s[6:7]
	s_add_u32 s6, s6, 0x2000
	s_addc_u32 s7, s7, 0
	s_waitcnt vmcnt(10)
	v_fma_f32 v50, v94, v230, v194
	v_fma_f32 v51, v95, v230, v195
	v_fma_f32 v52, v96, v230, v196
	v_fma_f32 v53, v97, v230, v197
	v_fma_f32 v54, v90, v230, v198
	v_fma_f32 v55, v91, v230, v199
	v_fma_f32 v56, v92, v230, v200
	v_fma_f32 v57, v93, v230, v201
	v_mul_f32_e32 v50, 0xbfb8aa3b, v50
	v_mul_f32_e32 v51, 0xbfb8aa3b, v51
	v_mul_f32_e32 v52, 0xbfb8aa3b, v52
	v_mul_f32_e32 v53, 0xbfb8aa3b, v53
	v_mul_f32_e32 v54, 0xbfb8aa3b, v54
	v_mul_f32_e32 v55, 0xbfb8aa3b, v55
	v_mul_f32_e32 v56, 0xbfb8aa3b, v56
	v_mul_f32_e32 v57, 0xbfb8aa3b, v57
	v_exp_f32_e32 v50, v50
	v_exp_f32_e32 v51, v51
	v_exp_f32_e32 v52, v52
	v_exp_f32_e32 v53, v53
	v_exp_f32_e32 v54, v54
	v_exp_f32_e32 v55, v55
	v_exp_f32_e32 v56, v56
	v_exp_f32_e32 v57, v57
	v_add_f32_e32 v50, 1.0, v50
	v_add_f32_e32 v51, 1.0, v51
	v_add_f32_e32 v52, 1.0, v52
	v_add_f32_e32 v53, 1.0, v53
	v_add_f32_e32 v54, 1.0, v54
	v_add_f32_e32 v55, 1.0, v55
	v_add_f32_e32 v56, 1.0, v56
	v_add_f32_e32 v57, 1.0, v57
	v_rcp_f32_e32 v50, v50
	v_rcp_f32_e32 v51, v51
	v_rcp_f32_e32 v52, v52
	v_rcp_f32_e32 v53, v53
	v_rcp_f32_e32 v54, v54
	v_rcp_f32_e32 v55, v55
	v_rcp_f32_e32 v56, v56
	v_rcp_f32_e32 v57, v57
	v_lshlrev_b32_e32 v58, 16, v34
	v_and_b32_e32 v59, 0xffff0000, v34
	v_pk_fma_f32 v[50:51], v[50:51], v[58:59], v[62:63]
	v_lshlrev_b32_e32 v58, 16, v35
	v_and_b32_e32 v59, 0xffff0000, v35
	v_pk_fma_f32 v[52:53], v[52:53], v[58:59], v[62:63]
	v_lshlrev_b32_e32 v58, 16, v36
	v_and_b32_e32 v59, 0xffff0000, v36
	v_pk_fma_f32 v[54:55], v[54:55], v[58:59], v[62:63]
	v_lshlrev_b32_e32 v58, 16, v37
	v_and_b32_e32 v59, 0xffff0000, v37
	v_pk_fma_f32 v[56:57], v[56:57], v[58:59], v[62:63]
	v_cvt_pk_bf16_f32 v34, v50, v51
	v_cvt_pk_bf16_f32 v35, v52, v53
	v_cvt_pk_bf16_f32 v36, v54, v55
	v_cvt_pk_bf16_f32 v37, v56, v57
	s_cbranch_vccz .Lgate_f_m10
	global_store_dwordx4 v225, v[34:37], s[8:9]
	s_add_u32 s8, s8, 0x2000
	s_addc_u32 s9, s9, 0
	s_branch .Lgate_f_j10

; __device__ __forceinline__ unsigned pk2(float lo, float hi) { f32x2_t v = {lo, hi}; bf16x2_t b = __builtin_convertvector(v, bf16x2_t); return __builtin_bit_cast(unsigned, b); }
; __device__ __forceinline__ float sigmoidf_(float x) { return __builtin_amdgcn_rcpf(1.0f + fexp2(-x * LOG2E)); }
;     __device__ __forceinline__ void operator()(AccRef acc, const pg8::Unit& u, int wr, int wc, int fr, int fq) const {
;     ...
;                 for (int m = 0; m < 4; ++m) {
;                     const size_t ci = ub + (size_t)((ai * 2 + bj) * 4 + m) * NTHREADS;
;                     const v4u pw = pw4[m], tw = tw4[m];
;                     const float rs = rst[(row0 + ai * 128 + m * 16) & 255];
;                     float v[8];
;                     v[0] = sigmoidf_(acc[ai][bj][m][0][0] * rs + bv0[0]) * bflo(pw.x); v[1] = sigmoidf_(acc[ai][bj][m][0][1] * rs + bv0[1]) * bfhi(pw.x);
;                     v[2] = sigmoidf_(acc[ai][bj][m][0][2] * rs + bv0[2]) * bflo(pw.y); v[3] = sigmoidf_(acc[ai][bj][m][0][3] * rs + bv0[3]) * bfhi(pw.y);
;                     v[4] = sigmoidf_(acc[ai][bj][m][1][0] * rs + bv1[0]) * bflo(pw.z); v[5] = sigmoidf_(acc[ai][bj][m][1][1] * rs + bv1[1]) * bfhi(pw.z);
;                     v[6] = sigmoidf_(acc[ai][bj][m][1][2] * rs + bv1[2]) * bflo(pw.w); v[7] = sigmoidf_(acc[ai][bj][m][1][3] * rs + bv1[3]) * bfhi(pw.w);
;                     v[0] += bflo(tw.x); v[1] += bfhi(tw.x); v[2] += bflo(tw.y); v[3] += bfhi(tw.y);
;                     v[4] += bflo(tw.z); v[5] += bfhi(tw.z); v[6] += bflo(tw.w); v[7] += bfhi(tw.w);
;                     v4u w; w.x = pk2(v[0], v[1]); w.y = pk2(v[2], v[3]); w.z = pk2(v[4], v[5]); w.w = pk2(v[6], v[7]);
;                     if (!last) TMP[ci] = w;
;                     else *(v4u*)(MRG + (size_t)(row0 + ai * 128 + m * 16) * D + col0 + bj * 128) = w;
.Lgate_f_j10:
	s_waitcnt vmcnt(9)
	v_fma_f32 v50, v78, v231, v194
	v_fma_f32 v51, v79, v231, v195
	v_fma_f32 v52, v80, v231, v196
	v_fma_f32 v53, v81, v231, v197
	v_fma_f32 v54, v74, v231, v198
	v_fma_f32 v55, v75, v231, v199
	v_fma_f32 v56, v76, v231, v200
	v_fma_f32 v57, v77, v231, v201
	v_mul_f32_e32 v50, 0xbfb8aa3b, v50
	v_mul_f32_e32 v51, 0xbfb8aa3b, v51
	v_mul_f32_e32 v52, 0xbfb8aa3b, v52
	v_mul_f32_e32 v53, 0xbfb8aa3b, v53
	v_mul_f32_e32 v54, 0xbfb8aa3b, v54
	v_mul_f32_e32 v55, 0xbfb8aa3b, v55
	v_mul_f32_e32 v56, 0xbfb8aa3b, v56
	v_mul_f32_e32 v57, 0xbfb8aa3b, v57
	v_exp_f32_e32 v50, v50
	v_exp_f32_e32 v51, v51
	v_exp_f32_e32 v52, v52
	v_exp_f32_e32 v53, v53
	v_exp_f32_e32 v54, v54
	v_exp_f32_e32 v55, v55
	v_exp_f32_e32 v56, v56
	v_exp_f32_e32 v57, v57
	v_add_f32_e32 v50, 1.0, v50
	v_add_f32_e32 v51, 1.0, v51
	v_add_f32_e32 v52, 1.0, v52
	v_add_f32_e32 v53, 1.0, v53
	v_add_f32_e32 v54, 1.0, v54
	v_add_f32_e32 v55, 1.0, v55
	v_add_f32_e32 v56, 1.0, v56
	v_add_f32_e32 v57, 1.0, v57
	v_rcp_f32_e32 v50, v50
	v_rcp_f32_e32 v51, v51
	v_rcp_f32_e32 v52, v52
	v_rcp_f32_e32 v53, v53
	v_rcp_f32_e32 v54, v54
	v_rcp_f32_e32 v55, v55
	v_rcp_f32_e32 v56, v56
	v_rcp_f32_e32 v57, v57
	v_lshlrev_b32_e32 v58, 16, v42
	v_and_b32_e32 v59, 0xffff0000, v42
	v_pk_fma_f32 v[50:51], v[50:51], v[58:59], v[62:63]
	v_lshlrev_b32_e32 v58, 16, v43
	v_and_b32_e32 v59, 0xffff0000, v43
	v_pk_fma_f32 v[52:53], v[52:53], v[58:59], v[62:63]
	v_lshlrev_b32_e32 v58, 16, v44
	v_and_b32_e32 v59, 0xffff0000, v44
	v_pk_fma_f32 v[54:55], v[54:55], v[58:59], v[62:63]
	v_lshlrev_b32_e32 v58, 16, v45
	v_and_b32_e32 v59, 0xffff0000, v45
	v_pk_fma_f32 v[56:57], v[56:57], v[58:59], v[62:63]
	v_cvt_pk_bf16_f32 v42, v50, v51
	v_cvt_pk_bf16_f32 v43, v52, v53
	v_cvt_pk_bf16_f32 v44, v54, v55
	v_cvt_pk_bf16_f32 v45, v56, v57
	s_cbranch_vccz .Lgate_f_m11
	global_store_dwordx4 v225, v[42:45], s[8:9]
	s_add_u32 s8, s8, 0x2000
	s_addc_u32 s9, s9, 0
	s_branch .Lgate_f_j11
.Lgate_f_m11:
	global_store_dwordx4 v226, v[42:45], s[8:9]
	s_sub_u32 s8, s8, 0x17f00
	s_subb_u32 s9, s9, 0
.Lgate_f_j11:
	s_waitcnt vmcnt(8)
	v_fma_f32 v50, v118, v228, v202
	v_fma_f32 v51, v119, v228, v203
	v_fma_f32 v52, v120, v228, v204
	v_fma_f32 v53, v121, v228, v205
	v_fma_f32 v54, v114, v228, v206
	v_fma_f32 v55, v115, v228, v207
	v_fma_f32 v56, v116, v228, v208
	v_fma_f32 v57, v117, v228, v209
	v_mul_f32_e32 v50, 0xbfb8aa3b, v50
	v_mul_f32_e32 v51, 0xbfb8aa3b, v51
	v_mul_f32_e32 v52, 0xbfb8aa3b, v52
	v_mul_f32_e32 v53, 0xbfb8aa3b, v53
	v_mul_f32_e32 v54, 0xbfb8aa3b, v54
	v_mul_f32_e32 v55, 0xbfb8aa3b, v55
	v_mul_f32_e32 v56, 0xbfb8aa3b, v56
	v_mul_f32_e32 v57, 0xbfb8aa3b, v57
	v_exp_f32_e32 v50, v50
	v_exp_f32_e32 v51, v51
	v_exp_f32_e32 v52, v52
	v_exp_f32_e32 v53, v53
	v_exp_f32_e32 v54, v54
	v_exp_f32_e32 v55, v55
	v_exp_f32_e32 v56, v56
	v_exp_f32_e32 v57, v57
	v_add_f32_e32 v50, 1.0, v50
	v_add_f32_e32 v51, 1.0, v51
	v_add_f32_e32 v52, 1.0, v52
	v_add_f32_e32 v53, 1.0, v53
	v_add_f32_e32 v54, 1.0, v54
	v_add_f32_e32 v55, 1.0, v55
	v_add_f32_e32 v56, 1.0, v56
	v_add_f32_e32 v57, 1.0, v57
	v_rcp_f32_e32 v50, v50
	v_rcp_f32_e32 v51, v51
	v_rcp_f32_e32 v52, v52
	v_rcp_f32_e32 v53, v53
	v_rcp_f32_e32 v54, v54
	v_rcp_f32_e32 v55, v55
	v_rcp_f32_e32 v56, v56
	v_rcp_f32_e32 v57, v57
	v_lshlrev_b32_e32 v58, 16, v2
	v_and_b32_e32 v59, 0xffff0000, v2
	v_pk_fma_f32 v[50:51], v[50:51], v[58:59], v[62:63]
	v_lshlrev_b32_e32 v58, 16, v3
	v_and_b32_e32 v59, 0xffff0000, v3
	v_pk_fma_f32 v[52:53], v[52:53], v[58:59], v[62:63]
	v_lshlrev_b32_e32 v58, 16, v4
	v_and_b32_e32 v59, 0xffff0000, v4
	v_pk_fma_f32 v[54:55], v[54:55], v[58:59], v[62:63]
	v_lshlrev_b32_e32 v58, 16, v5
	v_and_b32_e32 v59, 0xffff0000, v5
	v_pk_fma_f32 v[56:57], v[56:57], v[58:59], v[62:63]
	v_cvt_pk_bf16_f32 v2, v50, v51
	v_cvt_pk_bf16_f32 v3, v52, v53
	v_cvt_pk_bf16_f32 v4, v54, v55
	v_cvt_pk_bf16_f32 v5, v56, v57
	s_cbranch_vccz .Lgate_f_m12
	global_store_dwordx4 v225, v[2:5], s[8:9]
	s_add_u32 s8, s8, 0x2000
	s_addc_u32 s9, s9, 0
	s_branch .Lgate_f_j12

; __device__ __forceinline__ unsigned pk2(float lo, float hi) { f32x2_t v = {lo, hi}; bf16x2_t b = __builtin_convertvector(v, bf16x2_t); return __builtin_bit_cast(unsigned, b); }
; __device__ __forceinline__ float sigmoidf_(float x) { return __builtin_amdgcn_rcpf(1.0f + fexp2(-x * LOG2E)); }
;     __device__ __forceinline__ void operator()(AccRef acc, const pg8::Unit& u, int wr, int wc, int fr, int fq) const {
;     ...
;                 for (int m = 0; m < 4; ++m) {
;                     const size_t ci = ub + (size_t)((ai * 2 + bj) * 4 + m) * NTHREADS;
;                     const v4u pw = pw4[m], tw = tw4[m];
;                     const float rs = rst[(row0 + ai * 128 + m * 16) & 255];
;                     float v[8];
;                     v[0] = sigmoidf_(acc[ai][bj][m][0][0] * rs + bv0[0]) * bflo(pw.x); v[1] = sigmoidf_(acc[ai][bj][m][0][1] * rs + bv0[1]) * bfhi(pw.x);
;                     v[2] = sigmoidf_(acc[ai][bj][m][0][2] * rs + bv0[2]) * bflo(pw.y); v[3] = sigmoidf_(acc[ai][bj][m][0][3] * rs + bv0[3]) * bfhi(pw.y);
;                     v[4] = sigmoidf_(acc[ai][bj][m][1][0] * rs + bv1[0]) * bflo(pw.z); v[5] = sigmoidf_(acc[ai][bj][m][1][1] * rs + bv1[1]) * bfhi(pw.z);
;                     v[6] = sigmoidf_(acc[ai][bj][m][1][2] * rs + bv1[2]) * bflo(pw.w); v[7] = sigmoidf_(acc[ai][bj][m][1][3] * rs + bv1[3]) * bfhi(pw.w);
;                     v[0] += bflo(tw.x); v[1] += bfhi(tw.x); v[2] += bflo(tw.y); v[3] += bfhi(tw.y);
;                     v[4] += bflo(tw.z); v[5] += bfhi(tw.z); v[6] += bflo(tw.w); v[7] += bfhi(tw.w);
;                     v4u w; w.x = pk2(v[0], v[1]); w.y = pk2(v[2], v[3]); w.z = pk2(v[4], v[5]); w.w = pk2(v[6], v[7]);
;                     if (!last) TMP[ci] = w;
;                     else *(v4u*)(MRG + (size_t)(row0 + ai * 128 + m * 16) * D + col0 + bj * 128) = w;
.Lgate_f_j12:
	s_waitcnt vmcnt(7)
	v_fma_f32 v50, v102, v229, v202
	v_fma_f32 v51, v103, v229, v203
	v_fma_f32 v52, v104, v229, v204
	v_fma_f32 v53, v105, v229, v205
	v_fma_f32 v54, v98, v229, v206
	v_fma_f32 v55, v99, v229, v207
	v_fma_f32 v56, v100, v229, v208
	v_fma_f32 v57, v101, v229, v209
	v_mul_f32_e32 v50, 0xbfb8aa3b, v50
	v_mul_f32_e32 v51, 0xbfb8aa3b, v51
	v_mul_f32_e32 v52, 0xbfb8aa3b, v52
	v_mul_f32_e32 v53, 0xbfb8aa3b, v53
	v_mul_f32_e32 v54, 0xbfb8aa3b, v54
	v_mul_f32_e32 v55, 0xbfb8aa3b, v55
	v_mul_f32_e32 v56, 0xbfb8aa3b, v56
	v_mul_f32_e32 v57, 0xbfb8aa3b, v57
	v_exp_f32_e32 v50, v50
	v_exp_f32_e32 v51, v51
	v_exp_f32_e32 v52, v52
	v_exp_f32_e32 v53, v53
	v_exp_f32_e32 v54, v54
	v_exp_f32_e32 v55, v55
	v_exp_f32_e32 v56, v56
	v_exp_f32_e32 v57, v57
	v_add_f32_e32 v50, 1.0, v50
	v_add_f32_e32 v51, 1.0, v51
	v_add_f32_e32 v52, 1.0, v52
	v_add_f32_e32 v53, 1.0, v53
	v_add_f32_e32 v54, 1.0, v54
	v_add_f32_e32 v55, 1.0, v55
	v_add_f32_e32 v56, 1.0, v56
	v_add_f32_e32 v57, 1.0, v57
	v_rcp_f32_e32 v50, v50
	v_rcp_f32_e32 v51, v51
	v_rcp_f32_e32 v52, v52
	v_rcp_f32_e32 v53, v53
	v_rcp_f32_e32 v54, v54
	v_rcp_f32_e32 v55, v55
	v_rcp_f32_e32 v56, v56
	v_rcp_f32_e32 v57, v57
	v_lshlrev_b32_e32 v58, 16, v10
	v_and_b32_e32 v59, 0xffff0000, v10
	v_pk_fma_f32 v[50:51], v[50:51], v[58:59], v[62:63]
	v_lshlrev_b32_e32 v58, 16, v11
	v_and_b32_e32 v59, 0xffff0000, v11
	v_pk_fma_f32 v[52:53], v[52:53], v[58:59], v[62:63]
	v_lshlrev_b32_e32 v58, 16, v12
	v_and_b32_e32 v59, 0xffff0000, v12
	v_pk_fma_f32 v[54:55], v[54:55], v[58:59], v[62:63]
	v_lshlrev_b32_e32 v58, 16, v13
	v_and_b32_e32 v59, 0xffff0000, v13
	v_pk_fma_f32 v[56:57], v[56:57], v[58:59], v[62:63]
	v_cvt_pk_bf16_f32 v10, v50, v51
	v_cvt_pk_bf16_f32 v11, v52, v53
	v_cvt_pk_bf16_f32 v12, v54, v55
	v_cvt_pk_bf16_f32 v13, v56, v57
	s_cbranch_vccz .Lgate_f_m13
	global_store_dwordx4 v225, v[10:13], s[8:9]
	s_add_u32 s8, s8, 0x2000
	s_addc_u32 s9, s9, 0
	s_branch .Lgate_f_j13

; __device__ __forceinline__ unsigned pk2(float lo, float hi) { f32x2_t v = {lo, hi}; bf16x2_t b = __builtin_convertvector(v, bf16x2_t); return __builtin_bit_cast(unsigned, b); }
; __device__ __forceinline__ float sigmoidf_(float x) { return __builtin_amdgcn_rcpf(1.0f + fexp2(-x * LOG2E)); }
;     __device__ __forceinline__ void operator()(AccRef acc, const pg8::Unit& u, int wr, int wc, int fr, int fq) const {
;     ...
;                 for (int m = 0; m < 4; ++m) {
;                     const size_t ci = ub + (size_t)((ai * 2 + bj) * 4 + m) * NTHREADS;
;                     const v4u pw = pw4[m], tw = tw4[m];
;                     const float rs = rst[(row0 + ai * 128 + m * 16) & 255];
;                     float v[8];
;                     v[0] = sigmoidf_(acc[ai][bj][m][0][0] * rs + bv0[0]) * bflo(pw.x); v[1] = sigmoidf_(acc[ai][bj][m][0][1] * rs + bv0[1]) * bfhi(pw.x);
;                     v[2] = sigmoidf_(acc[ai][bj][m][0][2] * rs + bv0[2]) * bflo(pw.y); v[3] = sigmoidf_(acc[ai][bj][m][0][3] * rs + bv0[3]) * bfhi(pw.y);
;                     v[4] = sigmoidf_(acc[ai][bj][m][1][0] * rs + bv1[0]) * bflo(pw.z); v[5] = sigmoidf_(acc[ai][bj][m][1][1] * rs + bv1[1]) * bfhi(pw.z);
;                     v[6] = sigmoidf_(acc[ai][bj][m][1][2] * rs + bv1[2]) * bflo(pw.w); v[7] = sigmoidf_(acc[ai][bj][m][1][3] * rs + bv1[3]) * bfhi(pw.w);
;                     v[0] += bflo(tw.x); v[1] += bfhi(tw.x); v[2] += bflo(tw.y); v[3] += bfhi(tw.y);
;                     v[4] += bflo(tw.z); v[5] += bfhi(tw.z); v[6] += bflo(tw.w); v[7] += bfhi(tw.w);
;                     v4u w; w.x = pk2(v[0], v[1]); w.y = pk2(v[2], v[3]); w.z = pk2(v[4], v[5]); w.w = pk2(v[6], v[7]);
;                     if (!last) TMP[ci] = w;
;                     else *(v4u*)(MRG + (size_t)(row0 + ai * 128 + m * 16) * D + col0 + bj * 128) = w;
.Lgate_f_j13:
	s_waitcnt vmcnt(6)
	v_fma_f32 v50, v86, v230, v202
	v_fma_f32 v51, v87, v230, v203
	v_fma_f32 v52, v88, v230, v204
	v_fma_f32 v53, v89, v230, v205
	v_fma_f32 v54, v82, v230, v206
	v_fma_f32 v55, v83, v230, v207
	v_fma_f32 v56, v84, v230, v208
	v_fma_f32 v57, v85, v230, v209
	v_mul_f32_e32 v50, 0xbfb8aa3b, v50
	v_mul_f32_e32 v51, 0xbfb8aa3b, v51
	v_mul_f32_e32 v52, 0xbfb8aa3b, v52
	v_mul_f32_e32 v53, 0xbfb8aa3b, v53
	v_mul_f32_e32 v54, 0xbfb8aa3b, v54
	v_mul_f32_e32 v55, 0xbfb8aa3b, v55
	v_mul_f32_e32 v56, 0xbfb8aa3b, v56
	v_mul_f32_e32 v57, 0xbfb8aa3b, v57
	v_exp_f32_e32 v50, v50
	v_exp_f32_e32 v51, v51
	v_exp_f32_e32 v52, v52
	v_exp_f32_e32 v53, v53
	v_exp_f32_e32 v54, v54
	v_exp_f32_e32 v55, v55
	v_exp_f32_e32 v56, v56
	v_exp_f32_e32 v57, v57
	v_add_f32_e32 v50, 1.0, v50
	v_add_f32_e32 v51, 1.0, v51
	v_add_f32_e32 v52, 1.0, v52
	v_add_f32_e32 v53, 1.0, v53
	v_add_f32_e32 v54, 1.0, v54
	v_add_f32_e32 v55, 1.0, v55
	v_add_f32_e32 v56, 1.0, v56
	v_add_f32_e32 v57, 1.0, v57
	v_rcp_f32_e32 v50, v50
	v_rcp_f32_e32 v51, v51
	v_rcp_f32_e32 v52, v52
	v_rcp_f32_e32 v53, v53
	v_rcp_f32_e32 v54, v54
	v_rcp_f32_e32 v55, v55
	v_rcp_f32_e32 v56, v56
	v_rcp_f32_e32 v57, v57
	v_lshlrev_b32_e32 v58, 16, v18
	v_and_b32_e32 v59, 0xffff0000, v18
	v_pk_fma_f32 v[50:51], v[50:51], v[58:59], v[62:63]
	v_lshlrev_b32_e32 v58, 16, v19
	v_and_b32_e32 v59, 0xffff0000, v19
	v_pk_fma_f32 v[52:53], v[52:53], v[58:59], v[62:63]
	v_lshlrev_b32_e32 v58, 16, v20
	v_and_b32_e32 v59, 0xffff0000, v20
	v_pk_fma_f32 v[54:55], v[54:55], v[58:59], v[62:63]
	v_lshlrev_b32_e32 v58, 16, v21
	v_and_b32_e32 v59, 0xffff0000, v21
	v_pk_fma_f32 v[56:57], v[56:57], v[58:59], v[62:63]
	v_cvt_pk_bf16_f32 v18, v50, v51
	v_cvt_pk_bf16_f32 v19, v52, v53
	v_cvt_pk_bf16_f32 v20, v54, v55
	v_cvt_pk_bf16_f32 v21, v56, v57
	s_cbranch_vccz .Lgate_f_m14
	global_store_dwordx4 v225, v[18:21], s[8:9]
	s_add_u32 s8, s8, 0x2000
	s_addc_u32 s9, s9, 0
	s_branch .Lgate_f_j14

; __device__ __forceinline__ unsigned pk2(float lo, float hi) { f32x2_t v = {lo, hi}; bf16x2_t b = __builtin_convertvector(v, bf16x2_t); return __builtin_bit_cast(unsigned, b); }
; __device__ __forceinline__ float sigmoidf_(float x) { return __builtin_amdgcn_rcpf(1.0f + fexp2(-x * LOG2E)); }
;     __device__ __forceinline__ void operator()(AccRef acc, const pg8::Unit& u, int wr, int wc, int fr, int fq) const {
;     ...
;                 for (int m = 0; m < 4; ++m) {
;                     const size_t ci = ub + (size_t)((ai * 2 + bj) * 4 + m) * NTHREADS;
;                     const v4u pw = pw4[m], tw = tw4[m];
;                     const float rs = rst[(row0 + ai * 128 + m * 16) & 255];
;                     float v[8];
;                     v[0] = sigmoidf_(acc[ai][bj][m][0][0] * rs + bv0[0]) * bflo(pw.x); v[1] = sigmoidf_(acc[ai][bj][m][0][1] * rs + bv0[1]) * bfhi(pw.x);
;                     v[2] = sigmoidf_(acc[ai][bj][m][0][2] * rs + bv0[2]) * bflo(pw.y); v[3] = sigmoidf_(acc[ai][bj][m][0][3] * rs + bv0[3]) * bfhi(pw.y);
;                     v[4] = sigmoidf_(acc[ai][bj][m][1][0] * rs + bv1[0]) * bflo(pw.z); v[5] = sigmoidf_(acc[ai][bj][m][1][1] * rs + bv1[1]) * bfhi(pw.z);
;                     v[6] = sigmoidf_(acc[ai][bj][m][1][2] * rs + bv1[2]) * bflo(pw.w); v[7] = sigmoidf_(acc[ai][bj][m][1][3] * rs + bv1[3]) * bfhi(pw.w);
;                     v[0] += bflo(tw.x); v[1] += bfhi(tw.x); v[2] += bflo(tw.y); v[3] += bfhi(tw.y);
;                     v[4] += bflo(tw.z); v[5] += bfhi(tw.z); v[6] += bflo(tw.w); v[7] += bfhi(tw.w);
;                     v4u w; w.x = pk2(v[0], v[1]); w.y = pk2(v[2], v[3]); w.z = pk2(v[4], v[5]); w.w = pk2(v[6], v[7]);
;                     if (!last) TMP[ci] = w;
;                     else *(v4u*)(MRG + (size_t)(row0 + ai * 128 + m * 16) * D + col0 + bj * 128) = w;
.Lgate_f_j14:
	s_waitcnt vmcnt(5)
	v_fma_f32 v50, v70, v231, v202
	v_fma_f32 v51, v71, v231, v203
	v_fma_f32 v52, v72, v231, v204
	v_fma_f32 v53, v73, v231, v205
	v_fma_f32 v54, v66, v231, v206
	v_fma_f32 v55, v67, v231, v207
	v_fma_f32 v56, v68, v231, v208
	v_fma_f32 v57, v69, v231, v209
	v_mul_f32_e32 v50, 0xbfb8aa3b, v50
	v_mul_f32_e32 v51, 0xbfb8aa3b, v51
	v_mul_f32_e32 v52, 0xbfb8aa3b, v52
	v_mul_f32_e32 v53, 0xbfb8aa3b, v53
	v_mul_f32_e32 v54, 0xbfb8aa3b, v54
	v_mul_f32_e32 v55, 0xbfb8aa3b, v55
	v_mul_f32_e32 v56, 0xbfb8aa3b, v56
	v_mul_f32_e32 v57, 0xbfb8aa3b, v57
	v_exp_f32_e32 v50, v50
	v_exp_f32_e32 v51, v51
	v_exp_f32_e32 v52, v52
	v_exp_f32_e32 v53, v53
	v_exp_f32_e32 v54, v54
	v_exp_f32_e32 v55, v55
	v_exp_f32_e32 v56, v56
	v_exp_f32_e32 v57, v57
	v_add_f32_e32 v50, 1.0, v50
	v_add_f32_e32 v51, 1.0, v51
	v_add_f32_e32 v52, 1.0, v52
	v_add_f32_e32 v53, 1.0, v53
	v_add_f32_e32 v54, 1.0, v54
	v_add_f32_e32 v55, 1.0, v55
	v_add_f32_e32 v56, 1.0, v56
	v_add_f32_e32 v57, 1.0, v57
	v_rcp_f32_e32 v50, v50
	v_rcp_f32_e32 v51, v51
	v_rcp_f32_e32 v52, v52
	v_rcp_f32_e32 v53, v53
	v_rcp_f32_e32 v54, v54
	v_rcp_f32_e32 v55, v55
	v_rcp_f32_e32 v56, v56
	v_rcp_f32_e32 v57, v57
	v_lshlrev_b32_e32 v58, 16, v26
	v_and_b32_e32 v59, 0xffff0000, v26
	v_pk_fma_f32 v[50:51], v[50:51], v[58:59], v[62:63]
	v_lshlrev_b32_e32 v58, 16, v27
	v_and_b32_e32 v59, 0xffff0000, v27
	v_pk_fma_f32 v[52:53], v[52:53], v[58:59], v[62:63]
	v_lshlrev_b32_e32 v58, 16, v28
	v_and_b32_e32 v59, 0xffff0000, v28
	v_pk_fma_f32 v[54:55], v[54:55], v[58:59], v[62:63]
	v_lshlrev_b32_e32 v58, 16, v29
	v_and_b32_e32 v59, 0xffff0000, v29
	v_pk_fma_f32 v[56:57], v[56:57], v[58:59], v[62:63]
	v_cvt_pk_bf16_f32 v26, v50, v51
	v_cvt_pk_bf16_f32 v27, v52, v53
	v_cvt_pk_bf16_f32 v28, v54, v55
	v_cvt_pk_bf16_f32 v29, v56, v57
	s_cbranch_vccz .Lgate_f_m15
	global_store_dwordx4 v225, v[26:29], s[8:9]
	s_branch .Lgate_f_j15
.Lgate_f_m15:
	global_store_dwordx4 v226, v[26:29], s[8:9]

; __device__ __forceinline__ unsigned pk2(float lo, float hi) { f32x2_t v = {lo, hi}; bf16x2_t b = __builtin_convertvector(v, bf16x2_t); return __builtin_bit_cast(unsigned, b); }
; __device__ __forceinline__ float sigmoidf_(float x) { return __builtin_amdgcn_rcpf(1.0f + fexp2(-x * LOG2E)); }
;     __device__ __forceinline__ void operator()(AccRef acc, const pg8::Unit& u, int wr, int wc, int fr, int fq) const {
;     ...
;                 v4u pw4[4], tw4[4];
; #pragma unroll
;                 for (int m = 0; m < 4; ++m) {
;                     const size_t ci = ub + (size_t)((ai * 2 + bj) * 4 + m) * NTHREADS;
;                     pw4[m] = P[ci];
;                     if (!first) tw4[m] = TMP[ci]; else tw4[m] = (v4u){0u, 0u, 0u, 0u};
;                 }
; #pragma unroll
;                 for (int m = 0; m < 4; ++m) {
;                     const size_t ci = ub + (size_t)((ai * 2 + bj) * 4 + m) * NTHREADS;
;                     const v4u pw = pw4[m], tw = tw4[m];
;                     const float rs = rst[(row0 + ai * 128 + m * 16) & 255];
;                     float v[8];
;                     v[0] = sigmoidf_(acc[ai][bj][m][0][0] * rs + bv0[0]) * bflo(pw.x); v[1] = sigmoidf_(acc[ai][bj][m][0][1] * rs + bv0[1]) * bfhi(pw.x);
;                     v[2] = sigmoidf_(acc[ai][bj][m][0][2] * rs + bv0[2]) * bflo(pw.y); v[3] = sigmoidf_(acc[ai][bj][m][0][3] * rs + bv0[3]) * bfhi(pw.y);
;                     v[4] = sigmoidf_(acc[ai][bj][m][1][0] * rs + bv1[0]) * bflo(pw.z); v[5] = sigmoidf_(acc[ai][bj][m][1][1] * rs + bv1[1]) * bfhi(pw.z);
;                     v[6] = sigmoidf_(acc[ai][bj][m][1][2] * rs + bv1[2]) * bflo(pw.w); v[7] = sigmoidf_(acc[ai][bj][m][1][3] * rs + bv1[3]) * bfhi(pw.w);
;                     v[0] += bflo(tw.x); v[1] += bfhi(tw.x); v[2] += bflo(tw.y); v[3] += bfhi(tw.y);
;                     v[4] += bflo(tw.z); v[5] += bfhi(tw.z); v[6] += bflo(tw.w); v[7] += bfhi(tw.w);
;                     v4u w; w.x = pk2(v[0], v[1]); w.y = pk2(v[2], v[3]); w.z = pk2(v[4], v[5]); w.w = pk2(v[6], v[7]);
;                     if (!last) TMP[ci] = w;
;                     else *(v4u*)(MRG + (size_t)(row0 + ai * 128 + m * 16) * D + col0 + bj * 128) = w;
.Lgate_n:
	global_load_dwordx4 v[2:5], v224, s[6:7]
	global_load_dwordx4 v[6:9], v225, s[6:7]
	s_add_u32 s6, s6, 0x2000
	s_addc_u32 s7, s7, 0
	global_load_dwordx4 v[10:13], v224, s[6:7]
	global_load_dwordx4 v[14:17], v225, s[6:7]
	s_add_u32 s6, s6, 0x2000
	s_addc_u32 s7, s7, 0
	global_load_dwordx4 v[18:21], v224, s[6:7]
	global_load_dwordx4 v[22:25], v225, s[6:7]
	s_add_u32 s6, s6, 0x2000
	s_addc_u32 s7, s7, 0
	global_load_dwordx4 v[26:29], v224, s[6:7]
	global_load_dwordx4 v[30:33], v225, s[6:7]
	s_add_u32 s6, s6, 0x2000
	s_addc_u32 s7, s7, 0
	global_load_dwordx4 v[34:37], v224, s[6:7]
	global_load_dwordx4 v[38:41], v225, s[6:7]
	s_add_u32 s6, s6, 0x2000
	s_addc_u32 s7, s7, 0
	global_load_dwordx4 v[42:45], v224, s[6:7]
	global_load_dwordx4 v[46:49], v225, s[6:7]
	s_add_u32 s6, s6, 0x2000
	s_addc_u32 s7, s7, 0
	ds_read_b32 v210, v227 offset:0
	ds_read_b32 v211, v227 offset:64
	ds_read_b32 v212, v227 offset:128
	ds_read_b32 v213, v227 offset:192
	ds_read_b32 v228, v227 offset:512
	ds_read_b32 v229, v227 offset:576
	ds_read_b32 v230, v227 offset:640
	ds_read_b32 v231, v227 offset:704
	s_waitcnt lgkmcnt(0)
	s_waitcnt vmcnt(10)
	v_fma_f32 v50, v190, v210, v194
	v_fma_f32 v51, v191, v210, v195
	v_fma_f32 v52, v192, v210, v196
	v_fma_f32 v53, v193, v210, v197
	v_fma_f32 v54, v186, v210, v198
	v_fma_f32 v55, v187, v210, v199
	v_fma_f32 v56, v188, v210, v200
	v_fma_f32 v57, v189, v210, v201
	v_mul_f32_e32 v50, 0xbfb8aa3b, v50
	v_mul_f32_e32 v51, 0xbfb8aa3b, v51
	v_mul_f32_e32 v52, 0xbfb8aa3b, v52
	v_mul_f32_e32 v53, 0xbfb8aa3b, v53
	v_mul_f32_e32 v54, 0xbfb8aa3b, v54
	v_mul_f32_e32 v55, 0xbfb8aa3b, v55
	v_mul_f32_e32 v56, 0xbfb8aa3b, v56
	v_mul_f32_e32 v57, 0xbfb8aa3b, v57
	v_exp_f32_e32 v50, v50
	v_exp_f32_e32 v51, v51
	v_exp_f32_e32 v52, v52
	v_exp_f32_e32 v53, v53
	v_exp_f32_e32 v54, v54
	v_exp_f32_e32 v55, v55
	v_exp_f32_e32 v56, v56
	v_exp_f32_e32 v57, v57
	v_add_f32_e32 v50, 1.0, v50
	v_add_f32_e32 v51, 1.0, v51
	v_add_f32_e32 v52, 1.0, v52
	v_add_f32_e32 v53, 1.0, v53
	v_add_f32_e32 v54, 1.0, v54
	v_add_f32_e32 v55, 1.0, v55
	v_add_f32_e32 v56, 1.0, v56
	v_add_f32_e32 v57, 1.0, v57
	v_rcp_f32_e32 v50, v50
	v_rcp_f32_e32 v51, v51
	v_rcp_f32_e32 v52, v52
	v_rcp_f32_e32 v53, v53
	v_rcp_f32_e32 v54, v54
	v_rcp_f32_e32 v55, v55
	v_rcp_f32_e32 v56, v56
	v_rcp_f32_e32 v57, v57
	v_lshlrev_b32_e32 v58, 16, v2
	v_and_b32_e32 v59, 0xffff0000, v2
	v_lshlrev_b32_e32 v60, 16, v6
	v_and_b32_e32 v61, 0xffff0000, v6
	v_pk_fma_f32 v[50:51], v[50:51], v[58:59], v[60:61]
	v_lshlrev_b32_e32 v58, 16, v3
	v_and_b32_e32 v59, 0xffff0000, v3
	v_lshlrev_b32_e32 v60, 16, v7
	v_and_b32_e32 v61, 0xffff0000, v7
	v_pk_fma_f32 v[52:53], v[52:53], v[58:59], v[60:61]
	v_lshlrev_b32_e32 v58, 16, v4
	v_and_b32_e32 v59, 0xffff0000, v4
	v_lshlrev_b32_e32 v60, 16, v8
	v_and_b32_e32 v61, 0xffff0000, v8
	v_pk_fma_f32 v[54:55], v[54:55], v[58:59], v[60:61]
	v_lshlrev_b32_e32 v58, 16, v5
	v_and_b32_e32 v59, 0xffff0000, v5
	v_lshlrev_b32_e32 v60, 16, v9
	v_and_b32_e32 v61, 0xffff0000, v9
	v_pk_fma_f32 v[56:57], v[56:57], v[58:59], v[60:61]
	v_cvt_pk_bf16_f32 v2, v50, v51
	v_cvt_pk_bf16_f32 v3, v52, v53
	v_cvt_pk_bf16_f32 v4, v54, v55
	v_cvt_pk_bf16_f32 v5, v56, v57
	s_cbranch_vccz .Lgate_n_m0
	global_store_dwordx4 v225, v[2:5], s[8:9]
	s_add_u32 s8, s8, 0x2000
	s_addc_u32 s9, s9, 0
	s_branch .Lgate_n_j0

; __device__ __forceinline__ unsigned pk2(float lo, float hi) { f32x2_t v = {lo, hi}; bf16x2_t b = __builtin_convertvector(v, bf16x2_t); return __builtin_bit_cast(unsigned, b); }
; __device__ __forceinline__ float sigmoidf_(float x) { return __builtin_amdgcn_rcpf(1.0f + fexp2(-x * LOG2E)); }
;     __device__ __forceinline__ void operator()(AccRef acc, const pg8::Unit& u, int wr, int wc, int fr, int fq) const {
;     ...
;                 v4u pw4[4], tw4[4];
; #pragma unroll
;                 for (int m = 0; m < 4; ++m) {
;                     const size_t ci = ub + (size_t)((ai * 2 + bj) * 4 + m) * NTHREADS;
;                     pw4[m] = P[ci];
;                     if (!first) tw4[m] = TMP[ci]; else tw4[m] = (v4u){0u, 0u, 0u, 0u};
;                 }
; #pragma unroll
;                 for (int m = 0; m < 4; ++m) {
;                     const size_t ci = ub + (size_t)((ai * 2 + bj) * 4 + m) * NTHREADS;
;                     const v4u pw = pw4[m], tw = tw4[m];
;                     const float rs = rst[(row0 + ai * 128 + m * 16) & 255];
;                     float v[8];
;                     v[0] = sigmoidf_(acc[ai][bj][m][0][0] * rs + bv0[0]) * bflo(pw.x); v[1] = sigmoidf_(acc[ai][bj][m][0][1] * rs + bv0[1]) * bfhi(pw.x);
;                     v[2] = sigmoidf_(acc[ai][bj][m][0][2] * rs + bv0[2]) * bflo(pw.y); v[3] = sigmoidf_(acc[ai][bj][m][0][3] * rs + bv0[3]) * bfhi(pw.y);
;                     v[4] = sigmoidf_(acc[ai][bj][m][1][0] * rs + bv1[0]) * bflo(pw.z); v[5] = sigmoidf_(acc[ai][bj][m][1][1] * rs + bv1[1]) * bfhi(pw.z);
;                     v[6] = sigmoidf_(acc[ai][bj][m][1][2] * rs + bv1[2]) * bflo(pw.w); v[7] = sigmoidf_(acc[ai][bj][m][1][3] * rs + bv1[3]) * bfhi(pw.w);
;                     v[0] += bflo(tw.x); v[1] += bfhi(tw.x); v[2] += bflo(tw.y); v[3] += bfhi(tw.y);
;                     v[4] += bflo(tw.z); v[5] += bfhi(tw.z); v[6] += bflo(tw.w); v[7] += bfhi(tw.w);
;                     v4u w; w.x = pk2(v[0], v[1]); w.y = pk2(v[2], v[3]); w.z = pk2(v[4], v[5]); w.w = pk2(v[6], v[7]);
;                     if (!last) TMP[ci] = w;
;                     else *(v4u*)(MRG + (size_t)(row0 + ai * 128 + m * 16) * D + col0 + bj * 128) = w;
.Lgate_n_j0:
	global_load_dwordx4 v[2:5], v224, s[6:7]
	global_load_dwordx4 v[6:9], v225, s[6:7]
	s_add_u32 s6, s6, 0x2000
	s_addc_u32 s7, s7, 0
	s_waitcnt vmcnt(11)
	v_fma_f32 v50, v174, v211, v194
	v_fma_f32 v51, v175, v211, v195
	v_fma_f32 v52, v176, v211, v196
	v_fma_f32 v53, v177, v211, v197
	v_fma_f32 v54, v170, v211, v198
	v_fma_f32 v55, v171, v211, v199
	v_fma_f32 v56, v172, v211, v200
	v_fma_f32 v57, v173, v211, v201
	v_mul_f32_e32 v50, 0xbfb8aa3b, v50
	v_mul_f32_e32 v51, 0xbfb8aa3b, v51
	v_mul_f32_e32 v52, 0xbfb8aa3b, v52
	v_mul_f32_e32 v53, 0xbfb8aa3b, v53
	v_mul_f32_e32 v54, 0xbfb8aa3b, v54
	v_mul_f32_e32 v55, 0xbfb8aa3b, v55
	v_mul_f32_e32 v56, 0xbfb8aa3b, v56
	v_mul_f32_e32 v57, 0xbfb8aa3b, v57
	v_exp_f32_e32 v50, v50
	v_exp_f32_e32 v51, v51
	v_exp_f32_e32 v52, v52
	v_exp_f32_e32 v53, v53
	v_exp_f32_e32 v54, v54
	v_exp_f32_e32 v55, v55
	v_exp_f32_e32 v56, v56
	v_exp_f32_e32 v57, v57
	v_add_f32_e32 v50, 1.0, v50
	v_add_f32_e32 v51, 1.0, v51
	v_add_f32_e32 v52, 1.0, v52
	v_add_f32_e32 v53, 1.0, v53
	v_add_f32_e32 v54, 1.0, v54
	v_add_f32_e32 v55, 1.0, v55
	v_add_f32_e32 v56, 1.0, v56
	v_add_f32_e32 v57, 1.0, v57
	v_rcp_f32_e32 v50, v50
	v_rcp_f32_e32 v51, v51
	v_rcp_f32_e32 v52, v52
	v_rcp_f32_e32 v53, v53
	v_rcp_f32_e32 v54, v54
	v_rcp_f32_e32 v55, v55
	v_rcp_f32_e32 v56, v56
	v_rcp_f32_e32 v57, v57
	v_lshlrev_b32_e32 v58, 16, v10
	v_and_b32_e32 v59, 0xffff0000, v10
	v_lshlrev_b32_e32 v60, 16, v14
	v_and_b32_e32 v61, 0xffff0000, v14
	v_pk_fma_f32 v[50:51], v[50:51], v[58:59], v[60:61]
	v_lshlrev_b32_e32 v58, 16, v11
	v_and_b32_e32 v59, 0xffff0000, v11
	v_lshlrev_b32_e32 v60, 16, v15
	v_and_b32_e32 v61, 0xffff0000, v15
	v_pk_fma_f32 v[52:53], v[52:53], v[58:59], v[60:61]
	v_lshlrev_b32_e32 v58, 16, v12
	v_and_b32_e32 v59, 0xffff0000, v12
	v_lshlrev_b32_e32 v60, 16, v16
	v_and_b32_e32 v61, 0xffff0000, v16
	v_pk_fma_f32 v[54:55], v[54:55], v[58:59], v[60:61]
	v_lshlrev_b32_e32 v58, 16, v13
	v_and_b32_e32 v59, 0xffff0000, v13
	v_lshlrev_b32_e32 v60, 16, v17
	v_and_b32_e32 v61, 0xffff0000, v17
	v_pk_fma_f32 v[56:57], v[56:57], v[58:59], v[60:61]
	v_cvt_pk_bf16_f32 v10, v50, v51
	v_cvt_pk_bf16_f32 v11, v52, v53
	v_cvt_pk_bf16_f32 v12, v54, v55
	v_cvt_pk_bf16_f32 v13, v56, v57
	s_cbranch_vccz .Lgate_n_m1
	global_store_dwordx4 v225, v[10:13], s[8:9]
	s_add_u32 s8, s8, 0x2000
	s_addc_u32 s9, s9, 0
	s_branch .Lgate_n_j1

; __device__ __forceinline__ unsigned pk2(float lo, float hi) { f32x2_t v = {lo, hi}; bf16x2_t b = __builtin_convertvector(v, bf16x2_t); return __builtin_bit_cast(unsigned, b); }
; __device__ __forceinline__ float sigmoidf_(float x) { return __builtin_amdgcn_rcpf(1.0f + fexp2(-x * LOG2E)); }
;     __device__ __forceinline__ void operator()(AccRef acc, const pg8::Unit& u, int wr, int wc, int fr, int fq) const {
;     ...
;                 v4u pw4[4], tw4[4];
; #pragma unroll
;                 for (int m = 0; m < 4; ++m) {
;                     const size_t ci = ub + (size_t)((ai * 2 + bj) * 4 + m) * NTHREADS;
;                     pw4[m] = P[ci];
;                     if (!first) tw4[m] = TMP[ci]; else tw4[m] = (v4u){0u, 0u, 0u, 0u};
;                 }
; #pragma unroll
;                 for (int m = 0; m < 4; ++m) {
;                     const size_t ci = ub + (size_t)((ai * 2 + bj) * 4 + m) * NTHREADS;
;                     const v4u pw = pw4[m], tw = tw4[m];
;                     const float rs = rst[(row0 + ai * 128 + m * 16) & 255];
;                     float v[8];
;                     v[0] = sigmoidf_(acc[ai][bj][m][0][0] * rs + bv0[0]) * bflo(pw.x); v[1] = sigmoidf_(acc[ai][bj][m][0][1] * rs + bv0[1]) * bfhi(pw.x);
;                     v[2] = sigmoidf_(acc[ai][bj][m][0][2] * rs + bv0[2]) * bflo(pw.y); v[3] = sigmoidf_(acc[ai][bj][m][0][3] * rs + bv0[3]) * bfhi(pw.y);
;                     v[4] = sigmoidf_(acc[ai][bj][m][1][0] * rs + bv1[0]) * bflo(pw.z); v[5] = sigmoidf_(acc[ai][bj][m][1][1] * rs + bv1[1]) * bfhi(pw.z);
;                     v[6] = sigmoidf_(acc[ai][bj][m][1][2] * rs + bv1[2]) * bflo(pw.w); v[7] = sigmoidf_(acc[ai][bj][m][1][3] * rs + bv1[3]) * bfhi(pw.w);
;                     v[0] += bflo(tw.x); v[1] += bfhi(tw.x); v[2] += bflo(tw.y); v[3] += bfhi(tw.y);
;                     v[4] += bflo(tw.z); v[5] += bfhi(tw.z); v[6] += bflo(tw.w); v[7] += bfhi(tw.w);
;                     v4u w; w.x = pk2(v[0], v[1]); w.y = pk2(v[2], v[3]); w.z = pk2(v[4], v[5]); w.w = pk2(v[6], v[7]);
;                     if (!last) TMP[ci] = w;
;                     else *(v4u*)(MRG + (size_t)(row0 + ai * 128 + m * 16) * D + col0 + bj * 128) = w;
.Lgate_n_j1:
	global_load_dwordx4 v[10:13], v224, s[6:7]
	global_load_dwordx4 v[14:17], v225, s[6:7]
	s_add_u32 s6, s6, 0x2000
	s_addc_u32 s7, s7, 0
	s_waitcnt vmcnt(12)
	v_fma_f32 v50, v158, v212, v194
	v_fma_f32 v51, v159, v212, v195
	v_fma_f32 v52, v160, v212, v196
	v_fma_f32 v53, v161, v212, v197
	v_fma_f32 v54, v154, v212, v198
	v_fma_f32 v55, v155, v212, v199
	v_fma_f32 v56, v156, v212, v200
	v_fma_f32 v57, v157, v212, v201
	v_mul_f32_e32 v50, 0xbfb8aa3b, v50
	v_mul_f32_e32 v51, 0xbfb8aa3b, v51
	v_mul_f32_e32 v52, 0xbfb8aa3b, v52
	v_mul_f32_e32 v53, 0xbfb8aa3b, v53
	v_mul_f32_e32 v54, 0xbfb8aa3b, v54
	v_mul_f32_e32 v55, 0xbfb8aa3b, v55
	v_mul_f32_e32 v56, 0xbfb8aa3b, v56
	v_mul_f32_e32 v57, 0xbfb8aa3b, v57
	v_exp_f32_e32 v50, v50
	v_exp_f32_e32 v51, v51
	v_exp_f32_e32 v52, v52
	v_exp_f32_e32 v53, v53
	v_exp_f32_e32 v54, v54
	v_exp_f32_e32 v55, v55
	v_exp_f32_e32 v56, v56
	v_exp_f32_e32 v57, v57
	v_add_f32_e32 v50, 1.0, v50
	v_add_f32_e32 v51, 1.0, v51
	v_add_f32_e32 v52, 1.0, v52
	v_add_f32_e32 v53, 1.0, v53
	v_add_f32_e32 v54, 1.0, v54
	v_add_f32_e32 v55, 1.0, v55
	v_add_f32_e32 v56, 1.0, v56
	v_add_f32_e32 v57, 1.0, v57
	v_rcp_f32_e32 v50, v50
	v_rcp_f32_e32 v51, v51
	v_rcp_f32_e32 v52, v52
	v_rcp_f32_e32 v53, v53
	v_rcp_f32_e32 v54, v54
	v_rcp_f32_e32 v55, v55
	v_rcp_f32_e32 v56, v56
	v_rcp_f32_e32 v57, v57
	v_lshlrev_b32_e32 v58, 16, v18
	v_and_b32_e32 v59, 0xffff0000, v18
	v_lshlrev_b32_e32 v60, 16, v22
	v_and_b32_e32 v61, 0xffff0000, v22
	v_pk_fma_f32 v[50:51], v[50:51], v[58:59], v[60:61]
	v_lshlrev_b32_e32 v58, 16, v19
	v_and_b32_e32 v59, 0xffff0000, v19
	v_lshlrev_b32_e32 v60, 16, v23
	v_and_b32_e32 v61, 0xffff0000, v23
	v_pk_fma_f32 v[52:53], v[52:53], v[58:59], v[60:61]
	v_lshlrev_b32_e32 v58, 16, v20
	v_and_b32_e32 v59, 0xffff0000, v20
	v_lshlrev_b32_e32 v60, 16, v24
	v_and_b32_e32 v61, 0xffff0000, v24
	v_pk_fma_f32 v[54:55], v[54:55], v[58:59], v[60:61]
	v_lshlrev_b32_e32 v58, 16, v21
	v_and_b32_e32 v59, 0xffff0000, v21
	v_lshlrev_b32_e32 v60, 16, v25
	v_and_b32_e32 v61, 0xffff0000, v25
	v_pk_fma_f32 v[56:57], v[56:57], v[58:59], v[60:61]
	v_cvt_pk_bf16_f32 v18, v50, v51
	v_cvt_pk_bf16_f32 v19, v52, v53
	v_cvt_pk_bf16_f32 v20, v54, v55
	v_cvt_pk_bf16_f32 v21, v56, v57
	s_cbranch_vccz .Lgate_n_m2
	global_store_dwordx4 v225, v[18:21], s[8:9]
	s_add_u32 s8, s8, 0x2000
	s_addc_u32 s9, s9, 0
	s_branch .Lgate_n_j2

; __device__ __forceinline__ unsigned pk2(float lo, float hi) { f32x2_t v = {lo, hi}; bf16x2_t b = __builtin_convertvector(v, bf16x2_t); return __builtin_bit_cast(unsigned, b); }
; __device__ __forceinline__ float sigmoidf_(float x) { return __builtin_amdgcn_rcpf(1.0f + fexp2(-x * LOG2E)); }
;     __device__ __forceinline__ void operator()(AccRef acc, const pg8::Unit& u, int wr, int wc, int fr, int fq) const {
;     ...
;                 v4u pw4[4], tw4[4];
; #pragma unroll
;                 for (int m = 0; m < 4; ++m) {
;                     const size_t ci = ub + (size_t)((ai * 2 + bj) * 4 + m) * NTHREADS;
;                     pw4[m] = P[ci];
;                     if (!first) tw4[m] = TMP[ci]; else tw4[m] = (v4u){0u, 0u, 0u, 0u};
;                 }
; #pragma unroll
;                 for (int m = 0; m < 4; ++m) {
;                     const size_t ci = ub + (size_t)((ai * 2 + bj) * 4 + m) * NTHREADS;
;                     const v4u pw = pw4[m], tw = tw4[m];
;                     const float rs = rst[(row0 + ai * 128 + m * 16) & 255];
;                     float v[8];
;                     v[0] = sigmoidf_(acc[ai][bj][m][0][0] * rs + bv0[0]) * bflo(pw.x); v[1] = sigmoidf_(acc[ai][bj][m][0][1] * rs + bv0[1]) * bfhi(pw.x);
;                     v[2] = sigmoidf_(acc[ai][bj][m][0][2] * rs + bv0[2]) * bflo(pw.y); v[3] = sigmoidf_(acc[ai][bj][m][0][3] * rs + bv0[3]) * bfhi(pw.y);
;                     v[4] = sigmoidf_(acc[ai][bj][m][1][0] * rs + bv1[0]) * bflo(pw.z); v[5] = sigmoidf_(acc[ai][bj][m][1][1] * rs + bv1[1]) * bfhi(pw.z);
;                     v[6] = sigmoidf_(acc[ai][bj][m][1][2] * rs + bv1[2]) * bflo(pw.w); v[7] = sigmoidf_(acc[ai][bj][m][1][3] * rs + bv1[3]) * bfhi(pw.w);
;                     v[0] += bflo(tw.x); v[1] += bfhi(tw.x); v[2] += bflo(tw.y); v[3] += bfhi(tw.y);
;                     v[4] += bflo(tw.z); v[5] += bfhi(tw.z); v[6] += bflo(tw.w); v[7] += bfhi(tw.w);
;                     v4u w; w.x = pk2(v[0], v[1]); w.y = pk2(v[2], v[3]); w.z = pk2(v[4], v[5]); w.w = pk2(v[6], v[7]);
;                     if (!last) TMP[ci] = w;
;                     else *(v4u*)(MRG + (size_t)(row0 + ai * 128 + m * 16) * D + col0 + bj * 128) = w;
.Lgate_n_j2:
	global_load_dwordx4 v[18:21], v224, s[6:7]
	global_load_dwordx4 v[22:25], v225, s[6:7]
	s_add_u32 s6, s6, 0x2000
	s_addc_u32 s7, s7, 0
	s_waitcnt vmcnt(13)
	v_fma_f32 v50, v142, v213, v194
	v_fma_f32 v51, v143, v213, v195
	v_fma_f32 v52, v144, v213, v196
	v_fma_f32 v53, v145, v213, v197
	v_fma_f32 v54, v138, v213, v198
	v_fma_f32 v55, v139, v213, v199
	v_fma_f32 v56, v140, v213, v200
	v_fma_f32 v57, v141, v213, v201
	v_mul_f32_e32 v50, 0xbfb8aa3b, v50
	v_mul_f32_e32 v51, 0xbfb8aa3b, v51
	v_mul_f32_e32 v52, 0xbfb8aa3b, v52
	v_mul_f32_e32 v53, 0xbfb8aa3b, v53
	v_mul_f32_e32 v54, 0xbfb8aa3b, v54
	v_mul_f32_e32 v55, 0xbfb8aa3b, v55
	v_mul_f32_e32 v56, 0xbfb8aa3b, v56
	v_mul_f32_e32 v57, 0xbfb8aa3b, v57
	v_exp_f32_e32 v50, v50
	v_exp_f32_e32 v51, v51
	v_exp_f32_e32 v52, v52
	v_exp_f32_e32 v53, v53
	v_exp_f32_e32 v54, v54
	v_exp_f32_e32 v55, v55
	v_exp_f32_e32 v56, v56
	v_exp_f32_e32 v57, v57
	v_add_f32_e32 v50, 1.0, v50
	v_add_f32_e32 v51, 1.0, v51
	v_add_f32_e32 v52, 1.0, v52
	v_add_f32_e32 v53, 1.0, v53
	v_add_f32_e32 v54, 1.0, v54
	v_add_f32_e32 v55, 1.0, v55
	v_add_f32_e32 v56, 1.0, v56
	v_add_f32_e32 v57, 1.0, v57
	v_rcp_f32_e32 v50, v50
	v_rcp_f32_e32 v51, v51
	v_rcp_f32_e32 v52, v52
	v_rcp_f32_e32 v53, v53
	v_rcp_f32_e32 v54, v54
	v_rcp_f32_e32 v55, v55
	v_rcp_f32_e32 v56, v56
	v_rcp_f32_e32 v57, v57
	v_lshlrev_b32_e32 v58, 16, v26
	v_and_b32_e32 v59, 0xffff0000, v26
	v_lshlrev_b32_e32 v60, 16, v30
	v_and_b32_e32 v61, 0xffff0000, v30
	v_pk_fma_f32 v[50:51], v[50:51], v[58:59], v[60:61]
	v_lshlrev_b32_e32 v58, 16, v27
	v_and_b32_e32 v59, 0xffff0000, v27
	v_lshlrev_b32_e32 v60, 16, v31
	v_and_b32_e32 v61, 0xffff0000, v31
	v_pk_fma_f32 v[52:53], v[52:53], v[58:59], v[60:61]
	v_lshlrev_b32_e32 v58, 16, v28
	v_and_b32_e32 v59, 0xffff0000, v28
	v_lshlrev_b32_e32 v60, 16, v32
	v_and_b32_e32 v61, 0xffff0000, v32
	v_pk_fma_f32 v[54:55], v[54:55], v[58:59], v[60:61]
	v_lshlrev_b32_e32 v58, 16, v29
	v_and_b32_e32 v59, 0xffff0000, v29
	v_lshlrev_b32_e32 v60, 16, v33
	v_and_b32_e32 v61, 0xffff0000, v33
	v_pk_fma_f32 v[56:57], v[56:57], v[58:59], v[60:61]
	v_cvt_pk_bf16_f32 v26, v50, v51
	v_cvt_pk_bf16_f32 v27, v52, v53
	v_cvt_pk_bf16_f32 v28, v54, v55
	v_cvt_pk_bf16_f32 v29, v56, v57
	s_cbranch_vccz .Lgate_n_m3
	global_store_dwordx4 v225, v[26:29], s[8:9]
	s_add_u32 s8, s8, 0x2000
	s_addc_u32 s9, s9, 0
	s_branch .Lgate_n_j3

; __device__ __forceinline__ unsigned pk2(float lo, float hi) { f32x2_t v = {lo, hi}; bf16x2_t b = __builtin_convertvector(v, bf16x2_t); return __builtin_bit_cast(unsigned, b); }
; __device__ __forceinline__ float sigmoidf_(float x) { return __builtin_amdgcn_rcpf(1.0f + fexp2(-x * LOG2E)); }
;     __device__ __forceinline__ void operator()(AccRef acc, const pg8::Unit& u, int wr, int wc, int fr, int fq) const {
;     ...
;                 v4u pw4[4], tw4[4];
; #pragma unroll
;                 for (int m = 0; m < 4; ++m) {
;                     const size_t ci = ub + (size_t)((ai * 2 + bj) * 4 + m) * NTHREADS;
;                     pw4[m] = P[ci];
;                     if (!first) tw4[m] = TMP[ci]; else tw4[m] = (v4u){0u, 0u, 0u, 0u};
;                 }
; #pragma unroll
;                 for (int m = 0; m < 4; ++m) {
;                     const size_t ci = ub + (size_t)((ai * 2 + bj) * 4 + m) * NTHREADS;
;                     const v4u pw = pw4[m], tw = tw4[m];
;                     const float rs = rst[(row0 + ai * 128 + m * 16) & 255];
;                     float v[8];
;                     v[0] = sigmoidf_(acc[ai][bj][m][0][0] * rs + bv0[0]) * bflo(pw.x); v[1] = sigmoidf_(acc[ai][bj][m][0][1] * rs + bv0[1]) * bfhi(pw.x);
;                     v[2] = sigmoidf_(acc[ai][bj][m][0][2] * rs + bv0[2]) * bflo(pw.y); v[3] = sigmoidf_(acc[ai][bj][m][0][3] * rs + bv0[3]) * bfhi(pw.y);
;                     v[4] = sigmoidf_(acc[ai][bj][m][1][0] * rs + bv1[0]) * bflo(pw.z); v[5] = sigmoidf_(acc[ai][bj][m][1][1] * rs + bv1[1]) * bfhi(pw.z);
;                     v[6] = sigmoidf_(acc[ai][bj][m][1][2] * rs + bv1[2]) * bflo(pw.w); v[7] = sigmoidf_(acc[ai][bj][m][1][3] * rs + bv1[3]) * bfhi(pw.w);
;                     v[0] += bflo(tw.x); v[1] += bfhi(tw.x); v[2] += bflo(tw.y); v[3] += bfhi(tw.y);
;                     v[4] += bflo(tw.z); v[5] += bfhi(tw.z); v[6] += bflo(tw.w); v[7] += bfhi(tw.w);
;                     v4u w; w.x = pk2(v[0], v[1]); w.y = pk2(v[2], v[3]); w.z = pk2(v[4], v[5]); w.w = pk2(v[6], v[7]);
;                     if (!last) TMP[ci] = w;
;                     else *(v4u*)(MRG + (size_t)(row0 + ai * 128 + m * 16) * D + col0 + bj * 128) = w;
.Lgate_n_j3:
	global_load_dwordx4 v[26:29], v224, s[6:7]
	global_load_dwordx4 v[30:33], v225, s[6:7]
	s_add_u32 s6, s6, 0x2000
	s_addc_u32 s7, s7, 0
	s_waitcnt vmcnt(14)
	v_fma_f32 v50, v182, v210, v202
	v_fma_f32 v51, v183, v210, v203
	v_fma_f32 v52, v184, v210, v204
	v_fma_f32 v53, v185, v210, v205
	v_fma_f32 v54, v178, v210, v206
	v_fma_f32 v55, v179, v210, v207
	v_fma_f32 v56, v180, v210, v208
	v_fma_f32 v57, v181, v210, v209
	v_mul_f32_e32 v50, 0xbfb8aa3b, v50
	v_mul_f32_e32 v51, 0xbfb8aa3b, v51
	v_mul_f32_e32 v52, 0xbfb8aa3b, v52
	v_mul_f32_e32 v53, 0xbfb8aa3b, v53
	v_mul_f32_e32 v54, 0xbfb8aa3b, v54
	v_mul_f32_e32 v55, 0xbfb8aa3b, v55
	v_mul_f32_e32 v56, 0xbfb8aa3b, v56
	v_mul_f32_e32 v57, 0xbfb8aa3b, v57
	v_exp_f32_e32 v50, v50
	v_exp_f32_e32 v51, v51
	v_exp_f32_e32 v52, v52
	v_exp_f32_e32 v53, v53
	v_exp_f32_e32 v54, v54
	v_exp_f32_e32 v55, v55
	v_exp_f32_e32 v56, v56
	v_exp_f32_e32 v57, v57
	v_add_f32_e32 v50, 1.0, v50
	v_add_f32_e32 v51, 1.0, v51
	v_add_f32_e32 v52, 1.0, v52
	v_add_f32_e32 v53, 1.0, v53
	v_add_f32_e32 v54, 1.0, v54
	v_add_f32_e32 v55, 1.0, v55
	v_add_f32_e32 v56, 1.0, v56
	v_add_f32_e32 v57, 1.0, v57
	v_rcp_f32_e32 v50, v50
	v_rcp_f32_e32 v51, v51
	v_rcp_f32_e32 v52, v52
	v_rcp_f32_e32 v53, v53
	v_rcp_f32_e32 v54, v54
	v_rcp_f32_e32 v55, v55
	v_rcp_f32_e32 v56, v56
	v_rcp_f32_e32 v57, v57
	v_lshlrev_b32_e32 v58, 16, v34
	v_and_b32_e32 v59, 0xffff0000, v34
	v_lshlrev_b32_e32 v60, 16, v38
	v_and_b32_e32 v61, 0xffff0000, v38
	v_pk_fma_f32 v[50:51], v[50:51], v[58:59], v[60:61]
	v_lshlrev_b32_e32 v58, 16, v35
	v_and_b32_e32 v59, 0xffff0000, v35
	v_lshlrev_b32_e32 v60, 16, v39
	v_and_b32_e32 v61, 0xffff0000, v39
	v_pk_fma_f32 v[52:53], v[52:53], v[58:59], v[60:61]
	v_lshlrev_b32_e32 v58, 16, v36
	v_and_b32_e32 v59, 0xffff0000, v36
	v_lshlrev_b32_e32 v60, 16, v40
	v_and_b32_e32 v61, 0xffff0000, v40
	v_pk_fma_f32 v[54:55], v[54:55], v[58:59], v[60:61]
	v_lshlrev_b32_e32 v58, 16, v37
	v_and_b32_e32 v59, 0xffff0000, v37
	v_lshlrev_b32_e32 v60, 16, v41
	v_and_b32_e32 v61, 0xffff0000, v41
	v_pk_fma_f32 v[56:57], v[56:57], v[58:59], v[60:61]
	v_cvt_pk_bf16_f32 v34, v50, v51
	v_cvt_pk_bf16_f32 v35, v52, v53
	v_cvt_pk_bf16_f32 v36, v54, v55
	v_cvt_pk_bf16_f32 v37, v56, v57
	s_cbranch_vccz .Lgate_n_m4
	global_store_dwordx4 v225, v[34:37], s[8:9]
	s_add_u32 s8, s8, 0x2000
	s_addc_u32 s9, s9, 0
	s_branch .Lgate_n_j4

; __device__ __forceinline__ unsigned pk2(float lo, float hi) { f32x2_t v = {lo, hi}; bf16x2_t b = __builtin_convertvector(v, bf16x2_t); return __builtin_bit_cast(unsigned, b); }
; __device__ __forceinline__ float sigmoidf_(float x) { return __builtin_amdgcn_rcpf(1.0f + fexp2(-x * LOG2E)); }
;     __device__ __forceinline__ void operator()(AccRef acc, const pg8::Unit& u, int wr, int wc, int fr, int fq) const {
;     ...
;                 v4u pw4[4], tw4[4];
; #pragma unroll
;                 for (int m = 0; m < 4; ++m) {
;                     const size_t ci = ub + (size_t)((ai * 2 + bj) * 4 + m) * NTHREADS;
;                     pw4[m] = P[ci];
;                     if (!first) tw4[m] = TMP[ci]; else tw4[m] = (v4u){0u, 0u, 0u, 0u};
;                 }
; #pragma unroll
;                 for (int m = 0; m < 4; ++m) {
;                     const size_t ci = ub + (size_t)((ai * 2 + bj) * 4 + m) * NTHREADS;
;                     const v4u pw = pw4[m], tw = tw4[m];
;                     const float rs = rst[(row0 + ai * 128 + m * 16) & 255];
;                     float v[8];
;                     v[0] = sigmoidf_(acc[ai][bj][m][0][0] * rs + bv0[0]) * bflo(pw.x); v[1] = sigmoidf_(acc[ai][bj][m][0][1] * rs + bv0[1]) * bfhi(pw.x);
;                     v[2] = sigmoidf_(acc[ai][bj][m][0][2] * rs + bv0[2]) * bflo(pw.y); v[3] = sigmoidf_(acc[ai][bj][m][0][3] * rs + bv0[3]) * bfhi(pw.y);
;                     v[4] = sigmoidf_(acc[ai][bj][m][1][0] * rs + bv1[0]) * bflo(pw.z); v[5] = sigmoidf_(acc[ai][bj][m][1][1] * rs + bv1[1]) * bfhi(pw.z);
;                     v[6] = sigmoidf_(acc[ai][bj][m][1][2] * rs + bv1[2]) * bflo(pw.w); v[7] = sigmoidf_(acc[ai][bj][m][1][3] * rs + bv1[3]) * bfhi(pw.w);
;                     v[0] += bflo(tw.x); v[1] += bfhi(tw.x); v[2] += bflo(tw.y); v[3] += bfhi(tw.y);
;                     v[4] += bflo(tw.z); v[5] += bfhi(tw.z); v[6] += bflo(tw.w); v[7] += bfhi(tw.w);
;                     v4u w; w.x = pk2(v[0], v[1]); w.y = pk2(v[2], v[3]); w.z = pk2(v[4], v[5]); w.w = pk2(v[6], v[7]);
;                     if (!last) TMP[ci] = w;
;                     else *(v4u*)(MRG + (size_t)(row0 + ai * 128 + m * 16) * D + col0 + bj * 128) = w;
.Lgate_n_j4:
	global_load_dwordx4 v[34:37], v224, s[6:7]
	global_load_dwordx4 v[38:41], v225, s[6:7]
	s_add_u32 s6, s6, 0x2000
	s_addc_u32 s7, s7, 0
	s_waitcnt vmcnt(15)
	v_fma_f32 v50, v166, v211, v202
	v_fma_f32 v51, v167, v211, v203
	v_fma_f32 v52, v168, v211, v204
	v_fma_f32 v53, v169, v211, v205
	v_fma_f32 v54, v162, v211, v206
	v_fma_f32 v55, v163, v211, v207
	v_fma_f32 v56, v164, v211, v208
	v_fma_f32 v57, v165, v211, v209
	v_mul_f32_e32 v50, 0xbfb8aa3b, v50
	v_mul_f32_e32 v51, 0xbfb8aa3b, v51
	v_mul_f32_e32 v52, 0xbfb8aa3b, v52
	v_mul_f32_e32 v53, 0xbfb8aa3b, v53
	v_mul_f32_e32 v54, 0xbfb8aa3b, v54
	v_mul_f32_e32 v55, 0xbfb8aa3b, v55
	v_mul_f32_e32 v56, 0xbfb8aa3b, v56
	v_mul_f32_e32 v57, 0xbfb8aa3b, v57
	v_exp_f32_e32 v50, v50
	v_exp_f32_e32 v51, v51
	v_exp_f32_e32 v52, v52
	v_exp_f32_e32 v53, v53
	v_exp_f32_e32 v54, v54
	v_exp_f32_e32 v55, v55
	v_exp_f32_e32 v56, v56
	v_exp_f32_e32 v57, v57
	v_add_f32_e32 v50, 1.0, v50
	v_add_f32_e32 v51, 1.0, v51
	v_add_f32_e32 v52, 1.0, v52
	v_add_f32_e32 v53, 1.0, v53
	v_add_f32_e32 v54, 1.0, v54
	v_add_f32_e32 v55, 1.0, v55
	v_add_f32_e32 v56, 1.0, v56
	v_add_f32_e32 v57, 1.0, v57
	v_rcp_f32_e32 v50, v50
	v_rcp_f32_e32 v51, v51
	v_rcp_f32_e32 v52, v52
	v_rcp_f32_e32 v53, v53
	v_rcp_f32_e32 v54, v54
	v_rcp_f32_e32 v55, v55
	v_rcp_f32_e32 v56, v56
	v_rcp_f32_e32 v57, v57
	v_lshlrev_b32_e32 v58, 16, v42
	v_and_b32_e32 v59, 0xffff0000, v42
	v_lshlrev_b32_e32 v60, 16, v46
	v_and_b32_e32 v61, 0xffff0000, v46
	v_pk_fma_f32 v[50:51], v[50:51], v[58:59], v[60:61]
	v_lshlrev_b32_e32 v58, 16, v43
	v_and_b32_e32 v59, 0xffff0000, v43
	v_lshlrev_b32_e32 v60, 16, v47
	v_and_b32_e32 v61, 0xffff0000, v47
	v_pk_fma_f32 v[52:53], v[52:53], v[58:59], v[60:61]
	v_lshlrev_b32_e32 v58, 16, v44
	v_and_b32_e32 v59, 0xffff0000, v44
	v_lshlrev_b32_e32 v60, 16, v48
	v_and_b32_e32 v61, 0xffff0000, v48
	v_pk_fma_f32 v[54:55], v[54:55], v[58:59], v[60:61]
	v_lshlrev_b32_e32 v58, 16, v45
	v_and_b32_e32 v59, 0xffff0000, v45
	v_lshlrev_b32_e32 v60, 16, v49
	v_and_b32_e32 v61, 0xffff0000, v49
	v_pk_fma_f32 v[56:57], v[56:57], v[58:59], v[60:61]
	v_cvt_pk_bf16_f32 v42, v50, v51
	v_cvt_pk_bf16_f32 v43, v52, v53
	v_cvt_pk_bf16_f32 v44, v54, v55
	v_cvt_pk_bf16_f32 v45, v56, v57
	s_cbranch_vccz .Lgate_n_m5
	global_store_dwordx4 v225, v[42:45], s[8:9]
	s_add_u32 s8, s8, 0x2000
	s_addc_u32 s9, s9, 0
	s_branch .Lgate_n_j5

; __device__ __forceinline__ unsigned pk2(float lo, float hi) { f32x2_t v = {lo, hi}; bf16x2_t b = __builtin_convertvector(v, bf16x2_t); return __builtin_bit_cast(unsigned, b); }
; __device__ __forceinline__ float sigmoidf_(float x) { return __builtin_amdgcn_rcpf(1.0f + fexp2(-x * LOG2E)); }
;     __device__ __forceinline__ void operator()(AccRef acc, const pg8::Unit& u, int wr, int wc, int fr, int fq) const {
;     ...
;                 v4u pw4[4], tw4[4];
; #pragma unroll
;                 for (int m = 0; m < 4; ++m) {
;                     const size_t ci = ub + (size_t)((ai * 2 + bj) * 4 + m) * NTHREADS;
;                     pw4[m] = P[ci];
;                     if (!first) tw4[m] = TMP[ci]; else tw4[m] = (v4u){0u, 0u, 0u, 0u};
;                 }
; #pragma unroll
;                 for (int m = 0; m < 4; ++m) {
;                     const size_t ci = ub + (size_t)((ai * 2 + bj) * 4 + m) * NTHREADS;
;                     const v4u pw = pw4[m], tw = tw4[m];
;                     const float rs = rst[(row0 + ai * 128 + m * 16) & 255];
;                     float v[8];
;                     v[0] = sigmoidf_(acc[ai][bj][m][0][0] * rs + bv0[0]) * bflo(pw.x); v[1] = sigmoidf_(acc[ai][bj][m][0][1] * rs + bv0[1]) * bfhi(pw.x);
;                     v[2] = sigmoidf_(acc[ai][bj][m][0][2] * rs + bv0[2]) * bflo(pw.y); v[3] = sigmoidf_(acc[ai][bj][m][0][3] * rs + bv0[3]) * bfhi(pw.y);
;                     v[4] = sigmoidf_(acc[ai][bj][m][1][0] * rs + bv1[0]) * bflo(pw.z); v[5] = sigmoidf_(acc[ai][bj][m][1][1] * rs + bv1[1]) * bfhi(pw.z);
;                     v[6] = sigmoidf_(acc[ai][bj][m][1][2] * rs + bv1[2]) * bflo(pw.w); v[7] = sigmoidf_(acc[ai][bj][m][1][3] * rs + bv1[3]) * bfhi(pw.w);
;                     v[0] += bflo(tw.x); v[1] += bfhi(tw.x); v[2] += bflo(tw.y); v[3] += bfhi(tw.y);
;                     v[4] += bflo(tw.z); v[5] += bfhi(tw.z); v[6] += bflo(tw.w); v[7] += bfhi(tw.w);
;                     v4u w; w.x = pk2(v[0], v[1]); w.y = pk2(v[2], v[3]); w.z = pk2(v[4], v[5]); w.w = pk2(v[6], v[7]);
;                     if (!last) TMP[ci] = w;
;                     else *(v4u*)(MRG + (size_t)(row0 + ai * 128 + m * 16) * D + col0 + bj * 128) = w;
.Lgate_n_j5:
	global_load_dwordx4 v[42:45], v224, s[6:7]
	global_load_dwordx4 v[46:49], v225, s[6:7]
	s_add_u32 s6, s6, 0x2000
	s_addc_u32 s7, s7, 0
	s_waitcnt vmcnt(15)
	v_fma_f32 v50, v150, v212, v202
	v_fma_f32 v51, v151, v212, v203
	v_fma_f32 v52, v152, v212, v204
	v_fma_f32 v53, v153, v212, v205
	v_fma_f32 v54, v146, v212, v206
	v_fma_f32 v55, v147, v212, v207
	v_fma_f32 v56, v148, v212, v208
	v_fma_f32 v57, v149, v212, v209
	v_mul_f32_e32 v50, 0xbfb8aa3b, v50
	v_mul_f32_e32 v51, 0xbfb8aa3b, v51
	v_mul_f32_e32 v52, 0xbfb8aa3b, v52
	v_mul_f32_e32 v53, 0xbfb8aa3b, v53
	v_mul_f32_e32 v54, 0xbfb8aa3b, v54
	v_mul_f32_e32 v55, 0xbfb8aa3b, v55
	v_mul_f32_e32 v56, 0xbfb8aa3b, v56
	v_mul_f32_e32 v57, 0xbfb8aa3b, v57
	v_exp_f32_e32 v50, v50
	v_exp_f32_e32 v51, v51
	v_exp_f32_e32 v52, v52
	v_exp_f32_e32 v53, v53
	v_exp_f32_e32 v54, v54
	v_exp_f32_e32 v55, v55
	v_exp_f32_e32 v56, v56
	v_exp_f32_e32 v57, v57
	v_add_f32_e32 v50, 1.0, v50
	v_add_f32_e32 v51, 1.0, v51
	v_add_f32_e32 v52, 1.0, v52
	v_add_f32_e32 v53, 1.0, v53
	v_add_f32_e32 v54, 1.0, v54
	v_add_f32_e32 v55, 1.0, v55
	v_add_f32_e32 v56, 1.0, v56
	v_add_f32_e32 v57, 1.0, v57
	v_rcp_f32_e32 v50, v50
	v_rcp_f32_e32 v51, v51
	v_rcp_f32_e32 v52, v52
	v_rcp_f32_e32 v53, v53
	v_rcp_f32_e32 v54, v54
	v_rcp_f32_e32 v55, v55
	v_rcp_f32_e32 v56, v56
	v_rcp_f32_e32 v57, v57
	v_lshlrev_b32_e32 v58, 16, v2
	v_and_b32_e32 v59, 0xffff0000, v2
	v_lshlrev_b32_e32 v60, 16, v6
	v_and_b32_e32 v61, 0xffff0000, v6
	v_pk_fma_f32 v[50:51], v[50:51], v[58:59], v[60:61]
	v_lshlrev_b32_e32 v58, 16, v3
	v_and_b32_e32 v59, 0xffff0000, v3
	v_lshlrev_b32_e32 v60, 16, v7
	v_and_b32_e32 v61, 0xffff0000, v7
	v_pk_fma_f32 v[52:53], v[52:53], v[58:59], v[60:61]
	v_lshlrev_b32_e32 v58, 16, v4
	v_and_b32_e32 v59, 0xffff0000, v4
	v_lshlrev_b32_e32 v60, 16, v8
	v_and_b32_e32 v61, 0xffff0000, v8
	v_pk_fma_f32 v[54:55], v[54:55], v[58:59], v[60:61]
	v_lshlrev_b32_e32 v58, 16, v5
	v_and_b32_e32 v59, 0xffff0000, v5
	v_lshlrev_b32_e32 v60, 16, v9
	v_and_b32_e32 v61, 0xffff0000, v9
	v_pk_fma_f32 v[56:57], v[56:57], v[58:59], v[60:61]
	v_cvt_pk_bf16_f32 v2, v50, v51
	v_cvt_pk_bf16_f32 v3, v52, v53
	v_cvt_pk_bf16_f32 v4, v54, v55
	v_cvt_pk_bf16_f32 v5, v56, v57
	s_cbranch_vccz .Lgate_n_m6
	global_store_dwordx4 v225, v[2:5], s[8:9]
	s_add_u32 s8, s8, 0x2000
	s_addc_u32 s9, s9, 0
	s_branch .Lgate_n_j6

; __device__ __forceinline__ unsigned pk2(float lo, float hi) { f32x2_t v = {lo, hi}; bf16x2_t b = __builtin_convertvector(v, bf16x2_t); return __builtin_bit_cast(unsigned, b); }
; __device__ __forceinline__ float sigmoidf_(float x) { return __builtin_amdgcn_rcpf(1.0f + fexp2(-x * LOG2E)); }
;     __device__ __forceinline__ void operator()(AccRef acc, const pg8::Unit& u, int wr, int wc, int fr, int fq) const {
;     ...
;                 v4u pw4[4], tw4[4];
; #pragma unroll
;                 for (int m = 0; m < 4; ++m) {
;                     const size_t ci = ub + (size_t)((ai * 2 + bj) * 4 + m) * NTHREADS;
;                     pw4[m] = P[ci];
;                     if (!first) tw4[m] = TMP[ci]; else tw4[m] = (v4u){0u, 0u, 0u, 0u};
;                 }
; #pragma unroll
;                 for (int m = 0; m < 4; ++m) {
;                     const size_t ci = ub + (size_t)((ai * 2 + bj) * 4 + m) * NTHREADS;
;                     const v4u pw = pw4[m], tw = tw4[m];
;                     const float rs = rst[(row0 + ai * 128 + m * 16) & 255];
;                     float v[8];
;                     v[0] = sigmoidf_(acc[ai][bj][m][0][0] * rs + bv0[0]) * bflo(pw.x); v[1] = sigmoidf_(acc[ai][bj][m][0][1] * rs + bv0[1]) * bfhi(pw.x);
;                     v[2] = sigmoidf_(acc[ai][bj][m][0][2] * rs + bv0[2]) * bflo(pw.y); v[3] = sigmoidf_(acc[ai][bj][m][0][3] * rs + bv0[3]) * bfhi(pw.y);
;                     v[4] = sigmoidf_(acc[ai][bj][m][1][0] * rs + bv1[0]) * bflo(pw.z); v[5] = sigmoidf_(acc[ai][bj][m][1][1] * rs + bv1[1]) * bfhi(pw.z);
;                     v[6] = sigmoidf_(acc[ai][bj][m][1][2] * rs + bv1[2]) * bflo(pw.w); v[7] = sigmoidf_(acc[ai][bj][m][1][3] * rs + bv1[3]) * bfhi(pw.w);
;                     v[0] += bflo(tw.x); v[1] += bfhi(tw.x); v[2] += bflo(tw.y); v[3] += bfhi(tw.y);
;                     v[4] += bflo(tw.z); v[5] += bfhi(tw.z); v[6] += bflo(tw.w); v[7] += bfhi(tw.w);
;                     v4u w; w.x = pk2(v[0], v[1]); w.y = pk2(v[2], v[3]); w.z = pk2(v[4], v[5]); w.w = pk2(v[6], v[7]);
;                     if (!last) TMP[ci] = w;
;                     else *(v4u*)(MRG + (size_t)(row0 + ai * 128 + m * 16) * D + col0 + bj * 128) = w;
.Lgate_n_j6:
	global_load_dwordx4 v[2:5], v224, s[6:7]
	global_load_dwordx4 v[6:9], v225, s[6:7]
	s_add_u32 s6, s6, 0x2000
	s_addc_u32 s7, s7, 0
	s_waitcnt vmcnt(15)
	v_fma_f32 v50, v134, v213, v202
	v_fma_f32 v51, v135, v213, v203
	v_fma_f32 v52, v136, v213, v204
	v_fma_f32 v53, v137, v213, v205
	v_fma_f32 v54, v130, v213, v206
	v_fma_f32 v55, v131, v213, v207
	v_fma_f32 v56, v132, v213, v208
	v_fma_f32 v57, v133, v213, v209
	v_mul_f32_e32 v50, 0xbfb8aa3b, v50
	v_mul_f32_e32 v51, 0xbfb8aa3b, v51
	v_mul_f32_e32 v52, 0xbfb8aa3b, v52
	v_mul_f32_e32 v53, 0xbfb8aa3b, v53
	v_mul_f32_e32 v54, 0xbfb8aa3b, v54
	v_mul_f32_e32 v55, 0xbfb8aa3b, v55
	v_mul_f32_e32 v56, 0xbfb8aa3b, v56
	v_mul_f32_e32 v57, 0xbfb8aa3b, v57
	v_exp_f32_e32 v50, v50
	v_exp_f32_e32 v51, v51
	v_exp_f32_e32 v52, v52
	v_exp_f32_e32 v53, v53
	v_exp_f32_e32 v54, v54
	v_exp_f32_e32 v55, v55
	v_exp_f32_e32 v56, v56
	v_exp_f32_e32 v57, v57
	v_add_f32_e32 v50, 1.0, v50
	v_add_f32_e32 v51, 1.0, v51
	v_add_f32_e32 v52, 1.0, v52
	v_add_f32_e32 v53, 1.0, v53
	v_add_f32_e32 v54, 1.0, v54
	v_add_f32_e32 v55, 1.0, v55
	v_add_f32_e32 v56, 1.0, v56
	v_add_f32_e32 v57, 1.0, v57
	v_rcp_f32_e32 v50, v50
	v_rcp_f32_e32 v51, v51
	v_rcp_f32_e32 v52, v52
	v_rcp_f32_e32 v53, v53
	v_rcp_f32_e32 v54, v54
	v_rcp_f32_e32 v55, v55
	v_rcp_f32_e32 v56, v56
	v_rcp_f32_e32 v57, v57
	v_lshlrev_b32_e32 v58, 16, v10
	v_and_b32_e32 v59, 0xffff0000, v10
	v_lshlrev_b32_e32 v60, 16, v14
	v_and_b32_e32 v61, 0xffff0000, v14
	v_pk_fma_f32 v[50:51], v[50:51], v[58:59], v[60:61]
	v_lshlrev_b32_e32 v58, 16, v11
	v_and_b32_e32 v59, 0xffff0000, v11
	v_lshlrev_b32_e32 v60, 16, v15
	v_and_b32_e32 v61, 0xffff0000, v15
	v_pk_fma_f32 v[52:53], v[52:53], v[58:59], v[60:61]
	v_lshlrev_b32_e32 v58, 16, v12
	v_and_b32_e32 v59, 0xffff0000, v12
	v_lshlrev_b32_e32 v60, 16, v16
	v_and_b32_e32 v61, 0xffff0000, v16
	v_pk_fma_f32 v[54:55], v[54:55], v[58:59], v[60:61]
	v_lshlrev_b32_e32 v58, 16, v13
	v_and_b32_e32 v59, 0xffff0000, v13
	v_lshlrev_b32_e32 v60, 16, v17
	v_and_b32_e32 v61, 0xffff0000, v17
	v_pk_fma_f32 v[56:57], v[56:57], v[58:59], v[60:61]
	v_cvt_pk_bf16_f32 v10, v50, v51
	v_cvt_pk_bf16_f32 v11, v52, v53
	v_cvt_pk_bf16_f32 v12, v54, v55
	v_cvt_pk_bf16_f32 v13, v56, v57
	s_cbranch_vccz .Lgate_n_m7
	global_store_dwordx4 v225, v[10:13], s[8:9]
	s_add_u32 s8, s8, 0x2000
	s_addc_u32 s9, s9, 0
	s_branch .Lgate_n_j7

; __device__ __forceinline__ unsigned pk2(float lo, float hi) { f32x2_t v = {lo, hi}; bf16x2_t b = __builtin_convertvector(v, bf16x2_t); return __builtin_bit_cast(unsigned, b); }
; __device__ __forceinline__ float sigmoidf_(float x) { return __builtin_amdgcn_rcpf(1.0f + fexp2(-x * LOG2E)); }
;     __device__ __forceinline__ void operator()(AccRef acc, const pg8::Unit& u, int wr, int wc, int fr, int fq) const {
;     ...
;                 v4u pw4[4], tw4[4];
; #pragma unroll
;                 for (int m = 0; m < 4; ++m) {
;                     const size_t ci = ub + (size_t)((ai * 2 + bj) * 4 + m) * NTHREADS;
;                     pw4[m] = P[ci];
;                     if (!first) tw4[m] = TMP[ci]; else tw4[m] = (v4u){0u, 0u, 0u, 0u};
;                 }
; #pragma unroll
;                 for (int m = 0; m < 4; ++m) {
;                     const size_t ci = ub + (size_t)((ai * 2 + bj) * 4 + m) * NTHREADS;
;                     const v4u pw = pw4[m], tw = tw4[m];
;                     const float rs = rst[(row0 + ai * 128 + m * 16) & 255];
;                     float v[8];
;                     v[0] = sigmoidf_(acc[ai][bj][m][0][0] * rs + bv0[0]) * bflo(pw.x); v[1] = sigmoidf_(acc[ai][bj][m][0][1] * rs + bv0[1]) * bfhi(pw.x);
;                     v[2] = sigmoidf_(acc[ai][bj][m][0][2] * rs + bv0[2]) * bflo(pw.y); v[3] = sigmoidf_(acc[ai][bj][m][0][3] * rs + bv0[3]) * bfhi(pw.y);
;                     v[4] = sigmoidf_(acc[ai][bj][m][1][0] * rs + bv1[0]) * bflo(pw.z); v[5] = sigmoidf_(acc[ai][bj][m][1][1] * rs + bv1[1]) * bfhi(pw.z);
;                     v[6] = sigmoidf_(acc[ai][bj][m][1][2] * rs + bv1[2]) * bflo(pw.w); v[7] = sigmoidf_(acc[ai][bj][m][1][3] * rs + bv1[3]) * bfhi(pw.w);
;                     v[0] += bflo(tw.x); v[1] += bfhi(tw.x); v[2] += bflo(tw.y); v[3] += bfhi(tw.y);
;                     v[4] += bflo(tw.z); v[5] += bfhi(tw.z); v[6] += bflo(tw.w); v[7] += bfhi(tw.w);
;                     v4u w; w.x = pk2(v[0], v[1]); w.y = pk2(v[2], v[3]); w.z = pk2(v[4], v[5]); w.w = pk2(v[6], v[7]);
;                     if (!last) TMP[ci] = w;
;                     else *(v4u*)(MRG + (size_t)(row0 + ai * 128 + m * 16) * D + col0 + bj * 128) = w;
.Lgate_n_j7:
	global_load_dwordx4 v[10:13], v224, s[6:7]
	global_load_dwordx4 v[14:17], v225, s[6:7]
	s_add_u32 s6, s6, 0x2000
	s_addc_u32 s7, s7, 0
	s_waitcnt vmcnt(15)
	v_fma_f32 v50, v126, v228, v194
	v_fma_f32 v51, v127, v228, v195
	v_fma_f32 v52, v128, v228, v196
	v_fma_f32 v53, v129, v228, v197
	v_fma_f32 v54, v122, v228, v198
	v_fma_f32 v55, v123, v228, v199
	v_fma_f32 v56, v124, v228, v200
	v_fma_f32 v57, v125, v228, v201
	v_mul_f32_e32 v50, 0xbfb8aa3b, v50
	v_mul_f32_e32 v51, 0xbfb8aa3b, v51
	v_mul_f32_e32 v52, 0xbfb8aa3b, v52
	v_mul_f32_e32 v53, 0xbfb8aa3b, v53
	v_mul_f32_e32 v54, 0xbfb8aa3b, v54
	v_mul_f32_e32 v55, 0xbfb8aa3b, v55
	v_mul_f32_e32 v56, 0xbfb8aa3b, v56
	v_mul_f32_e32 v57, 0xbfb8aa3b, v57
	v_exp_f32_e32 v50, v50
	v_exp_f32_e32 v51, v51
	v_exp_f32_e32 v52, v52
	v_exp_f32_e32 v53, v53
	v_exp_f32_e32 v54, v54
	v_exp_f32_e32 v55, v55
	v_exp_f32_e32 v56, v56
	v_exp_f32_e32 v57, v57
	v_add_f32_e32 v50, 1.0, v50
	v_add_f32_e32 v51, 1.0, v51
	v_add_f32_e32 v52, 1.0, v52
	v_add_f32_e32 v53, 1.0, v53
	v_add_f32_e32 v54, 1.0, v54
	v_add_f32_e32 v55, 1.0, v55
	v_add_f32_e32 v56, 1.0, v56
	v_add_f32_e32 v57, 1.0, v57
	v_rcp_f32_e32 v50, v50
	v_rcp_f32_e32 v51, v51
	v_rcp_f32_e32 v52, v52
	v_rcp_f32_e32 v53, v53
	v_rcp_f32_e32 v54, v54
	v_rcp_f32_e32 v55, v55
	v_rcp_f32_e32 v56, v56
	v_rcp_f32_e32 v57, v57
	v_lshlrev_b32_e32 v58, 16, v18
	v_and_b32_e32 v59, 0xffff0000, v18
	v_lshlrev_b32_e32 v60, 16, v22
	v_and_b32_e32 v61, 0xffff0000, v22
	v_pk_fma_f32 v[50:51], v[50:51], v[58:59], v[60:61]
	v_lshlrev_b32_e32 v58, 16, v19
	v_and_b32_e32 v59, 0xffff0000, v19
	v_lshlrev_b32_e32 v60, 16, v23
	v_and_b32_e32 v61, 0xffff0000, v23
	v_pk_fma_f32 v[52:53], v[52:53], v[58:59], v[60:61]
	v_lshlrev_b32_e32 v58, 16, v20
	v_and_b32_e32 v59, 0xffff0000, v20
	v_lshlrev_b32_e32 v60, 16, v24
	v_and_b32_e32 v61, 0xffff0000, v24
	v_pk_fma_f32 v[54:55], v[54:55], v[58:59], v[60:61]
	v_lshlrev_b32_e32 v58, 16, v21
	v_and_b32_e32 v59, 0xffff0000, v21
	v_lshlrev_b32_e32 v60, 16, v25
	v_and_b32_e32 v61, 0xffff0000, v25
	v_pk_fma_f32 v[56:57], v[56:57], v[58:59], v[60:61]
	v_cvt_pk_bf16_f32 v18, v50, v51
	v_cvt_pk_bf16_f32 v19, v52, v53
	v_cvt_pk_bf16_f32 v20, v54, v55
	v_cvt_pk_bf16_f32 v21, v56, v57
	s_cbranch_vccz .Lgate_n_m8
	global_store_dwordx4 v225, v[18:21], s[8:9]
	s_add_u32 s8, s8, 0x2000
	s_addc_u32 s9, s9, 0
	s_branch .Lgate_n_j8

; __device__ __forceinline__ unsigned pk2(float lo, float hi) { f32x2_t v = {lo, hi}; bf16x2_t b = __builtin_convertvector(v, bf16x2_t); return __builtin_bit_cast(unsigned, b); }
; __device__ __forceinline__ float sigmoidf_(float x) { return __builtin_amdgcn_rcpf(1.0f + fexp2(-x * LOG2E)); }
;     __device__ __forceinline__ void operator()(AccRef acc, const pg8::Unit& u, int wr, int wc, int fr, int fq) const {
;     ...
;                 v4u pw4[4], tw4[4];
; #pragma unroll
;                 for (int m = 0; m < 4; ++m) {
;                     const size_t ci = ub + (size_t)((ai * 2 + bj) * 4 + m) * NTHREADS;
;                     pw4[m] = P[ci];
;                     if (!first) tw4[m] = TMP[ci]; else tw4[m] = (v4u){0u, 0u, 0u, 0u};
;                 }
; #pragma unroll
;                 for (int m = 0; m < 4; ++m) {
;                     const size_t ci = ub + (size_t)((ai * 2 + bj) * 4 + m) * NTHREADS;
;                     const v4u pw = pw4[m], tw = tw4[m];
;                     const float rs = rst[(row0 + ai * 128 + m * 16) & 255];
;                     float v[8];
;                     v[0] = sigmoidf_(acc[ai][bj][m][0][0] * rs + bv0[0]) * bflo(pw.x); v[1] = sigmoidf_(acc[ai][bj][m][0][1] * rs + bv0[1]) * bfhi(pw.x);
;                     v[2] = sigmoidf_(acc[ai][bj][m][0][2] * rs + bv0[2]) * bflo(pw.y); v[3] = sigmoidf_(acc[ai][bj][m][0][3] * rs + bv0[3]) * bfhi(pw.y);
;                     v[4] = sigmoidf_(acc[ai][bj][m][1][0] * rs + bv1[0]) * bflo(pw.z); v[5] = sigmoidf_(acc[ai][bj][m][1][1] * rs + bv1[1]) * bfhi(pw.z);
;                     v[6] = sigmoidf_(acc[ai][bj][m][1][2] * rs + bv1[2]) * bflo(pw.w); v[7] = sigmoidf_(acc[ai][bj][m][1][3] * rs + bv1[3]) * bfhi(pw.w);
;                     v[0] += bflo(tw.x); v[1] += bfhi(tw.x); v[2] += bflo(tw.y); v[3] += bfhi(tw.y);
;                     v[4] += bflo(tw.z); v[5] += bfhi(tw.z); v[6] += bflo(tw.w); v[7] += bfhi(tw.w);
;                     v4u w; w.x = pk2(v[0], v[1]); w.y = pk2(v[2], v[3]); w.z = pk2(v[4], v[5]); w.w = pk2(v[6], v[7]);
;                     if (!last) TMP[ci] = w;
;                     else *(v4u*)(MRG + (size_t)(row0 + ai * 128 + m * 16) * D + col0 + bj * 128) = w;
.Lgate_n_j8:
	global_load_dwordx4 v[18:21], v224, s[6:7]
	global_load_dwordx4 v[22:25], v225, s[6:7]
	s_add_u32 s6, s6, 0x2000
	s_addc_u32 s7, s7, 0
	s_waitcnt vmcnt(15)
	v_fma_f32 v50, v110, v229, v194
	v_fma_f32 v51, v111, v229, v195
	v_fma_f32 v52, v112, v229, v196
	v_fma_f32 v53, v113, v229, v197
	v_fma_f32 v54, v106, v229, v198
	v_fma_f32 v55, v107, v229, v199
	v_fma_f32 v56, v108, v229, v200
	v_fma_f32 v57, v109, v229, v201
	v_mul_f32_e32 v50, 0xbfb8aa3b, v50
	v_mul_f32_e32 v51, 0xbfb8aa3b, v51
	v_mul_f32_e32 v52, 0xbfb8aa3b, v52
	v_mul_f32_e32 v53, 0xbfb8aa3b, v53
	v_mul_f32_e32 v54, 0xbfb8aa3b, v54
	v_mul_f32_e32 v55, 0xbfb8aa3b, v55
	v_mul_f32_e32 v56, 0xbfb8aa3b, v56
	v_mul_f32_e32 v57, 0xbfb8aa3b, v57
	v_exp_f32_e32 v50, v50
	v_exp_f32_e32 v51, v51
	v_exp_f32_e32 v52, v52
	v_exp_f32_e32 v53, v53
	v_exp_f32_e32 v54, v54
	v_exp_f32_e32 v55, v55
	v_exp_f32_e32 v56, v56
	v_exp_f32_e32 v57, v57
	v_add_f32_e32 v50, 1.0, v50
	v_add_f32_e32 v51, 1.0, v51
	v_add_f32_e32 v52, 1.0, v52
	v_add_f32_e32 v53, 1.0, v53
	v_add_f32_e32 v54, 1.0, v54
	v_add_f32_e32 v55, 1.0, v55
	v_add_f32_e32 v56, 1.0, v56
	v_add_f32_e32 v57, 1.0, v57
	v_rcp_f32_e32 v50, v50
	v_rcp_f32_e32 v51, v51
	v_rcp_f32_e32 v52, v52
	v_rcp_f32_e32 v53, v53
	v_rcp_f32_e32 v54, v54
	v_rcp_f32_e32 v55, v55
	v_rcp_f32_e32 v56, v56
	v_rcp_f32_e32 v57, v57
	v_lshlrev_b32_e32 v58, 16, v26
	v_and_b32_e32 v59, 0xffff0000, v26
	v_lshlrev_b32_e32 v60, 16, v30
	v_and_b32_e32 v61, 0xffff0000, v30
	v_pk_fma_f32 v[50:51], v[50:51], v[58:59], v[60:61]
	v_lshlrev_b32_e32 v58, 16, v27
	v_and_b32_e32 v59, 0xffff0000, v27
	v_lshlrev_b32_e32 v60, 16, v31
	v_and_b32_e32 v61, 0xffff0000, v31
	v_pk_fma_f32 v[52:53], v[52:53], v[58:59], v[60:61]
	v_lshlrev_b32_e32 v58, 16, v28
	v_and_b32_e32 v59, 0xffff0000, v28
	v_lshlrev_b32_e32 v60, 16, v32
	v_and_b32_e32 v61, 0xffff0000, v32
	v_pk_fma_f32 v[54:55], v[54:55], v[58:59], v[60:61]
	v_lshlrev_b32_e32 v58, 16, v29
	v_and_b32_e32 v59, 0xffff0000, v29
	v_lshlrev_b32_e32 v60, 16, v33
	v_and_b32_e32 v61, 0xffff0000, v33
	v_pk_fma_f32 v[56:57], v[56:57], v[58:59], v[60:61]
	v_cvt_pk_bf16_f32 v26, v50, v51
	v_cvt_pk_bf16_f32 v27, v52, v53
	v_cvt_pk_bf16_f32 v28, v54, v55
	v_cvt_pk_bf16_f32 v29, v56, v57
	s_cbranch_vccz .Lgate_n_m9
	global_store_dwordx4 v225, v[26:29], s[8:9]
	s_add_u32 s8, s8, 0x2000
	s_addc_u32 s9, s9, 0
	s_branch .Lgate_n_j9

; __device__ __forceinline__ unsigned pk2(float lo, float hi) { f32x2_t v = {lo, hi}; bf16x2_t b = __builtin_convertvector(v, bf16x2_t); return __builtin_bit_cast(unsigned, b); }
; __device__ __forceinline__ float sigmoidf_(float x) { return __builtin_amdgcn_rcpf(1.0f + fexp2(-x * LOG2E)); }
;     __device__ __forceinline__ void operator()(AccRef acc, const pg8::Unit& u, int wr, int wc, int fr, int fq) const {
;     ...
;                 v4u pw4[4], tw4[4];
; #pragma unroll
;                 for (int m = 0; m < 4; ++m) {
;                     const size_t ci = ub + (size_t)((ai * 2 + bj) * 4 + m) * NTHREADS;
;                     pw4[m] = P[ci];
;                     if (!first) tw4[m] = TMP[ci]; else tw4[m] = (v4u){0u, 0u, 0u, 0u};
;                 }
; #pragma unroll
;                 for (int m = 0; m < 4; ++m) {
;                     const size_t ci = ub + (size_t)((ai * 2 + bj) * 4 + m) * NTHREADS;
;                     const v4u pw = pw4[m], tw = tw4[m];
;                     const float rs = rst[(row0 + ai * 128 + m * 16) & 255];
;                     float v[8];
;                     v[0] = sigmoidf_(acc[ai][bj][m][0][0] * rs + bv0[0]) * bflo(pw.x); v[1] = sigmoidf_(acc[ai][bj][m][0][1] * rs + bv0[1]) * bfhi(pw.x);
;                     v[2] = sigmoidf_(acc[ai][bj][m][0][2] * rs + bv0[2]) * bflo(pw.y); v[3] = sigmoidf_(acc[ai][bj][m][0][3] * rs + bv0[3]) * bfhi(pw.y);
;                     v[4] = sigmoidf_(acc[ai][bj][m][1][0] * rs + bv1[0]) * bflo(pw.z); v[5] = sigmoidf_(acc[ai][bj][m][1][1] * rs + bv1[1]) * bfhi(pw.z);
;                     v[6] = sigmoidf_(acc[ai][bj][m][1][2] * rs + bv1[2]) * bflo(pw.w); v[7] = sigmoidf_(acc[ai][bj][m][1][3] * rs + bv1[3]) * bfhi(pw.w);
;                     v[0] += bflo(tw.x); v[1] += bfhi(tw.x); v[2] += bflo(tw.y); v[3] += bfhi(tw.y);
;                     v[4] += bflo(tw.z); v[5] += bfhi(tw.z); v[6] += bflo(tw.w); v[7] += bfhi(tw.w);
;                     v4u w; w.x = pk2(v[0], v[1]); w.y = pk2(v[2], v[3]); w.z = pk2(v[4], v[5]); w.w = pk2(v[6], v[7]);
;                     if (!last) TMP[ci] = w;
;                     else *(v4u*)(MRG + (size_t)(row0 + ai * 128 + m * 16) * D + col0 + bj * 128) = w;
.Lgate_n_j9:
	global_load_dwordx4 v[26:29], v224, s[6:7]
	global_load_dwordx4 v[30:33], v225, s[6:7]
	s_add_u32 s6, s6, 0x2000
	s_addc_u32 s7, s7, 0
	s_waitcnt vmcnt(15)
	v_fma_f32 v50, v94, v230, v194
	v_fma_f32 v51, v95, v230, v195
	v_fma_f32 v52, v96, v230, v196
	v_fma_f32 v53, v97, v230, v197
	v_fma_f32 v54, v90, v230, v198
	v_fma_f32 v55, v91, v230, v199
	v_fma_f32 v56, v92, v230, v200
	v_fma_f32 v57, v93, v230, v201
	v_mul_f32_e32 v50, 0xbfb8aa3b, v50
	v_mul_f32_e32 v51, 0xbfb8aa3b, v51
	v_mul_f32_e32 v52, 0xbfb8aa3b, v52
	v_mul_f32_e32 v53, 0xbfb8aa3b, v53
	v_mul_f32_e32 v54, 0xbfb8aa3b, v54
	v_mul_f32_e32 v55, 0xbfb8aa3b, v55
	v_mul_f32_e32 v56, 0xbfb8aa3b, v56
	v_mul_f32_e32 v57, 0xbfb8aa3b, v57
	v_exp_f32_e32 v50, v50
	v_exp_f32_e32 v51, v51
	v_exp_f32_e32 v52, v52
	v_exp_f32_e32 v53, v53
	v_exp_f32_e32 v54, v54
	v_exp_f32_e32 v55, v55
	v_exp_f32_e32 v56, v56
	v_exp_f32_e32 v57, v57
	v_add_f32_e32 v50, 1.0, v50
	v_add_f32_e32 v51, 1.0, v51
	v_add_f32_e32 v52, 1.0, v52
	v_add_f32_e32 v53, 1.0, v53
	v_add_f32_e32 v54, 1.0, v54
	v_add_f32_e32 v55, 1.0, v55
	v_add_f32_e32 v56, 1.0, v56
	v_add_f32_e32 v57, 1.0, v57
	v_rcp_f32_e32 v50, v50
	v_rcp_f32_e32 v51, v51
	v_rcp_f32_e32 v52, v52
	v_rcp_f32_e32 v53, v53
	v_rcp_f32_e32 v54, v54
	v_rcp_f32_e32 v55, v55
	v_rcp_f32_e32 v56, v56
	v_rcp_f32_e32 v57, v57
	v_lshlrev_b32_e32 v58, 16, v34
	v_and_b32_e32 v59, 0xffff0000, v34
	v_lshlrev_b32_e32 v60, 16, v38
	v_and_b32_e32 v61, 0xffff0000, v38
	v_pk_fma_f32 v[50:51], v[50:51], v[58:59], v[60:61]
	v_lshlrev_b32_e32 v58, 16, v35
	v_and_b32_e32 v59, 0xffff0000, v35
	v_lshlrev_b32_e32 v60, 16, v39
	v_and_b32_e32 v61, 0xffff0000, v39
	v_pk_fma_f32 v[52:53], v[52:53], v[58:59], v[60:61]
	v_lshlrev_b32_e32 v58, 16, v36
	v_and_b32_e32 v59, 0xffff0000, v36
	v_lshlrev_b32_e32 v60, 16, v40
	v_and_b32_e32 v61, 0xffff0000, v40
	v_pk_fma_f32 v[54:55], v[54:55], v[58:59], v[60:61]
	v_lshlrev_b32_e32 v58, 16, v37
	v_and_b32_e32 v59, 0xffff0000, v37
	v_lshlrev_b32_e32 v60, 16, v41
	v_and_b32_e32 v61, 0xffff0000, v41
	v_pk_fma_f32 v[56:57], v[56:57], v[58:59], v[60:61]
	v_cvt_pk_bf16_f32 v34, v50, v51
	v_cvt_pk_bf16_f32 v35, v52, v53
	v_cvt_pk_bf16_f32 v36, v54, v55
	v_cvt_pk_bf16_f32 v37, v56, v57
	s_cbranch_vccz .Lgate_n_m10
	global_store_dwordx4 v225, v[34:37], s[8:9]
	s_add_u32 s8, s8, 0x2000
	s_addc_u32 s9, s9, 0
	s_branch .Lgate_n_j10

; __device__ __forceinline__ unsigned pk2(float lo, float hi) { f32x2_t v = {lo, hi}; bf16x2_t b = __builtin_convertvector(v, bf16x2_t); return __builtin_bit_cast(unsigned, b); }
; __device__ __forceinline__ float sigmoidf_(float x) { return __builtin_amdgcn_rcpf(1.0f + fexp2(-x * LOG2E)); }
;     __device__ __forceinline__ void operator()(AccRef acc, const pg8::Unit& u, int wr, int wc, int fr, int fq) const {
;     ...
;                 v4u pw4[4], tw4[4];
; #pragma unroll
;                 for (int m = 0; m < 4; ++m) {
;                     const size_t ci = ub + (size_t)((ai * 2 + bj) * 4 + m) * NTHREADS;
;                     pw4[m] = P[ci];
;                     if (!first) tw4[m] = TMP[ci]; else tw4[m] = (v4u){0u, 0u, 0u, 0u};
;                 }
; #pragma unroll
;                 for (int m = 0; m < 4; ++m) {
;                     const size_t ci = ub + (size_t)((ai * 2 + bj) * 4 + m) * NTHREADS;
;                     const v4u pw = pw4[m], tw = tw4[m];
;                     const float rs = rst[(row0 + ai * 128 + m * 16) & 255];
;                     float v[8];
;                     v[0] = sigmoidf_(acc[ai][bj][m][0][0] * rs + bv0[0]) * bflo(pw.x); v[1] = sigmoidf_(acc[ai][bj][m][0][1] * rs + bv0[1]) * bfhi(pw.x);
;                     v[2] = sigmoidf_(acc[ai][bj][m][0][2] * rs + bv0[2]) * bflo(pw.y); v[3] = sigmoidf_(acc[ai][bj][m][0][3] * rs + bv0[3]) * bfhi(pw.y);
;                     v[4] = sigmoidf_(acc[ai][bj][m][1][0] * rs + bv1[0]) * bflo(pw.z); v[5] = sigmoidf_(acc[ai][bj][m][1][1] * rs + bv1[1]) * bfhi(pw.z);
;                     v[6] = sigmoidf_(acc[ai][bj][m][1][2] * rs + bv1[2]) * bflo(pw.w); v[7] = sigmoidf_(acc[ai][bj][m][1][3] * rs + bv1[3]) * bfhi(pw.w);
;                     v[0] += bflo(tw.x); v[1] += bfhi(tw.x); v[2] += bflo(tw.y); v[3] += bfhi(tw.y);
;                     v[4] += bflo(tw.z); v[5] += bfhi(tw.z); v[6] += bflo(tw.w); v[7] += bfhi(tw.w);
;                     v4u w; w.x = pk2(v[0], v[1]); w.y = pk2(v[2], v[3]); w.z = pk2(v[4], v[5]); w.w = pk2(v[6], v[7]);
;                     if (!last) TMP[ci] = w;
;                     else *(v4u*)(MRG + (size_t)(row0 + ai * 128 + m * 16) * D + col0 + bj * 128) = w;
.Lgate_n_j10:
	s_waitcnt vmcnt(13)
	v_fma_f32 v50, v78, v231, v194
	v_fma_f32 v51, v79, v231, v195
	v_fma_f32 v52, v80, v231, v196
	v_fma_f32 v53, v81, v231, v197
	v_fma_f32 v54, v74, v231, v198
	v_fma_f32 v55, v75, v231, v199
	v_fma_f32 v56, v76, v231, v200
	v_fma_f32 v57, v77, v231, v201
	v_mul_f32_e32 v50, 0xbfb8aa3b, v50
	v_mul_f32_e32 v51, 0xbfb8aa3b, v51
	v_mul_f32_e32 v52, 0xbfb8aa3b, v52
	v_mul_f32_e32 v53, 0xbfb8aa3b, v53
	v_mul_f32_e32 v54, 0xbfb8aa3b, v54
	v_mul_f32_e32 v55, 0xbfb8aa3b, v55
	v_mul_f32_e32 v56, 0xbfb8aa3b, v56
	v_mul_f32_e32 v57, 0xbfb8aa3b, v57
	v_exp_f32_e32 v50, v50
	v_exp_f32_e32 v51, v51
	v_exp_f32_e32 v52, v52
	v_exp_f32_e32 v53, v53
	v_exp_f32_e32 v54, v54
	v_exp_f32_e32 v55, v55
	v_exp_f32_e32 v56, v56
	v_exp_f32_e32 v57, v57
	v_add_f32_e32 v50, 1.0, v50
	v_add_f32_e32 v51, 1.0, v51
	v_add_f32_e32 v52, 1.0, v52
	v_add_f32_e32 v53, 1.0, v53
	v_add_f32_e32 v54, 1.0, v54
	v_add_f32_e32 v55, 1.0, v55
	v_add_f32_e32 v56, 1.0, v56
	v_add_f32_e32 v57, 1.0, v57
	v_rcp_f32_e32 v50, v50
	v_rcp_f32_e32 v51, v51
	v_rcp_f32_e32 v52, v52
	v_rcp_f32_e32 v53, v53
	v_rcp_f32_e32 v54, v54
	v_rcp_f32_e32 v55, v55
	v_rcp_f32_e32 v56, v56
	v_rcp_f32_e32 v57, v57
	v_lshlrev_b32_e32 v58, 16, v42
	v_and_b32_e32 v59, 0xffff0000, v42
	v_lshlrev_b32_e32 v60, 16, v46
	v_and_b32_e32 v61, 0xffff0000, v46
	v_pk_fma_f32 v[50:51], v[50:51], v[58:59], v[60:61]
	v_lshlrev_b32_e32 v58, 16, v43
	v_and_b32_e32 v59, 0xffff0000, v43
	v_lshlrev_b32_e32 v60, 16, v47
	v_and_b32_e32 v61, 0xffff0000, v47
	v_pk_fma_f32 v[52:53], v[52:53], v[58:59], v[60:61]
	v_lshlrev_b32_e32 v58, 16, v44
	v_and_b32_e32 v59, 0xffff0000, v44
	v_lshlrev_b32_e32 v60, 16, v48
	v_and_b32_e32 v61, 0xffff0000, v48
	v_pk_fma_f32 v[54:55], v[54:55], v[58:59], v[60:61]
	v_lshlrev_b32_e32 v58, 16, v45
	v_and_b32_e32 v59, 0xffff0000, v45
	v_lshlrev_b32_e32 v60, 16, v49
	v_and_b32_e32 v61, 0xffff0000, v49
	v_pk_fma_f32 v[56:57], v[56:57], v[58:59], v[60:61]
	v_cvt_pk_bf16_f32 v42, v50, v51
	v_cvt_pk_bf16_f32 v43, v52, v53
	v_cvt_pk_bf16_f32 v44, v54, v55
	v_cvt_pk_bf16_f32 v45, v56, v57
	s_cbranch_vccz .Lgate_n_m11
	global_store_dwordx4 v225, v[42:45], s[8:9]
	s_add_u32 s8, s8, 0x2000
	s_addc_u32 s9, s9, 0
	s_branch .Lgate_n_j11

; __device__ __forceinline__ unsigned pk2(float lo, float hi) { f32x2_t v = {lo, hi}; bf16x2_t b = __builtin_convertvector(v, bf16x2_t); return __builtin_bit_cast(unsigned, b); }
; __device__ __forceinline__ float sigmoidf_(float x) { return __builtin_amdgcn_rcpf(1.0f + fexp2(-x * LOG2E)); }
;     __device__ __forceinline__ void operator()(AccRef acc, const pg8::Unit& u, int wr, int wc, int fr, int fq) const {
;     ...
;                 v4u pw4[4], tw4[4];
; #pragma unroll
;                 for (int m = 0; m < 4; ++m) {
;                     const size_t ci = ub + (size_t)((ai * 2 + bj) * 4 + m) * NTHREADS;
;                     pw4[m] = P[ci];
;                     if (!first) tw4[m] = TMP[ci]; else tw4[m] = (v4u){0u, 0u, 0u, 0u};
;                 }
; #pragma unroll
;                 for (int m = 0; m < 4; ++m) {
;                     const size_t ci = ub + (size_t)((ai * 2 + bj) * 4 + m) * NTHREADS;
;                     const v4u pw = pw4[m], tw = tw4[m];
;                     const float rs = rst[(row0 + ai * 128 + m * 16) & 255];
;                     float v[8];
;                     v[0] = sigmoidf_(acc[ai][bj][m][0][0] * rs + bv0[0]) * bflo(pw.x); v[1] = sigmoidf_(acc[ai][bj][m][0][1] * rs + bv0[1]) * bfhi(pw.x);
;                     v[2] = sigmoidf_(acc[ai][bj][m][0][2] * rs + bv0[2]) * bflo(pw.y); v[3] = sigmoidf_(acc[ai][bj][m][0][3] * rs + bv0[3]) * bfhi(pw.y);
;                     v[4] = sigmoidf_(acc[ai][bj][m][1][0] * rs + bv1[0]) * bflo(pw.z); v[5] = sigmoidf_(acc[ai][bj][m][1][1] * rs + bv1[1]) * bfhi(pw.z);
;                     v[6] = sigmoidf_(acc[ai][bj][m][1][2] * rs + bv1[2]) * bflo(pw.w); v[7] = sigmoidf_(acc[ai][bj][m][1][3] * rs + bv1[3]) * bfhi(pw.w);
;                     v[0] += bflo(tw.x); v[1] += bfhi(tw.x); v[2] += bflo(tw.y); v[3] += bfhi(tw.y);
;                     v[4] += bflo(tw.z); v[5] += bfhi(tw.z); v[6] += bflo(tw.w); v[7] += bfhi(tw.w);
;                     v4u w; w.x = pk2(v[0], v[1]); w.y = pk2(v[2], v[3]); w.z = pk2(v[4], v[5]); w.w = pk2(v[6], v[7]);
;                     if (!last) TMP[ci] = w;
;                     else *(v4u*)(MRG + (size_t)(row0 + ai * 128 + m * 16) * D + col0 + bj * 128) = w;
.Lgate_n_j11:
	s_waitcnt vmcnt(11)
	v_fma_f32 v50, v118, v228, v202
	v_fma_f32 v51, v119, v228, v203
	v_fma_f32 v52, v120, v228, v204
	v_fma_f32 v53, v121, v228, v205
	v_fma_f32 v54, v114, v228, v206
	v_fma_f32 v55, v115, v228, v207
	v_fma_f32 v56, v116, v228, v208
	v_fma_f32 v57, v117, v228, v209
	v_mul_f32_e32 v50, 0xbfb8aa3b, v50
	v_mul_f32_e32 v51, 0xbfb8aa3b, v51
	v_mul_f32_e32 v52, 0xbfb8aa3b, v52
	v_mul_f32_e32 v53, 0xbfb8aa3b, v53
	v_mul_f32_e32 v54, 0xbfb8aa3b, v54
	v_mul_f32_e32 v55, 0xbfb8aa3b, v55
	v_mul_f32_e32 v56, 0xbfb8aa3b, v56
	v_mul_f32_e32 v57, 0xbfb8aa3b, v57
	v_exp_f32_e32 v50, v50
	v_exp_f32_e32 v51, v51
	v_exp_f32_e32 v52, v52
	v_exp_f32_e32 v53, v53
	v_exp_f32_e32 v54, v54
	v_exp_f32_e32 v55, v55
	v_exp_f32_e32 v56, v56
	v_exp_f32_e32 v57, v57
	v_add_f32_e32 v50, 1.0, v50
	v_add_f32_e32 v51, 1.0, v51
	v_add_f32_e32 v52, 1.0, v52
	v_add_f32_e32 v53, 1.0, v53
	v_add_f32_e32 v54, 1.0, v54
	v_add_f32_e32 v55, 1.0, v55
	v_add_f32_e32 v56, 1.0, v56
	v_add_f32_e32 v57, 1.0, v57
	v_rcp_f32_e32 v50, v50
	v_rcp_f32_e32 v51, v51
	v_rcp_f32_e32 v52, v52
	v_rcp_f32_e32 v53, v53
	v_rcp_f32_e32 v54, v54
	v_rcp_f32_e32 v55, v55
	v_rcp_f32_e32 v56, v56
	v_rcp_f32_e32 v57, v57
	v_lshlrev_b32_e32 v58, 16, v2
	v_and_b32_e32 v59, 0xffff0000, v2
	v_lshlrev_b32_e32 v60, 16, v6
	v_and_b32_e32 v61, 0xffff0000, v6
	v_pk_fma_f32 v[50:51], v[50:51], v[58:59], v[60:61]
	v_lshlrev_b32_e32 v58, 16, v3
	v_and_b32_e32 v59, 0xffff0000, v3
	v_lshlrev_b32_e32 v60, 16, v7
	v_and_b32_e32 v61, 0xffff0000, v7
	v_pk_fma_f32 v[52:53], v[52:53], v[58:59], v[60:61]
	v_lshlrev_b32_e32 v58, 16, v4
	v_and_b32_e32 v59, 0xffff0000, v4
	v_lshlrev_b32_e32 v60, 16, v8
	v_and_b32_e32 v61, 0xffff0000, v8
	v_pk_fma_f32 v[54:55], v[54:55], v[58:59], v[60:61]
	v_lshlrev_b32_e32 v58, 16, v5
	v_and_b32_e32 v59, 0xffff0000, v5
	v_lshlrev_b32_e32 v60, 16, v9
	v_and_b32_e32 v61, 0xffff0000, v9
	v_pk_fma_f32 v[56:57], v[56:57], v[58:59], v[60:61]
	v_cvt_pk_bf16_f32 v2, v50, v51
	v_cvt_pk_bf16_f32 v3, v52, v53
	v_cvt_pk_bf16_f32 v4, v54, v55
	v_cvt_pk_bf16_f32 v5, v56, v57
	s_cbranch_vccz .Lgate_n_m12
	global_store_dwordx4 v225, v[2:5], s[8:9]
	s_add_u32 s8, s8, 0x2000
	s_addc_u32 s9, s9, 0
	s_branch .Lgate_n_j12

; __device__ __forceinline__ unsigned pk2(float lo, float hi) { f32x2_t v = {lo, hi}; bf16x2_t b = __builtin_convertvector(v, bf16x2_t); return __builtin_bit_cast(unsigned, b); }
; __device__ __forceinline__ float sigmoidf_(float x) { return __builtin_amdgcn_rcpf(1.0f + fexp2(-x * LOG2E)); }
;     __device__ __forceinline__ void operator()(AccRef acc, const pg8::Unit& u, int wr, int wc, int fr, int fq) const {
;     ...
;                 v4u pw4[4], tw4[4];
; #pragma unroll
;                 for (int m = 0; m < 4; ++m) {
;                     const size_t ci = ub + (size_t)((ai * 2 + bj) * 4 + m) * NTHREADS;
;                     pw4[m] = P[ci];
;                     if (!first) tw4[m] = TMP[ci]; else tw4[m] = (v4u){0u, 0u, 0u, 0u};
;                 }
; #pragma unroll
;                 for (int m = 0; m < 4; ++m) {
;                     const size_t ci = ub + (size_t)((ai * 2 + bj) * 4 + m) * NTHREADS;
;                     const v4u pw = pw4[m], tw = tw4[m];
;                     const float rs = rst[(row0 + ai * 128 + m * 16) & 255];
;                     float v[8];
;                     v[0] = sigmoidf_(acc[ai][bj][m][0][0] * rs + bv0[0]) * bflo(pw.x); v[1] = sigmoidf_(acc[ai][bj][m][0][1] * rs + bv0[1]) * bfhi(pw.x);
;                     v[2] = sigmoidf_(acc[ai][bj][m][0][2] * rs + bv0[2]) * bflo(pw.y); v[3] = sigmoidf_(acc[ai][bj][m][0][3] * rs + bv0[3]) * bfhi(pw.y);
;                     v[4] = sigmoidf_(acc[ai][bj][m][1][0] * rs + bv1[0]) * bflo(pw.z); v[5] = sigmoidf_(acc[ai][bj][m][1][1] * rs + bv1[1]) * bfhi(pw.z);
;                     v[6] = sigmoidf_(acc[ai][bj][m][1][2] * rs + bv1[2]) * bflo(pw.w); v[7] = sigmoidf_(acc[ai][bj][m][1][3] * rs + bv1[3]) * bfhi(pw.w);
;                     v[0] += bflo(tw.x); v[1] += bfhi(tw.x); v[2] += bflo(tw.y); v[3] += bfhi(tw.y);
;                     v[4] += bflo(tw.z); v[5] += bfhi(tw.z); v[6] += bflo(tw.w); v[7] += bfhi(tw.w);
;                     v4u w; w.x = pk2(v[0], v[1]); w.y = pk2(v[2], v[3]); w.z = pk2(v[4], v[5]); w.w = pk2(v[6], v[7]);
;                     if (!last) TMP[ci] = w;
;                     else *(v4u*)(MRG + (size_t)(row0 + ai * 128 + m * 16) * D + col0 + bj * 128) = w;
.Lgate_n_j12:
	s_waitcnt vmcnt(9)
	v_fma_f32 v50, v102, v229, v202
	v_fma_f32 v51, v103, v229, v203
	v_fma_f32 v52, v104, v229, v204
	v_fma_f32 v53, v105, v229, v205
	v_fma_f32 v54, v98, v229, v206
	v_fma_f32 v55, v99, v229, v207
	v_fma_f32 v56, v100, v229, v208
	v_fma_f32 v57, v101, v229, v209
	v_mul_f32_e32 v50, 0xbfb8aa3b, v50
	v_mul_f32_e32 v51, 0xbfb8aa3b, v51
	v_mul_f32_e32 v52, 0xbfb8aa3b, v52
	v_mul_f32_e32 v53, 0xbfb8aa3b, v53
	v_mul_f32_e32 v54, 0xbfb8aa3b, v54
	v_mul_f32_e32 v55, 0xbfb8aa3b, v55
	v_mul_f32_e32 v56, 0xbfb8aa3b, v56
	v_mul_f32_e32 v57, 0xbfb8aa3b, v57
	v_exp_f32_e32 v50, v50
	v_exp_f32_e32 v51, v51
	v_exp_f32_e32 v52, v52
	v_exp_f32_e32 v53, v53
	v_exp_f32_e32 v54, v54
	v_exp_f32_e32 v55, v55
	v_exp_f32_e32 v56, v56
	v_exp_f32_e32 v57, v57
	v_add_f32_e32 v50, 1.0, v50
	v_add_f32_e32 v51, 1.0, v51
	v_add_f32_e32 v52, 1.0, v52
	v_add_f32_e32 v53, 1.0, v53
	v_add_f32_e32 v54, 1.0, v54
	v_add_f32_e32 v55, 1.0, v55
	v_add_f32_e32 v56, 1.0, v56
	v_add_f32_e32 v57, 1.0, v57
	v_rcp_f32_e32 v50, v50
	v_rcp_f32_e32 v51, v51
	v_rcp_f32_e32 v52, v52
	v_rcp_f32_e32 v53, v53
	v_rcp_f32_e32 v54, v54
	v_rcp_f32_e32 v55, v55
	v_rcp_f32_e32 v56, v56
	v_rcp_f32_e32 v57, v57
	v_lshlrev_b32_e32 v58, 16, v10
	v_and_b32_e32 v59, 0xffff0000, v10
	v_lshlrev_b32_e32 v60, 16, v14
	v_and_b32_e32 v61, 0xffff0000, v14
	v_pk_fma_f32 v[50:51], v[50:51], v[58:59], v[60:61]
	v_lshlrev_b32_e32 v58, 16, v11
	v_and_b32_e32 v59, 0xffff0000, v11
	v_lshlrev_b32_e32 v60, 16, v15
	v_and_b32_e32 v61, 0xffff0000, v15
	v_pk_fma_f32 v[52:53], v[52:53], v[58:59], v[60:61]
	v_lshlrev_b32_e32 v58, 16, v12
	v_and_b32_e32 v59, 0xffff0000, v12
	v_lshlrev_b32_e32 v60, 16, v16
	v_and_b32_e32 v61, 0xffff0000, v16
	v_pk_fma_f32 v[54:55], v[54:55], v[58:59], v[60:61]
	v_lshlrev_b32_e32 v58, 16, v13
	v_and_b32_e32 v59, 0xffff0000, v13
	v_lshlrev_b32_e32 v60, 16, v17
	v_and_b32_e32 v61, 0xffff0000, v17
	v_pk_fma_f32 v[56:57], v[56:57], v[58:59], v[60:61]
	v_cvt_pk_bf16_f32 v10, v50, v51
	v_cvt_pk_bf16_f32 v11, v52, v53
	v_cvt_pk_bf16_f32 v12, v54, v55
	v_cvt_pk_bf16_f32 v13, v56, v57
	s_cbranch_vccz .Lgate_n_m13
	global_store_dwordx4 v225, v[10:13], s[8:9]
	s_add_u32 s8, s8, 0x2000
	s_addc_u32 s9, s9, 0
	s_branch .Lgate_n_j13

; __device__ __forceinline__ unsigned pk2(float lo, float hi) { f32x2_t v = {lo, hi}; bf16x2_t b = __builtin_convertvector(v, bf16x2_t); return __builtin_bit_cast(unsigned, b); }
; __device__ __forceinline__ float sigmoidf_(float x) { return __builtin_amdgcn_rcpf(1.0f + fexp2(-x * LOG2E)); }
;     __device__ __forceinline__ void operator()(AccRef acc, const pg8::Unit& u, int wr, int wc, int fr, int fq) const {
;     ...
;                 v4u pw4[4], tw4[4];
; #pragma unroll
;                 for (int m = 0; m < 4; ++m) {
;                     const size_t ci = ub + (size_t)((ai * 2 + bj) * 4 + m) * NTHREADS;
;                     pw4[m] = P[ci];
;                     if (!first) tw4[m] = TMP[ci]; else tw4[m] = (v4u){0u, 0u, 0u, 0u};
;                 }
; #pragma unroll
;                 for (int m = 0; m < 4; ++m) {
;                     const size_t ci = ub + (size_t)((ai * 2 + bj) * 4 + m) * NTHREADS;
;                     const v4u pw = pw4[m], tw = tw4[m];
;                     const float rs = rst[(row0 + ai * 128 + m * 16) & 255];
;                     float v[8];
;                     v[0] = sigmoidf_(acc[ai][bj][m][0][0] * rs + bv0[0]) * bflo(pw.x); v[1] = sigmoidf_(acc[ai][bj][m][0][1] * rs + bv0[1]) * bfhi(pw.x);
;                     v[2] = sigmoidf_(acc[ai][bj][m][0][2] * rs + bv0[2]) * bflo(pw.y); v[3] = sigmoidf_(acc[ai][bj][m][0][3] * rs + bv0[3]) * bfhi(pw.y);
;                     v[4] = sigmoidf_(acc[ai][bj][m][1][0] * rs + bv1[0]) * bflo(pw.z); v[5] = sigmoidf_(acc[ai][bj][m][1][1] * rs + bv1[1]) * bfhi(pw.z);
;                     v[6] = sigmoidf_(acc[ai][bj][m][1][2] * rs + bv1[2]) * bflo(pw.w); v[7] = sigmoidf_(acc[ai][bj][m][1][3] * rs + bv1[3]) * bfhi(pw.w);
;                     v[0] += bflo(tw.x); v[1] += bfhi(tw.x); v[2] += bflo(tw.y); v[3] += bfhi(tw.y);
;                     v[4] += bflo(tw.z); v[5] += bfhi(tw.z); v[6] += bflo(tw.w); v[7] += bfhi(tw.w);
;                     v4u w; w.x = pk2(v[0], v[1]); w.y = pk2(v[2], v[3]); w.z = pk2(v[4], v[5]); w.w = pk2(v[6], v[7]);
;                     if (!last) TMP[ci] = w;
;                     else *(v4u*)(MRG + (size_t)(row0 + ai * 128 + m * 16) * D + col0 + bj * 128) = w;
.Lgate_n_j13:
	s_waitcnt vmcnt(7)
	v_fma_f32 v50, v86, v230, v202
	v_fma_f32 v51, v87, v230, v203
	v_fma_f32 v52, v88, v230, v204
	v_fma_f32 v53, v89, v230, v205
	v_fma_f32 v54, v82, v230, v206
	v_fma_f32 v55, v83, v230, v207
	v_fma_f32 v56, v84, v230, v208
	v_fma_f32 v57, v85, v230, v209
	v_mul_f32_e32 v50, 0xbfb8aa3b, v50
	v_mul_f32_e32 v51, 0xbfb8aa3b, v51
	v_mul_f32_e32 v52, 0xbfb8aa3b, v52
	v_mul_f32_e32 v53, 0xbfb8aa3b, v53
	v_mul_f32_e32 v54, 0xbfb8aa3b, v54
	v_mul_f32_e32 v55, 0xbfb8aa3b, v55
	v_mul_f32_e32 v56, 0xbfb8aa3b, v56
	v_mul_f32_e32 v57, 0xbfb8aa3b, v57
	v_exp_f32_e32 v50, v50
	v_exp_f32_e32 v51, v51
	v_exp_f32_e32 v52, v52
	v_exp_f32_e32 v53, v53
	v_exp_f32_e32 v54, v54
	v_exp_f32_e32 v55, v55
	v_exp_f32_e32 v56, v56
	v_exp_f32_e32 v57, v57
	v_add_f32_e32 v50, 1.0, v50
	v_add_f32_e32 v51, 1.0, v51
	v_add_f32_e32 v52, 1.0, v52
	v_add_f32_e32 v53, 1.0, v53
	v_add_f32_e32 v54, 1.0, v54
	v_add_f32_e32 v55, 1.0, v55
	v_add_f32_e32 v56, 1.0, v56
	v_add_f32_e32 v57, 1.0, v57
	v_rcp_f32_e32 v50, v50
	v_rcp_f32_e32 v51, v51
	v_rcp_f32_e32 v52, v52
	v_rcp_f32_e32 v53, v53
	v_rcp_f32_e32 v54, v54
	v_rcp_f32_e32 v55, v55
	v_rcp_f32_e32 v56, v56
	v_rcp_f32_e32 v57, v57
	v_lshlrev_b32_e32 v58, 16, v18
	v_and_b32_e32 v59, 0xffff0000, v18
	v_lshlrev_b32_e32 v60, 16, v22
	v_and_b32_e32 v61, 0xffff0000, v22
	v_pk_fma_f32 v[50:51], v[50:51], v[58:59], v[60:61]
	v_lshlrev_b32_e32 v58, 16, v19
	v_and_b32_e32 v59, 0xffff0000, v19
	v_lshlrev_b32_e32 v60, 16, v23
	v_and_b32_e32 v61, 0xffff0000, v23
	v_pk_fma_f32 v[52:53], v[52:53], v[58:59], v[60:61]
	v_lshlrev_b32_e32 v58, 16, v20
	v_and_b32_e32 v59, 0xffff0000, v20
	v_lshlrev_b32_e32 v60, 16, v24
	v_and_b32_e32 v61, 0xffff0000, v24
	v_pk_fma_f32 v[54:55], v[54:55], v[58:59], v[60:61]
	v_lshlrev_b32_e32 v58, 16, v21
	v_and_b32_e32 v59, 0xffff0000, v21
	v_lshlrev_b32_e32 v60, 16, v25
	v_and_b32_e32 v61, 0xffff0000, v25
	v_pk_fma_f32 v[56:57], v[56:57], v[58:59], v[60:61]
	v_cvt_pk_bf16_f32 v18, v50, v51
	v_cvt_pk_bf16_f32 v19, v52, v53
	v_cvt_pk_bf16_f32 v20, v54, v55
	v_cvt_pk_bf16_f32 v21, v56, v57
	s_cbranch_vccz .Lgate_n_m14
	global_store_dwordx4 v225, v[18:21], s[8:9]
	s_add_u32 s8, s8, 0x2000
	s_addc_u32 s9, s9, 0
	s_branch .Lgate_n_j14

; __device__ __forceinline__ unsigned pk2(float lo, float hi) { f32x2_t v = {lo, hi}; bf16x2_t b = __builtin_convertvector(v, bf16x2_t); return __builtin_bit_cast(unsigned, b); }
; __device__ __forceinline__ float sigmoidf_(float x) { return __builtin_amdgcn_rcpf(1.0f + fexp2(-x * LOG2E)); }
;     __device__ __forceinline__ void operator()(AccRef acc, const pg8::Unit& u, int wr, int wc, int fr, int fq) const {
;     ...
;                 v4u pw4[4], tw4[4];
; #pragma unroll
;                 for (int m = 0; m < 4; ++m) {
;                     const size_t ci = ub + (size_t)((ai * 2 + bj) * 4 + m) * NTHREADS;
;                     pw4[m] = P[ci];
;                     if (!first) tw4[m] = TMP[ci]; else tw4[m] = (v4u){0u, 0u, 0u, 0u};
;                 }
; #pragma unroll
;                 for (int m = 0; m < 4; ++m) {
;                     const size_t ci = ub + (size_t)((ai * 2 + bj) * 4 + m) * NTHREADS;
;                     const v4u pw = pw4[m], tw = tw4[m];
;                     const float rs = rst[(row0 + ai * 128 + m * 16) & 255];
;                     float v[8];
;                     v[0] = sigmoidf_(acc[ai][bj][m][0][0] * rs + bv0[0]) * bflo(pw.x); v[1] = sigmoidf_(acc[ai][bj][m][0][1] * rs + bv0[1]) * bfhi(pw.x);
;                     v[2] = sigmoidf_(acc[ai][bj][m][0][2] * rs + bv0[2]) * bflo(pw.y); v[3] = sigmoidf_(acc[ai][bj][m][0][3] * rs + bv0[3]) * bfhi(pw.y);
;                     v[4] = sigmoidf_(acc[ai][bj][m][1][0] * rs + bv1[0]) * bflo(pw.z); v[5] = sigmoidf_(acc[ai][bj][m][1][1] * rs + bv1[1]) * bfhi(pw.z);
;                     v[6] = sigmoidf_(acc[ai][bj][m][1][2] * rs + bv1[2]) * bflo(pw.w); v[7] = sigmoidf_(acc[ai][bj][m][1][3] * rs + bv1[3]) * bfhi(pw.w);
;                     v[0] += bflo(tw.x); v[1] += bfhi(tw.x); v[2] += bflo(tw.y); v[3] += bfhi(tw.y);
;                     v[4] += bflo(tw.z); v[5] += bfhi(tw.z); v[6] += bflo(tw.w); v[7] += bfhi(tw.w);
;                     v4u w; w.x = pk2(v[0], v[1]); w.y = pk2(v[2], v[3]); w.z = pk2(v[4], v[5]); w.w = pk2(v[6], v[7]);
;                     if (!last) TMP[ci] = w;
;                     else *(v4u*)(MRG + (size_t)(row0 + ai * 128 + m * 16) * D + col0 + bj * 128) = w;
.Lgate_n_j14:
	s_waitcnt vmcnt(5)
	v_fma_f32 v50, v70, v231, v202
	v_fma_f32 v51, v71, v231, v203
	v_fma_f32 v52, v72, v231, v204
	v_fma_f32 v53, v73, v231, v205
	v_fma_f32 v54, v66, v231, v206
	v_fma_f32 v55, v67, v231, v207
	v_fma_f32 v56, v68, v231, v208
	v_fma_f32 v57, v69, v231, v209
	v_mul_f32_e32 v50, 0xbfb8aa3b, v50
	v_mul_f32_e32 v51, 0xbfb8aa3b, v51
	v_mul_f32_e32 v52, 0xbfb8aa3b, v52
	v_mul_f32_e32 v53, 0xbfb8aa3b, v53
	v_mul_f32_e32 v54, 0xbfb8aa3b, v54
	v_mul_f32_e32 v55, 0xbfb8aa3b, v55
	v_mul_f32_e32 v56, 0xbfb8aa3b, v56
	v_mul_f32_e32 v57, 0xbfb8aa3b, v57
	v_exp_f32_e32 v50, v50
	v_exp_f32_e32 v51, v51
	v_exp_f32_e32 v52, v52
	v_exp_f32_e32 v53, v53
	v_exp_f32_e32 v54, v54
	v_exp_f32_e32 v55, v55
	v_exp_f32_e32 v56, v56
	v_exp_f32_e32 v57, v57
	v_add_f32_e32 v50, 1.0, v50
	v_add_f32_e32 v51, 1.0, v51
	v_add_f32_e32 v52, 1.0, v52
	v_add_f32_e32 v53, 1.0, v53
	v_add_f32_e32 v54, 1.0, v54
	v_add_f32_e32 v55, 1.0, v55
	v_add_f32_e32 v56, 1.0, v56
	v_add_f32_e32 v57, 1.0, v57
	v_rcp_f32_e32 v50, v50
	v_rcp_f32_e32 v51, v51
	v_rcp_f32_e32 v52, v52
	v_rcp_f32_e32 v53, v53
	v_rcp_f32_e32 v54, v54
	v_rcp_f32_e32 v55, v55
	v_rcp_f32_e32 v56, v56
	v_rcp_f32_e32 v57, v57
	v_lshlrev_b32_e32 v58, 16, v26
	v_and_b32_e32 v59, 0xffff0000, v26
	v_lshlrev_b32_e32 v60, 16, v30
	v_and_b32_e32 v61, 0xffff0000, v30
	v_pk_fma_f32 v[50:51], v[50:51], v[58:59], v[60:61]
	v_lshlrev_b32_e32 v58, 16, v27
	v_and_b32_e32 v59, 0xffff0000, v27
	v_lshlrev_b32_e32 v60, 16, v31
	v_and_b32_e32 v61, 0xffff0000, v31
	v_pk_fma_f32 v[52:53], v[52:53], v[58:59], v[60:61]
	v_lshlrev_b32_e32 v58, 16, v28
	v_and_b32_e32 v59, 0xffff0000, v28
	v_lshlrev_b32_e32 v60, 16, v32
	v_and_b32_e32 v61, 0xffff0000, v32
	v_pk_fma_f32 v[54:55], v[54:55], v[58:59], v[60:61]
	v_lshlrev_b32_e32 v58, 16, v29
	v_and_b32_e32 v59, 0xffff0000, v29
	v_lshlrev_b32_e32 v60, 16, v33
	v_and_b32_e32 v61, 0xffff0000, v33
	v_pk_fma_f32 v[56:57], v[56:57], v[58:59], v[60:61]
	v_cvt_pk_bf16_f32 v26, v50, v51
	v_cvt_pk_bf16_f32 v27, v52, v53
	v_cvt_pk_bf16_f32 v28, v54, v55
	v_cvt_pk_bf16_f32 v29, v56, v57
	s_cbranch_vccz .Lgate_n_m15
	global_store_dwordx4 v225, v[26:29], s[8:9]
	s_branch .Lgate_n_j15

; template <class Epi, class Sched, bool ALIGN_EPI = false, bool SP2 = false>
; __device__ __forceinline__ void gemm_phase(PG8_LAS unsigned char* lds, const Gemm g, const Sched& S, const Epi& E) {
;     ...
;         if constexpr (!Epi::AFTER_DRAIN) { E(acc, cur, wr, wc, fr, fq); S.done(cur); }
;         if (!has_next) break;
.Lgate_n_j15:
	s_branch .LBB0_377
.LBB0_377:
	s_andn2_b64 vcc, exec, s[96:97]
	s_cbranch_vccnz .LBB0_469

; #define PG8_WAIT_V(n) asm volatile("s_waitcnt vmcnt(" #n ")" ::: "memory")
; #define PG8_BAR __builtin_amdgcn_s_barrier()
; template <class Epi, class Sched, bool ALIGN_EPI = false, bool SP2 = false>
; __device__ __forceinline__ void gemm_phase(PG8_LAS unsigned char* lds, const Gemm g, const Sched& S, const Epi& E) {
;     ...
;         cur = nxt; cA = nA; cB = nB; ++ui;
;         if constexpr (ALIGN_EPI) { if (wr == 1) PG8_BAR; }
;     }
;     PG8_WAIT_V(0);
;     if constexpr (!ALIGN_EPI) { if (wr == 0) PG8_BAR; }
;     PG8_BAR;
.LBB0_476:
	s_or_b64 exec, exec, s[6:7]
	s_and_b64 vcc, exec, s[4:5]
	s_mov_b64 s[4:5], -1
	s_cbranch_vccnz .LBB0_160
	s_branch .LBB0_470
.LBB0_492:
	s_waitcnt vmcnt(0)
	s_mov_b32 s70, 0x3fb8aa3b
	v_readlane_b32 s78, v255, 30
	v_readlane_b32 s16, v255, 39
	s_barrier
	v_readlane_b32 s64, v255, 17
	v_readlane_b32 s65, v255, 20
	v_readlane_b32 s68, v255, 21
	v_readlane_b32 s69, v255, 22
	s_mov_b32 s71, 0x3f828f5c
	s_mov_b32 s72, 0xc2ce8ed0
	s_mov_b32 s73, 0x42b17218
	v_readlane_b32 s74, v255, 25
	v_readlane_b32 s79, v255, 31
	v_readlane_b32 s17, v255, 40
